# 4-phase K-loop (32 MFMAs per barrier pair, LDS-DMA waits re-derived) for P2/P5/P10/P12/P13 GEMMs + peeled C=0 first iteration; P3 loops 8-phase with peel
# speedup vs baseline: 1.0259x; 1.0196x over previous
.LBB0_566:
	s_ashr_i32 s9, s8, 31
	v_cmp_lt_i64_e32 vcc, s[10:11], v[144:145]
	s_lshl_b64 s[10:11], s[8:9], 19
	s_add_u32 s10, s40, s10
	s_addc_u32 s11, s41, s11
	s_and_b64 s[12:13], vcc, exec
	s_cselect_b32 s9, s11, s17
	s_cselect_b32 s75, s10, s16
	s_ashr_i32 s7, s6, 31
	s_lshl_b64 s[12:13], s[6:7], 19
	s_add_u32 s12, s48, s12
	s_addc_u32 s13, s49, s13
	s_and_b64 s[18:19], vcc, exec
	s_cselect_b32 s7, s13, s35
	s_cselect_b32 s76, s12, s34
	s_add_u32 s16, s16, 0x40080
	s_addc_u32 s17, s17, 0
	s_add_u32 s77, s34, 0x100
	s_addc_u32 s78, s35, 0
	s_mov_b32 s79, -2
	ds_read_b128 v[154:157], v151
	ds_read_b128 v[158:161], v151 offset:1024
	ds_read_b128 v[162:165], v151 offset:2048
	ds_read_b128 v[166:169], v151 offset:3072
	s_add_u32 s18, s16, 0xfffc0080
	s_addc_u32 s19, s17, -1
	s_cmp_eq_u32 s79, 12
	s_cselect_b32 s19, s9, s19
	s_cselect_b32 s18, s75, s18
	s_cselect_b32 s35, s7, s78
	s_cselect_b32 s34, s76, s77
	v_lshl_add_u64 v[172:173], s[16:17], 0, v[140:141]
	s_add_i32 m0, s53, 0xc000
	ds_read_b128 v[176:179], v152
	ds_read_b128 v[180:183], v152 offset:1024
	ds_read_b128 v[184:187], v152 offset:2048
	ds_read_b128 v[188:191], v152 offset:3072
	ds_read_b128 v[192:195], v152 offset:4096
	ds_read_b128 v[196:199], v152 offset:5120
	ds_read_b128 v[200:203], v152 offset:6144
	ds_read_b128 v[204:207], v152 offset:7168
	global_load_lds_dwordx4 v[172:173], off
	v_lshl_add_u64 v[172:173], s[16:17], 0, v[142:143]
	s_add_i32 m0, s53, 0xe000
	s_nop 0
	global_load_lds_dwordx4 v[172:173], off
	ds_read_b128 v[208:211], v153
	ds_read_b128 v[212:215], v153 offset:1024
	ds_read_b128 v[216:219], v153 offset:2048
	ds_read_b128 v[220:223], v153 offset:3072
	s_waitcnt vmcnt(8)
	s_waitcnt lgkmcnt(0)
	s_setprio 1
	s_barrier
	v_mfma_f32_16x16x32_bf16 v[126:129], v[154:157], v[176:179], 0
	v_mfma_f32_16x16x32_bf16 v[122:125], v[162:165], v[176:179], 0
	v_mfma_f32_16x16x32_bf16 v[110:113], v[154:157], v[184:187], 0
	v_mfma_f32_16x16x32_bf16 v[106:109], v[162:165], v[184:187], 0
	v_mfma_f32_16x16x32_bf16 v[94:97], v[154:157], v[192:195], 0
	v_mfma_f32_16x16x32_bf16 v[90:93], v[162:165], v[192:195], 0
	v_mfma_f32_16x16x32_bf16 v[78:81], v[154:157], v[200:203], 0
	v_mfma_f32_16x16x32_bf16 v[74:77], v[162:165], v[200:203], 0
	v_mfma_f32_16x16x32_bf16 v[126:129], v[158:161], v[180:183], v[126:129]
	v_mfma_f32_16x16x32_bf16 v[122:125], v[166:169], v[180:183], v[122:125]
	v_mfma_f32_16x16x32_bf16 v[110:113], v[158:161], v[188:191], v[110:113]
	v_mfma_f32_16x16x32_bf16 v[106:109], v[166:169], v[188:191], v[106:109]
	v_mfma_f32_16x16x32_bf16 v[94:97], v[158:161], v[196:199], v[94:97]
	v_mfma_f32_16x16x32_bf16 v[90:93], v[166:169], v[196:199], v[90:93]
	v_mfma_f32_16x16x32_bf16 v[78:81], v[158:161], v[204:207], v[78:81]
	v_mfma_f32_16x16x32_bf16 v[74:77], v[166:169], v[204:207], v[74:77]
	v_mfma_f32_16x16x32_bf16 v[118:121], v[208:211], v[176:179], 0
	v_mfma_f32_16x16x32_bf16 v[114:117], v[216:219], v[176:179], 0
	v_mfma_f32_16x16x32_bf16 v[102:105], v[208:211], v[184:187], 0
	v_mfma_f32_16x16x32_bf16 v[98:101], v[216:219], v[184:187], 0
	v_mfma_f32_16x16x32_bf16 v[86:89], v[208:211], v[192:195], 0
	v_mfma_f32_16x16x32_bf16 v[82:85], v[216:219], v[192:195], 0
	v_mfma_f32_16x16x32_bf16 v[70:73], v[208:211], v[200:203], 0
	v_mfma_f32_16x16x32_bf16 v[66:69], v[216:219], v[200:203], 0
	v_mfma_f32_16x16x32_bf16 v[118:121], v[212:215], v[180:183], v[118:121]
	v_mfma_f32_16x16x32_bf16 v[114:117], v[220:223], v[180:183], v[114:117]
	v_mfma_f32_16x16x32_bf16 v[102:105], v[212:215], v[188:191], v[102:105]
	v_mfma_f32_16x16x32_bf16 v[98:101], v[220:223], v[188:191], v[98:101]
	v_mfma_f32_16x16x32_bf16 v[86:89], v[212:215], v[196:199], v[86:89]
	v_mfma_f32_16x16x32_bf16 v[82:85], v[220:223], v[196:199], v[82:85]
	v_mfma_f32_16x16x32_bf16 v[70:73], v[212:215], v[204:207], v[70:73]
	v_mfma_f32_16x16x32_bf16 v[66:69], v[220:223], v[204:207], v[66:69]
	s_barrier
	s_setprio 0
	s_add_i32 s20, s72, s52
	v_lshl_add_u64 v[172:173], s[34:35], 0, v[134:135]
	s_mov_b32 m0, s20
	s_nop 0
	global_load_lds_dwordx4 v[172:173], off
	v_lshl_add_u64 v[224:225], s[34:35], 0, v[130:131]
	s_add_i32 m0, s20, 0x2000
	s_nop 0
	global_load_lds_dwordx4 v[224:225], off
	s_mov_b32 m0, s53
	v_lshl_add_u64 v[226:227], s[18:19], 0, v[136:137]
	ds_read_b128 v[176:179], v152 offset:16384
	ds_read_b128 v[180:183], v152 offset:17408
	ds_read_b128 v[184:187], v152 offset:18432
	ds_read_b128 v[188:191], v152 offset:19456
	ds_read_b128 v[192:195], v152 offset:20480
	ds_read_b128 v[196:199], v152 offset:21504
	ds_read_b128 v[200:203], v152 offset:22528
	ds_read_b128 v[204:207], v152 offset:23552
	global_load_lds_dwordx4 v[226:227], off
	v_lshl_add_u64 v[228:229], s[18:19], 0, v[132:133]
	s_mov_b32 m0, s54
	s_nop 0
	global_load_lds_dwordx4 v[228:229], off
	s_add_u32 s20, s34, 0x40000
	s_addc_u32 s21, s35, 0
	s_add_i32 s60, s73, s52
	v_lshl_add_u64 v[246:247], s[20:21], 0, v[134:135]
	s_mov_b32 m0, s60
	s_nop 0
	global_load_lds_dwordx4 v[246:247], off
	v_lshl_add_u64 v[246:247], s[20:21], 0, v[130:131]
	s_add_i32 m0, s60, 0x2000
	s_nop 0
	global_load_lds_dwordx4 v[246:247], off
	s_waitcnt vmcnt(8)
	s_waitcnt lgkmcnt(0)
	s_setprio 1
	s_barrier
	v_mfma_f32_16x16x32_bf16 v[62:65], v[154:157], v[176:179], 0
	v_mfma_f32_16x16x32_bf16 v[58:61], v[162:165], v[176:179], 0
	v_mfma_f32_16x16x32_bf16 v[46:49], v[154:157], v[184:187], 0
	v_mfma_f32_16x16x32_bf16 v[42:45], v[162:165], v[184:187], 0
	v_mfma_f32_16x16x32_bf16 v[30:33], v[154:157], v[192:195], 0
	v_mfma_f32_16x16x32_bf16 v[26:29], v[162:165], v[192:195], 0
	v_mfma_f32_16x16x32_bf16 v[14:17], v[154:157], v[200:203], 0
	v_mfma_f32_16x16x32_bf16 v[10:13], v[162:165], v[200:203], 0
	v_mfma_f32_16x16x32_bf16 v[62:65], v[158:161], v[180:183], v[62:65]
	v_mfma_f32_16x16x32_bf16 v[58:61], v[166:169], v[180:183], v[58:61]
	v_mfma_f32_16x16x32_bf16 v[46:49], v[158:161], v[188:191], v[46:49]
	v_mfma_f32_16x16x32_bf16 v[42:45], v[166:169], v[188:191], v[42:45]
	v_mfma_f32_16x16x32_bf16 v[30:33], v[158:161], v[196:199], v[30:33]
	v_mfma_f32_16x16x32_bf16 v[26:29], v[166:169], v[196:199], v[26:29]
	v_mfma_f32_16x16x32_bf16 v[14:17], v[158:161], v[204:207], v[14:17]
	v_mfma_f32_16x16x32_bf16 v[10:13], v[166:169], v[204:207], v[10:13]
	v_mfma_f32_16x16x32_bf16 v[54:57], v[208:211], v[176:179], 0
	v_mfma_f32_16x16x32_bf16 v[50:53], v[216:219], v[176:179], 0
	v_mfma_f32_16x16x32_bf16 v[38:41], v[208:211], v[184:187], 0
	v_mfma_f32_16x16x32_bf16 v[34:37], v[216:219], v[184:187], 0
	v_mfma_f32_16x16x32_bf16 v[22:25], v[208:211], v[192:195], 0
	v_mfma_f32_16x16x32_bf16 v[18:21], v[216:219], v[192:195], 0
	v_mfma_f32_16x16x32_bf16 v[6:9], v[208:211], v[200:203], 0
	v_mfma_f32_16x16x32_bf16 v[2:5], v[216:219], v[200:203], 0
	v_mfma_f32_16x16x32_bf16 v[54:57], v[212:215], v[180:183], v[54:57]
	v_mfma_f32_16x16x32_bf16 v[50:53], v[220:223], v[180:183], v[50:53]
	v_mfma_f32_16x16x32_bf16 v[38:41], v[212:215], v[188:191], v[38:41]
	v_mfma_f32_16x16x32_bf16 v[34:37], v[220:223], v[188:191], v[34:37]
	v_mfma_f32_16x16x32_bf16 v[22:25], v[212:215], v[196:199], v[22:25]
	v_mfma_f32_16x16x32_bf16 v[18:21], v[220:223], v[196:199], v[18:21]
	v_mfma_f32_16x16x32_bf16 v[6:9], v[212:215], v[204:207], v[6:9]
	v_mfma_f32_16x16x32_bf16 v[2:5], v[220:223], v[204:207], v[2:5]
	s_barrier
	s_setprio 0
	s_add_i32 s20, 0, 0x18000
	v_add_u32_e32 v166, s20, v150
	ds_read_b128 v[154:157], v166
	ds_read_b128 v[158:161], v166 offset:1024
	ds_read_b128 v[162:165], v166 offset:2048
	ds_read_b128 v[166:169], v166 offset:3072
	s_add_u32 s18, s18, 0x40000
	s_addc_u32 s19, s19, 0
	s_mov_b32 m0, s55
	v_lshl_add_u64 v[208:209], s[18:19], 0, v[136:137]
	ds_read_b128 v[176:179], v152 offset:32768
	ds_read_b128 v[180:183], v152 offset:33792
	ds_read_b128 v[184:187], v152 offset:34816
	ds_read_b128 v[188:191], v152 offset:35840
	ds_read_b128 v[192:195], v152 offset:36864
	ds_read_b128 v[196:199], v152 offset:37888
	ds_read_b128 v[200:203], v152 offset:38912
	ds_read_b128 v[204:207], v152 offset:39936
	global_load_lds_dwordx4 v[208:209], off
	v_lshl_add_u64 v[208:209], s[18:19], 0, v[132:133]
	s_mov_b32 m0, s56
	s_nop 0
	global_load_lds_dwordx4 v[208:209], off
	s_add_i32 s21, 0, 0x1c000
	v_add_u32_e32 v171, s21, v150
	ds_read_b128 v[208:211], v171
	ds_read_b128 v[212:215], v171 offset:1024
	ds_read_b128 v[216:219], v171 offset:2048
	ds_read_b128 v[220:223], v171 offset:3072
	s_waitcnt vmcnt(8)
	s_waitcnt lgkmcnt(0)
	s_setprio 1
	s_barrier
	v_mfma_f32_16x16x32_bf16 v[126:129], v[154:157], v[176:179], v[126:129]
	v_mfma_f32_16x16x32_bf16 v[122:125], v[162:165], v[176:179], v[122:125]
	v_mfma_f32_16x16x32_bf16 v[110:113], v[154:157], v[184:187], v[110:113]
	v_mfma_f32_16x16x32_bf16 v[106:109], v[162:165], v[184:187], v[106:109]
	v_mfma_f32_16x16x32_bf16 v[94:97], v[154:157], v[192:195], v[94:97]
	v_mfma_f32_16x16x32_bf16 v[90:93], v[162:165], v[192:195], v[90:93]
	v_mfma_f32_16x16x32_bf16 v[78:81], v[154:157], v[200:203], v[78:81]
	v_mfma_f32_16x16x32_bf16 v[74:77], v[162:165], v[200:203], v[74:77]
	v_mfma_f32_16x16x32_bf16 v[126:129], v[158:161], v[180:183], v[126:129]
	v_mfma_f32_16x16x32_bf16 v[122:125], v[166:169], v[180:183], v[122:125]
	v_mfma_f32_16x16x32_bf16 v[110:113], v[158:161], v[188:191], v[110:113]
	v_mfma_f32_16x16x32_bf16 v[106:109], v[166:169], v[188:191], v[106:109]
	v_mfma_f32_16x16x32_bf16 v[94:97], v[158:161], v[196:199], v[94:97]
	v_mfma_f32_16x16x32_bf16 v[90:93], v[166:169], v[196:199], v[90:93]
	v_mfma_f32_16x16x32_bf16 v[78:81], v[158:161], v[204:207], v[78:81]
	v_mfma_f32_16x16x32_bf16 v[74:77], v[166:169], v[204:207], v[74:77]
	v_mfma_f32_16x16x32_bf16 v[118:121], v[208:211], v[176:179], v[118:121]
	v_mfma_f32_16x16x32_bf16 v[114:117], v[216:219], v[176:179], v[114:117]
	v_mfma_f32_16x16x32_bf16 v[102:105], v[208:211], v[184:187], v[102:105]
	v_mfma_f32_16x16x32_bf16 v[98:101], v[216:219], v[184:187], v[98:101]
	v_mfma_f32_16x16x32_bf16 v[86:89], v[208:211], v[192:195], v[86:89]
	v_mfma_f32_16x16x32_bf16 v[82:85], v[216:219], v[192:195], v[82:85]
	v_mfma_f32_16x16x32_bf16 v[70:73], v[208:211], v[200:203], v[70:73]
	v_mfma_f32_16x16x32_bf16 v[66:69], v[216:219], v[200:203], v[66:69]
	v_mfma_f32_16x16x32_bf16 v[118:121], v[212:215], v[180:183], v[118:121]
	v_mfma_f32_16x16x32_bf16 v[114:117], v[220:223], v[180:183], v[114:117]
	v_mfma_f32_16x16x32_bf16 v[102:105], v[212:215], v[188:191], v[102:105]
	v_mfma_f32_16x16x32_bf16 v[98:101], v[220:223], v[188:191], v[98:101]
	v_mfma_f32_16x16x32_bf16 v[86:89], v[212:215], v[196:199], v[86:89]
	v_mfma_f32_16x16x32_bf16 v[82:85], v[220:223], v[196:199], v[82:85]
	v_mfma_f32_16x16x32_bf16 v[70:73], v[212:215], v[204:207], v[70:73]
	v_mfma_f32_16x16x32_bf16 v[66:69], v[220:223], v[204:207], v[66:69]
	s_barrier
	s_setprio 0
	s_add_i32 s18, s20, s52
	v_lshl_add_u64 v[172:173], v[172:173], 0, s[4:5]
	s_mov_b32 m0, s18
	s_nop 0
	global_load_lds_dwordx4 v[172:173], off
	v_lshl_add_u64 v[172:173], v[224:225], 0, s[4:5]
	s_add_i32 m0, s18, 0x2000
	s_nop 0
	global_load_lds_dwordx4 v[172:173], off
	s_mov_b32 m0, s68
	v_lshl_add_u64 v[172:173], v[226:227], 0, s[4:5]
	ds_read_b128 v[176:179], v152 offset:49152
	ds_read_b128 v[180:183], v152 offset:50176
	ds_read_b128 v[184:187], v152 offset:51200
	ds_read_b128 v[188:191], v152 offset:52224
	ds_read_b128 v[192:195], v152 offset:53248
	ds_read_b128 v[196:199], v152 offset:54272
	ds_read_b128 v[200:203], v152 offset:55296
	ds_read_b128 v[204:207], v152 offset:56320
	global_load_lds_dwordx4 v[172:173], off
	v_lshl_add_u64 v[172:173], v[228:229], 0, s[4:5]
	s_mov_b32 m0, s69
	s_nop 0
	global_load_lds_dwordx4 v[172:173], off
	s_add_u32 s18, s34, 0x40080
	s_addc_u32 s19, s35, 0
	s_add_i32 s20, s21, s52
	v_lshl_add_u64 v[248:249], s[18:19], 0, v[134:135]
	s_mov_b32 m0, s20
	s_nop 0
	global_load_lds_dwordx4 v[248:249], off
	v_lshl_add_u64 v[248:249], s[18:19], 0, v[130:131]
	s_add_i32 m0, s20, 0x2000
	s_nop 0
	global_load_lds_dwordx4 v[248:249], off
	s_waitcnt vmcnt(8)
	s_waitcnt lgkmcnt(0)
	s_setprio 1
	s_barrier
	v_mfma_f32_16x16x32_bf16 v[62:65], v[154:157], v[176:179], v[62:65]
	v_mfma_f32_16x16x32_bf16 v[58:61], v[162:165], v[176:179], v[58:61]
	v_mfma_f32_16x16x32_bf16 v[46:49], v[154:157], v[184:187], v[46:49]
	v_mfma_f32_16x16x32_bf16 v[42:45], v[162:165], v[184:187], v[42:45]
	v_mfma_f32_16x16x32_bf16 v[30:33], v[154:157], v[192:195], v[30:33]
	v_mfma_f32_16x16x32_bf16 v[26:29], v[162:165], v[192:195], v[26:29]
	v_mfma_f32_16x16x32_bf16 v[14:17], v[154:157], v[200:203], v[14:17]
	v_mfma_f32_16x16x32_bf16 v[10:13], v[162:165], v[200:203], v[10:13]
	v_mfma_f32_16x16x32_bf16 v[62:65], v[158:161], v[180:183], v[62:65]
	v_mfma_f32_16x16x32_bf16 v[58:61], v[166:169], v[180:183], v[58:61]
	v_mfma_f32_16x16x32_bf16 v[46:49], v[158:161], v[188:191], v[46:49]
	v_mfma_f32_16x16x32_bf16 v[42:45], v[166:169], v[188:191], v[42:45]
	v_mfma_f32_16x16x32_bf16 v[30:33], v[158:161], v[196:199], v[30:33]
	v_mfma_f32_16x16x32_bf16 v[26:29], v[166:169], v[196:199], v[26:29]
	v_mfma_f32_16x16x32_bf16 v[14:17], v[158:161], v[204:207], v[14:17]
	v_mfma_f32_16x16x32_bf16 v[10:13], v[166:169], v[204:207], v[10:13]
	v_mfma_f32_16x16x32_bf16 v[54:57], v[208:211], v[176:179], v[54:57]
	v_mfma_f32_16x16x32_bf16 v[50:53], v[216:219], v[176:179], v[50:53]
	v_mfma_f32_16x16x32_bf16 v[38:41], v[208:211], v[184:187], v[38:41]
	v_mfma_f32_16x16x32_bf16 v[34:37], v[216:219], v[184:187], v[34:37]
	v_mfma_f32_16x16x32_bf16 v[22:25], v[208:211], v[192:195], v[22:25]
	v_mfma_f32_16x16x32_bf16 v[18:21], v[216:219], v[192:195], v[18:21]
	v_mfma_f32_16x16x32_bf16 v[6:9], v[208:211], v[200:203], v[6:9]
	v_mfma_f32_16x16x32_bf16 v[2:5], v[216:219], v[200:203], v[2:5]
	v_mfma_f32_16x16x32_bf16 v[54:57], v[212:215], v[180:183], v[54:57]
	v_mfma_f32_16x16x32_bf16 v[50:53], v[220:223], v[180:183], v[50:53]
	v_mfma_f32_16x16x32_bf16 v[38:41], v[212:215], v[188:191], v[38:41]
	v_mfma_f32_16x16x32_bf16 v[34:37], v[220:223], v[188:191], v[34:37]
	v_mfma_f32_16x16x32_bf16 v[22:25], v[212:215], v[196:199], v[22:25]
	v_mfma_f32_16x16x32_bf16 v[18:21], v[220:223], v[196:199], v[18:21]
	v_mfma_f32_16x16x32_bf16 v[6:9], v[212:215], v[204:207], v[6:9]
	v_mfma_f32_16x16x32_bf16 v[2:5], v[220:223], v[204:207], v[2:5]
	s_barrier
	s_setprio 0
	s_add_i32 s79, s79, 2
	s_add_u32 s16, s16, 0x100
	s_addc_u32 s17, s17, 0
	s_add_u32 s77, s77, 0x100
	s_addc_u32 s78, s78, 0
	s_cmp_gt_u32 s79, 13
.LBB0_567:
	ds_read_b128 v[154:157], v151
	ds_read_b128 v[158:161], v151 offset:1024
	ds_read_b128 v[162:165], v151 offset:2048
	ds_read_b128 v[166:169], v151 offset:3072
	s_add_u32 s18, s16, 0xfffc0080
	s_addc_u32 s19, s17, -1
	s_cmp_eq_u32 s79, 12
	s_cselect_b32 s19, s9, s19
	s_cselect_b32 s18, s75, s18
	s_cselect_b32 s35, s7, s78
	s_cselect_b32 s34, s76, s77
	v_lshl_add_u64 v[172:173], s[16:17], 0, v[140:141]
	s_add_i32 m0, s53, 0xc000
	ds_read_b128 v[176:179], v152
	ds_read_b128 v[180:183], v152 offset:1024
	ds_read_b128 v[184:187], v152 offset:2048
	ds_read_b128 v[188:191], v152 offset:3072
	ds_read_b128 v[192:195], v152 offset:4096
	ds_read_b128 v[196:199], v152 offset:5120
	ds_read_b128 v[200:203], v152 offset:6144
	ds_read_b128 v[204:207], v152 offset:7168
	global_load_lds_dwordx4 v[172:173], off
	v_lshl_add_u64 v[172:173], s[16:17], 0, v[142:143]
	s_add_i32 m0, s53, 0xe000
	s_nop 0
	global_load_lds_dwordx4 v[172:173], off
	ds_read_b128 v[208:211], v153
	ds_read_b128 v[212:215], v153 offset:1024
	ds_read_b128 v[216:219], v153 offset:2048
	ds_read_b128 v[220:223], v153 offset:3072
	s_waitcnt vmcnt(8)
	s_waitcnt lgkmcnt(0)
	s_setprio 1
	s_barrier
	v_mfma_f32_16x16x32_bf16 v[126:129], v[154:157], v[176:179], v[126:129]
	v_mfma_f32_16x16x32_bf16 v[122:125], v[162:165], v[176:179], v[122:125]
	v_mfma_f32_16x16x32_bf16 v[110:113], v[154:157], v[184:187], v[110:113]
	v_mfma_f32_16x16x32_bf16 v[106:109], v[162:165], v[184:187], v[106:109]
	v_mfma_f32_16x16x32_bf16 v[94:97], v[154:157], v[192:195], v[94:97]
	v_mfma_f32_16x16x32_bf16 v[90:93], v[162:165], v[192:195], v[90:93]
	v_mfma_f32_16x16x32_bf16 v[78:81], v[154:157], v[200:203], v[78:81]
	v_mfma_f32_16x16x32_bf16 v[74:77], v[162:165], v[200:203], v[74:77]
	v_mfma_f32_16x16x32_bf16 v[126:129], v[158:161], v[180:183], v[126:129]
	v_mfma_f32_16x16x32_bf16 v[122:125], v[166:169], v[180:183], v[122:125]
	v_mfma_f32_16x16x32_bf16 v[110:113], v[158:161], v[188:191], v[110:113]
	v_mfma_f32_16x16x32_bf16 v[106:109], v[166:169], v[188:191], v[106:109]
	v_mfma_f32_16x16x32_bf16 v[94:97], v[158:161], v[196:199], v[94:97]
	v_mfma_f32_16x16x32_bf16 v[90:93], v[166:169], v[196:199], v[90:93]
	v_mfma_f32_16x16x32_bf16 v[78:81], v[158:161], v[204:207], v[78:81]
	v_mfma_f32_16x16x32_bf16 v[74:77], v[166:169], v[204:207], v[74:77]
	v_mfma_f32_16x16x32_bf16 v[118:121], v[208:211], v[176:179], v[118:121]
	v_mfma_f32_16x16x32_bf16 v[114:117], v[216:219], v[176:179], v[114:117]
	v_mfma_f32_16x16x32_bf16 v[102:105], v[208:211], v[184:187], v[102:105]
	v_mfma_f32_16x16x32_bf16 v[98:101], v[216:219], v[184:187], v[98:101]
	v_mfma_f32_16x16x32_bf16 v[86:89], v[208:211], v[192:195], v[86:89]
	v_mfma_f32_16x16x32_bf16 v[82:85], v[216:219], v[192:195], v[82:85]
	v_mfma_f32_16x16x32_bf16 v[70:73], v[208:211], v[200:203], v[70:73]
	v_mfma_f32_16x16x32_bf16 v[66:69], v[216:219], v[200:203], v[66:69]
	v_mfma_f32_16x16x32_bf16 v[118:121], v[212:215], v[180:183], v[118:121]
	v_mfma_f32_16x16x32_bf16 v[114:117], v[220:223], v[180:183], v[114:117]
	v_mfma_f32_16x16x32_bf16 v[102:105], v[212:215], v[188:191], v[102:105]
	v_mfma_f32_16x16x32_bf16 v[98:101], v[220:223], v[188:191], v[98:101]
	v_mfma_f32_16x16x32_bf16 v[86:89], v[212:215], v[196:199], v[86:89]
	v_mfma_f32_16x16x32_bf16 v[82:85], v[220:223], v[196:199], v[82:85]
	v_mfma_f32_16x16x32_bf16 v[70:73], v[212:215], v[204:207], v[70:73]
	v_mfma_f32_16x16x32_bf16 v[66:69], v[220:223], v[204:207], v[66:69]
	s_barrier
	s_setprio 0
	s_add_i32 s20, s72, s52
	v_lshl_add_u64 v[172:173], s[34:35], 0, v[134:135]
	s_mov_b32 m0, s20
	s_nop 0
	global_load_lds_dwordx4 v[172:173], off
	v_lshl_add_u64 v[224:225], s[34:35], 0, v[130:131]
	s_add_i32 m0, s20, 0x2000
	s_nop 0
	global_load_lds_dwordx4 v[224:225], off
	s_mov_b32 m0, s53
	v_lshl_add_u64 v[226:227], s[18:19], 0, v[136:137]
	ds_read_b128 v[176:179], v152 offset:16384
	ds_read_b128 v[180:183], v152 offset:17408
	ds_read_b128 v[184:187], v152 offset:18432
	ds_read_b128 v[188:191], v152 offset:19456
	ds_read_b128 v[192:195], v152 offset:20480
	ds_read_b128 v[196:199], v152 offset:21504
	ds_read_b128 v[200:203], v152 offset:22528
	ds_read_b128 v[204:207], v152 offset:23552
	global_load_lds_dwordx4 v[226:227], off
	v_lshl_add_u64 v[228:229], s[18:19], 0, v[132:133]
	s_mov_b32 m0, s54
	s_nop 0
	global_load_lds_dwordx4 v[228:229], off
	s_add_u32 s20, s34, 0x40000
	s_addc_u32 s21, s35, 0
	s_add_i32 s60, s73, s52
	v_lshl_add_u64 v[246:247], s[20:21], 0, v[134:135]
	s_mov_b32 m0, s60
	s_nop 0
	global_load_lds_dwordx4 v[246:247], off
	v_lshl_add_u64 v[246:247], s[20:21], 0, v[130:131]
	s_add_i32 m0, s60, 0x2000
	s_nop 0
	global_load_lds_dwordx4 v[246:247], off
	s_waitcnt vmcnt(8)
	s_waitcnt lgkmcnt(0)
	s_setprio 1
	s_barrier
	v_mfma_f32_16x16x32_bf16 v[62:65], v[154:157], v[176:179], v[62:65]
	v_mfma_f32_16x16x32_bf16 v[58:61], v[162:165], v[176:179], v[58:61]
	v_mfma_f32_16x16x32_bf16 v[46:49], v[154:157], v[184:187], v[46:49]
	v_mfma_f32_16x16x32_bf16 v[42:45], v[162:165], v[184:187], v[42:45]
	v_mfma_f32_16x16x32_bf16 v[30:33], v[154:157], v[192:195], v[30:33]
	v_mfma_f32_16x16x32_bf16 v[26:29], v[162:165], v[192:195], v[26:29]
	v_mfma_f32_16x16x32_bf16 v[14:17], v[154:157], v[200:203], v[14:17]
	v_mfma_f32_16x16x32_bf16 v[10:13], v[162:165], v[200:203], v[10:13]
	v_mfma_f32_16x16x32_bf16 v[62:65], v[158:161], v[180:183], v[62:65]
	v_mfma_f32_16x16x32_bf16 v[58:61], v[166:169], v[180:183], v[58:61]
	v_mfma_f32_16x16x32_bf16 v[46:49], v[158:161], v[188:191], v[46:49]
	v_mfma_f32_16x16x32_bf16 v[42:45], v[166:169], v[188:191], v[42:45]
	v_mfma_f32_16x16x32_bf16 v[30:33], v[158:161], v[196:199], v[30:33]
	v_mfma_f32_16x16x32_bf16 v[26:29], v[166:169], v[196:199], v[26:29]
	v_mfma_f32_16x16x32_bf16 v[14:17], v[158:161], v[204:207], v[14:17]
	v_mfma_f32_16x16x32_bf16 v[10:13], v[166:169], v[204:207], v[10:13]
	v_mfma_f32_16x16x32_bf16 v[54:57], v[208:211], v[176:179], v[54:57]
	v_mfma_f32_16x16x32_bf16 v[50:53], v[216:219], v[176:179], v[50:53]
	v_mfma_f32_16x16x32_bf16 v[38:41], v[208:211], v[184:187], v[38:41]
	v_mfma_f32_16x16x32_bf16 v[34:37], v[216:219], v[184:187], v[34:37]
	v_mfma_f32_16x16x32_bf16 v[22:25], v[208:211], v[192:195], v[22:25]
	v_mfma_f32_16x16x32_bf16 v[18:21], v[216:219], v[192:195], v[18:21]
	v_mfma_f32_16x16x32_bf16 v[6:9], v[208:211], v[200:203], v[6:9]
	v_mfma_f32_16x16x32_bf16 v[2:5], v[216:219], v[200:203], v[2:5]
	v_mfma_f32_16x16x32_bf16 v[54:57], v[212:215], v[180:183], v[54:57]
	v_mfma_f32_16x16x32_bf16 v[50:53], v[220:223], v[180:183], v[50:53]
	v_mfma_f32_16x16x32_bf16 v[38:41], v[212:215], v[188:191], v[38:41]
	v_mfma_f32_16x16x32_bf16 v[34:37], v[220:223], v[188:191], v[34:37]
	v_mfma_f32_16x16x32_bf16 v[22:25], v[212:215], v[196:199], v[22:25]
	v_mfma_f32_16x16x32_bf16 v[18:21], v[220:223], v[196:199], v[18:21]
	v_mfma_f32_16x16x32_bf16 v[6:9], v[212:215], v[204:207], v[6:9]
	v_mfma_f32_16x16x32_bf16 v[2:5], v[220:223], v[204:207], v[2:5]
	s_barrier
	s_setprio 0
	s_add_i32 s20, 0, 0x18000
	v_add_u32_e32 v166, s20, v150
	ds_read_b128 v[154:157], v166
	ds_read_b128 v[158:161], v166 offset:1024
	ds_read_b128 v[162:165], v166 offset:2048
	ds_read_b128 v[166:169], v166 offset:3072
	s_add_u32 s18, s18, 0x40000
	s_addc_u32 s19, s19, 0
	s_mov_b32 m0, s55
	v_lshl_add_u64 v[208:209], s[18:19], 0, v[136:137]
	ds_read_b128 v[176:179], v152 offset:32768
	ds_read_b128 v[180:183], v152 offset:33792
	ds_read_b128 v[184:187], v152 offset:34816
	ds_read_b128 v[188:191], v152 offset:35840
	ds_read_b128 v[192:195], v152 offset:36864
	ds_read_b128 v[196:199], v152 offset:37888
	ds_read_b128 v[200:203], v152 offset:38912
	ds_read_b128 v[204:207], v152 offset:39936
	global_load_lds_dwordx4 v[208:209], off
	v_lshl_add_u64 v[208:209], s[18:19], 0, v[132:133]
	s_mov_b32 m0, s56
	s_nop 0
	global_load_lds_dwordx4 v[208:209], off
	s_add_i32 s21, 0, 0x1c000
	v_add_u32_e32 v171, s21, v150
	ds_read_b128 v[208:211], v171
	ds_read_b128 v[212:215], v171 offset:1024
	ds_read_b128 v[216:219], v171 offset:2048
	ds_read_b128 v[220:223], v171 offset:3072
	s_waitcnt vmcnt(8)
	s_waitcnt lgkmcnt(0)
	s_setprio 1
	s_barrier
	v_mfma_f32_16x16x32_bf16 v[126:129], v[154:157], v[176:179], v[126:129]
	v_mfma_f32_16x16x32_bf16 v[122:125], v[162:165], v[176:179], v[122:125]
	v_mfma_f32_16x16x32_bf16 v[110:113], v[154:157], v[184:187], v[110:113]
	v_mfma_f32_16x16x32_bf16 v[106:109], v[162:165], v[184:187], v[106:109]
	v_mfma_f32_16x16x32_bf16 v[94:97], v[154:157], v[192:195], v[94:97]
	v_mfma_f32_16x16x32_bf16 v[90:93], v[162:165], v[192:195], v[90:93]
	v_mfma_f32_16x16x32_bf16 v[78:81], v[154:157], v[200:203], v[78:81]
	v_mfma_f32_16x16x32_bf16 v[74:77], v[162:165], v[200:203], v[74:77]
	v_mfma_f32_16x16x32_bf16 v[126:129], v[158:161], v[180:183], v[126:129]
	v_mfma_f32_16x16x32_bf16 v[122:125], v[166:169], v[180:183], v[122:125]
	v_mfma_f32_16x16x32_bf16 v[110:113], v[158:161], v[188:191], v[110:113]
	v_mfma_f32_16x16x32_bf16 v[106:109], v[166:169], v[188:191], v[106:109]
	v_mfma_f32_16x16x32_bf16 v[94:97], v[158:161], v[196:199], v[94:97]
	v_mfma_f32_16x16x32_bf16 v[90:93], v[166:169], v[196:199], v[90:93]
	v_mfma_f32_16x16x32_bf16 v[78:81], v[158:161], v[204:207], v[78:81]
	v_mfma_f32_16x16x32_bf16 v[74:77], v[166:169], v[204:207], v[74:77]
	v_mfma_f32_16x16x32_bf16 v[118:121], v[208:211], v[176:179], v[118:121]
	v_mfma_f32_16x16x32_bf16 v[114:117], v[216:219], v[176:179], v[114:117]
	v_mfma_f32_16x16x32_bf16 v[102:105], v[208:211], v[184:187], v[102:105]
	v_mfma_f32_16x16x32_bf16 v[98:101], v[216:219], v[184:187], v[98:101]
	v_mfma_f32_16x16x32_bf16 v[86:89], v[208:211], v[192:195], v[86:89]
	v_mfma_f32_16x16x32_bf16 v[82:85], v[216:219], v[192:195], v[82:85]
	v_mfma_f32_16x16x32_bf16 v[70:73], v[208:211], v[200:203], v[70:73]
	v_mfma_f32_16x16x32_bf16 v[66:69], v[216:219], v[200:203], v[66:69]
	v_mfma_f32_16x16x32_bf16 v[118:121], v[212:215], v[180:183], v[118:121]
	v_mfma_f32_16x16x32_bf16 v[114:117], v[220:223], v[180:183], v[114:117]
	v_mfma_f32_16x16x32_bf16 v[102:105], v[212:215], v[188:191], v[102:105]
	v_mfma_f32_16x16x32_bf16 v[98:101], v[220:223], v[188:191], v[98:101]
	v_mfma_f32_16x16x32_bf16 v[86:89], v[212:215], v[196:199], v[86:89]
	v_mfma_f32_16x16x32_bf16 v[82:85], v[220:223], v[196:199], v[82:85]
	v_mfma_f32_16x16x32_bf16 v[70:73], v[212:215], v[204:207], v[70:73]
	v_mfma_f32_16x16x32_bf16 v[66:69], v[220:223], v[204:207], v[66:69]
	s_barrier
	s_setprio 0
	s_add_i32 s18, s20, s52
	v_lshl_add_u64 v[172:173], v[172:173], 0, s[4:5]
	s_mov_b32 m0, s18
	s_nop 0
	global_load_lds_dwordx4 v[172:173], off
	v_lshl_add_u64 v[172:173], v[224:225], 0, s[4:5]
	s_add_i32 m0, s18, 0x2000
	s_nop 0
	global_load_lds_dwordx4 v[172:173], off
	s_mov_b32 m0, s68
	v_lshl_add_u64 v[172:173], v[226:227], 0, s[4:5]
	ds_read_b128 v[176:179], v152 offset:49152
	ds_read_b128 v[180:183], v152 offset:50176
	ds_read_b128 v[184:187], v152 offset:51200
	ds_read_b128 v[188:191], v152 offset:52224
	ds_read_b128 v[192:195], v152 offset:53248
	ds_read_b128 v[196:199], v152 offset:54272
	ds_read_b128 v[200:203], v152 offset:55296
	ds_read_b128 v[204:207], v152 offset:56320
	global_load_lds_dwordx4 v[172:173], off
	v_lshl_add_u64 v[172:173], v[228:229], 0, s[4:5]
	s_mov_b32 m0, s69
	s_nop 0
	global_load_lds_dwordx4 v[172:173], off
	s_add_u32 s18, s34, 0x40080
	s_addc_u32 s19, s35, 0
	s_add_i32 s20, s21, s52
	v_lshl_add_u64 v[248:249], s[18:19], 0, v[134:135]
	s_mov_b32 m0, s20
	s_nop 0
	global_load_lds_dwordx4 v[248:249], off
	v_lshl_add_u64 v[248:249], s[18:19], 0, v[130:131]
	s_add_i32 m0, s20, 0x2000
	s_nop 0
	global_load_lds_dwordx4 v[248:249], off
	s_waitcnt vmcnt(8)
	s_waitcnt lgkmcnt(0)
	s_setprio 1
	s_barrier
	v_mfma_f32_16x16x32_bf16 v[62:65], v[154:157], v[176:179], v[62:65]
	v_mfma_f32_16x16x32_bf16 v[58:61], v[162:165], v[176:179], v[58:61]
	v_mfma_f32_16x16x32_bf16 v[46:49], v[154:157], v[184:187], v[46:49]
	v_mfma_f32_16x16x32_bf16 v[42:45], v[162:165], v[184:187], v[42:45]
	v_mfma_f32_16x16x32_bf16 v[30:33], v[154:157], v[192:195], v[30:33]
	v_mfma_f32_16x16x32_bf16 v[26:29], v[162:165], v[192:195], v[26:29]
	v_mfma_f32_16x16x32_bf16 v[14:17], v[154:157], v[200:203], v[14:17]
	v_mfma_f32_16x16x32_bf16 v[10:13], v[162:165], v[200:203], v[10:13]
	v_mfma_f32_16x16x32_bf16 v[62:65], v[158:161], v[180:183], v[62:65]
	v_mfma_f32_16x16x32_bf16 v[58:61], v[166:169], v[180:183], v[58:61]
	v_mfma_f32_16x16x32_bf16 v[46:49], v[158:161], v[188:191], v[46:49]
	v_mfma_f32_16x16x32_bf16 v[42:45], v[166:169], v[188:191], v[42:45]
	v_mfma_f32_16x16x32_bf16 v[30:33], v[158:161], v[196:199], v[30:33]
	v_mfma_f32_16x16x32_bf16 v[26:29], v[166:169], v[196:199], v[26:29]
	v_mfma_f32_16x16x32_bf16 v[14:17], v[158:161], v[204:207], v[14:17]
	v_mfma_f32_16x16x32_bf16 v[10:13], v[166:169], v[204:207], v[10:13]
	v_mfma_f32_16x16x32_bf16 v[54:57], v[208:211], v[176:179], v[54:57]
	v_mfma_f32_16x16x32_bf16 v[50:53], v[216:219], v[176:179], v[50:53]
	v_mfma_f32_16x16x32_bf16 v[38:41], v[208:211], v[184:187], v[38:41]
	v_mfma_f32_16x16x32_bf16 v[34:37], v[216:219], v[184:187], v[34:37]
	v_mfma_f32_16x16x32_bf16 v[22:25], v[208:211], v[192:195], v[22:25]
	v_mfma_f32_16x16x32_bf16 v[18:21], v[216:219], v[192:195], v[18:21]
	v_mfma_f32_16x16x32_bf16 v[6:9], v[208:211], v[200:203], v[6:9]
	v_mfma_f32_16x16x32_bf16 v[2:5], v[216:219], v[200:203], v[2:5]
	v_mfma_f32_16x16x32_bf16 v[54:57], v[212:215], v[180:183], v[54:57]
	v_mfma_f32_16x16x32_bf16 v[50:53], v[220:223], v[180:183], v[50:53]
	v_mfma_f32_16x16x32_bf16 v[38:41], v[212:215], v[188:191], v[38:41]
	v_mfma_f32_16x16x32_bf16 v[34:37], v[220:223], v[188:191], v[34:37]
	v_mfma_f32_16x16x32_bf16 v[22:25], v[212:215], v[196:199], v[22:25]
	v_mfma_f32_16x16x32_bf16 v[18:21], v[220:223], v[196:199], v[18:21]
	v_mfma_f32_16x16x32_bf16 v[6:9], v[212:215], v[204:207], v[6:9]
	v_mfma_f32_16x16x32_bf16 v[2:5], v[220:223], v[204:207], v[2:5]
	s_barrier
	s_setprio 0
	s_add_i32 s79, s79, 2
	s_add_u32 s16, s16, 0x100
	s_addc_u32 s17, s17, 0
	s_add_u32 s77, s77, 0x100
	s_addc_u32 s78, s78, 0
	s_cmp_gt_u32 s79, 13
	s_cbranch_scc0 .LBB0_567
	v_mul_f32_e32 v154, 0xbfb8aa3b, v126
	v_mul_f32_e32 v155, 0xbfb8aa3b, v127
	v_exp_f32_e32 v154, v154
	v_exp_f32_e32 v155, v155
	s_and_b64 vcc, exec, s[2:3]
	s_mov_b64 s[34:35], s[12:13]
	v_add_f32_e32 v154, 1.0, v154
	v_add_f32_e32 v155, 1.0, v155
	v_rcp_f32_e32 v156, v154
	v_rcp_f32_e32 v157, v155
	v_mul_f32_e32 v155, 0xbfb8aa3b, v128
	v_exp_f32_e32 v155, v155
	v_lshl_add_u32 v154, s14, 8, v149
	v_pk_mul_f32 v[126:127], v[126:127], v[156:157]
	v_mul_f32_e32 v156, 0xbfb8aa3b, v129
	v_exp_f32_e32 v156, v156
	v_pk_mul_f32 v[118:119], v[126:127], v[118:119]
	v_add_f32_e32 v126, 1.0, v155
	v_mul_f32_e32 v155, 0xbfb8aa3b, v122
	v_add_f32_e32 v127, 1.0, v156
	v_rcp_f32_e32 v126, v126
	v_rcp_f32_e32 v127, v127
	v_exp_f32_e32 v155, v155
	v_mul_f32_e32 v156, 0xbfb8aa3b, v123
	v_exp_f32_e32 v156, v156
	v_pk_mul_f32 v[126:127], v[128:129], v[126:127]
	v_add_f32_e32 v128, 1.0, v155
	v_mul_f32_e32 v155, 0xbfb8aa3b, v124
	v_add_f32_e32 v129, 1.0, v156
	v_exp_f32_e32 v155, v155
	v_mul_f32_e32 v156, 0xbfb8aa3b, v125
	v_exp_f32_e32 v157, v156
	v_rcp_f32_e32 v128, v128
	v_add_f32_e32 v155, 1.0, v155
	v_rcp_f32_e32 v129, v129
	v_rcp_f32_e32 v156, v155
	v_add_f32_e32 v155, 1.0, v157
	v_rcp_f32_e32 v157, v155
	v_pk_mul_f32 v[122:123], v[122:123], v[128:129]
	s_lshl_b32 s14, s15, 7
	v_pk_mul_f32 v[122:123], v[122:123], v[114:115]
	v_pk_mul_f32 v[114:115], v[124:125], v[156:157]
	s_ashr_i32 s15, s14, 31
	v_pk_mul_f32 v[124:125], v[114:115], v[116:117]
	v_mov_b64_e32 v[114:115], s[0:1]
	v_mad_i64_i32 v[116:117], s[16:17], v154, s74, v[114:115]
	s_lshl_b64 s[14:15], s[14:15], 1
	v_lshl_add_u64 v[116:117], v[116:117], 0, s[14:15]
	v_pk_mul_f32 v[120:121], v[126:127], v[120:121]
	v_lshl_add_u64 v[126:127], v[116:117], 0, v[138:139]
	v_cvt_pk_bf16_f32 v116, v118, v119
	v_mul_f32_e32 v118, 0xbfb8aa3b, v110
	v_exp_f32_e32 v119, v118
	v_mul_f32_e32 v118, 0xbfb8aa3b, v111
	v_cvt_pk_bf16_f32 v117, v120, v121
	v_exp_f32_e32 v121, v118
	v_add_f32_e32 v119, 1.0, v119
	v_rcp_f32_e32 v120, v119
	v_cvt_pk_bf16_f32 v118, v122, v123
	v_add_f32_e32 v119, 1.0, v121
	v_rcp_f32_e32 v121, v119
	v_cvt_pk_bf16_f32 v119, v124, v125
	global_store_dwordx4 v[126:127], v[116:119], off nt
	v_pk_mul_f32 v[110:111], v[110:111], v[120:121]
	s_nop 0
	v_mul_f32_e32 v116, 0xbfb8aa3b, v112
	v_mul_f32_e32 v117, 0xbfb8aa3b, v113
	v_exp_f32_e32 v116, v116
	v_exp_f32_e32 v117, v117
	v_pk_mul_f32 v[102:103], v[110:111], v[102:103]
	v_or_b32_e32 v118, 16, v154
	v_add_f32_e32 v110, 1.0, v116
	v_add_f32_e32 v111, 1.0, v117
	v_mul_f32_e32 v116, 0xbfb8aa3b, v106
	v_mul_f32_e32 v117, 0xbfb8aa3b, v107
	v_rcp_f32_e32 v110, v110
	v_rcp_f32_e32 v111, v111
	v_exp_f32_e32 v116, v116
	v_exp_f32_e32 v117, v117
	v_pk_mul_f32 v[110:111], v[112:113], v[110:111]
	v_add_f32_e32 v112, 1.0, v116
	v_add_f32_e32 v113, 1.0, v117
	v_mul_f32_e32 v116, 0xbfb8aa3b, v108
	v_mul_f32_e32 v117, 0xbfb8aa3b, v109
	v_exp_f32_e32 v116, v116
	v_exp_f32_e32 v117, v117
	v_rcp_f32_e32 v112, v112
	v_rcp_f32_e32 v113, v113
	v_add_f32_e32 v116, 1.0, v116
	v_add_f32_e32 v117, 1.0, v117
	v_rcp_f32_e32 v116, v116
	v_rcp_f32_e32 v117, v117
	v_pk_mul_f32 v[106:107], v[106:107], v[112:113]
	v_pk_mul_f32 v[104:105], v[110:111], v[104:105]
	v_pk_mul_f32 v[106:107], v[106:107], v[98:99]
	v_pk_mul_f32 v[98:99], v[108:109], v[116:117]
	s_nop 0
	v_pk_mul_f32 v[108:109], v[98:99], v[100:101]
	v_mad_i64_i32 v[98:99], s[16:17], v118, s74, v[114:115]
	v_mul_f32_e32 v100, 0xbfb8aa3b, v94
	v_lshl_add_u64 v[98:99], v[98:99], 0, s[14:15]
	v_exp_f32_e32 v101, v100
	v_mul_f32_e32 v100, 0xbfb8aa3b, v95
	v_lshl_add_u64 v[110:111], v[98:99], 0, v[138:139]
	v_cvt_pk_bf16_f32 v98, v102, v103
	v_exp_f32_e32 v103, v100
	v_add_f32_e32 v101, 1.0, v101
	v_rcp_f32_e32 v102, v101
	v_cvt_pk_bf16_f32 v99, v104, v105
	v_add_f32_e32 v101, 1.0, v103
	v_cvt_pk_bf16_f32 v100, v106, v107
	v_rcp_f32_e32 v103, v101
	v_cvt_pk_bf16_f32 v101, v108, v109
	global_store_dwordx4 v[110:111], v[98:101], off nt
	v_pk_mul_f32 v[94:95], v[94:95], v[102:103]
	s_nop 0
	v_mul_f32_e32 v98, 0xbfb8aa3b, v96
	v_mul_f32_e32 v99, 0xbfb8aa3b, v97
	v_exp_f32_e32 v98, v98
	v_exp_f32_e32 v99, v99
	v_pk_mul_f32 v[86:87], v[94:95], v[86:87]
	v_or_b32_e32 v100, 32, v154
	v_add_f32_e32 v94, 1.0, v98
	v_add_f32_e32 v95, 1.0, v99
	v_mul_f32_e32 v98, 0xbfb8aa3b, v90
	v_mul_f32_e32 v99, 0xbfb8aa3b, v91
	v_rcp_f32_e32 v94, v94
	v_rcp_f32_e32 v95, v95
	v_exp_f32_e32 v98, v98
	v_exp_f32_e32 v99, v99
	v_pk_mul_f32 v[94:95], v[96:97], v[94:95]
	v_add_f32_e32 v96, 1.0, v98
	v_add_f32_e32 v97, 1.0, v99
	v_mul_f32_e32 v98, 0xbfb8aa3b, v92
	v_mul_f32_e32 v99, 0xbfb8aa3b, v93
	v_exp_f32_e32 v98, v98
	v_exp_f32_e32 v99, v99
	v_rcp_f32_e32 v96, v96
	v_rcp_f32_e32 v97, v97
	v_add_f32_e32 v98, 1.0, v98
	v_add_f32_e32 v99, 1.0, v99
	v_rcp_f32_e32 v98, v98
	v_rcp_f32_e32 v99, v99
	v_pk_mul_f32 v[90:91], v[90:91], v[96:97]
	v_pk_mul_f32 v[88:89], v[94:95], v[88:89]
	v_pk_mul_f32 v[90:91], v[90:91], v[82:83]
	v_pk_mul_f32 v[82:83], v[92:93], v[98:99]
	s_nop 0
	v_pk_mul_f32 v[92:93], v[82:83], v[84:85]
	v_mad_i64_i32 v[82:83], s[16:17], v100, s74, v[114:115]
	v_mul_f32_e32 v84, 0xbfb8aa3b, v78
	v_lshl_add_u64 v[82:83], v[82:83], 0, s[14:15]
	v_exp_f32_e32 v85, v84
	v_mul_f32_e32 v84, 0xbfb8aa3b, v79
	v_lshl_add_u64 v[94:95], v[82:83], 0, v[138:139]
	v_cvt_pk_bf16_f32 v82, v86, v87
	v_exp_f32_e32 v87, v84
	v_add_f32_e32 v85, 1.0, v85
	v_rcp_f32_e32 v86, v85
	v_cvt_pk_bf16_f32 v83, v88, v89
	v_add_f32_e32 v85, 1.0, v87
	v_cvt_pk_bf16_f32 v84, v90, v91
	v_rcp_f32_e32 v87, v85
	v_cvt_pk_bf16_f32 v85, v92, v93
	global_store_dwordx4 v[94:95], v[82:85], off nt
	v_pk_mul_f32 v[78:79], v[78:79], v[86:87]
	s_nop 0
	v_mul_f32_e32 v82, 0xbfb8aa3b, v80
	v_mul_f32_e32 v83, 0xbfb8aa3b, v81
	v_exp_f32_e32 v82, v82
	v_exp_f32_e32 v83, v83
	v_pk_mul_f32 v[70:71], v[78:79], v[70:71]
	v_or_b32_e32 v84, 48, v154
	v_add_f32_e32 v78, 1.0, v82
	v_add_f32_e32 v79, 1.0, v83
	v_mul_f32_e32 v82, 0xbfb8aa3b, v74
	v_mul_f32_e32 v83, 0xbfb8aa3b, v75
	v_rcp_f32_e32 v78, v78
	v_rcp_f32_e32 v79, v79
	v_exp_f32_e32 v82, v82
	v_exp_f32_e32 v83, v83
	v_pk_mul_f32 v[78:79], v[80:81], v[78:79]
	v_add_f32_e32 v80, 1.0, v82
	v_add_f32_e32 v81, 1.0, v83
	v_mul_f32_e32 v82, 0xbfb8aa3b, v76
	v_mul_f32_e32 v83, 0xbfb8aa3b, v77
	v_exp_f32_e32 v82, v82
	v_exp_f32_e32 v83, v83
	v_rcp_f32_e32 v80, v80
	v_rcp_f32_e32 v81, v81
	v_add_f32_e32 v82, 1.0, v82
	v_add_f32_e32 v83, 1.0, v83
	v_rcp_f32_e32 v82, v82
	v_rcp_f32_e32 v83, v83
	v_pk_mul_f32 v[74:75], v[74:75], v[80:81]
	v_pk_mul_f32 v[72:73], v[78:79], v[72:73]
	v_pk_mul_f32 v[74:75], v[74:75], v[66:67]
	v_pk_mul_f32 v[66:67], v[76:77], v[82:83]
	s_nop 0
	v_pk_mul_f32 v[76:77], v[66:67], v[68:69]
	v_mad_i64_i32 v[66:67], s[16:17], v84, s74, v[114:115]
	v_mul_f32_e32 v68, 0xbfb8aa3b, v62
	v_lshl_add_u64 v[66:67], v[66:67], 0, s[14:15]
	v_exp_f32_e32 v69, v68
	v_mul_f32_e32 v68, 0xbfb8aa3b, v63
	v_lshl_add_u64 v[78:79], v[66:67], 0, v[138:139]
	v_cvt_pk_bf16_f32 v66, v70, v71
	v_exp_f32_e32 v71, v68
	v_add_f32_e32 v69, 1.0, v69
	v_rcp_f32_e32 v70, v69
	v_cvt_pk_bf16_f32 v67, v72, v73
	v_add_f32_e32 v69, 1.0, v71
	v_cvt_pk_bf16_f32 v68, v74, v75
	v_rcp_f32_e32 v71, v69
	v_cvt_pk_bf16_f32 v69, v76, v77
	global_store_dwordx4 v[78:79], v[66:69], off nt
	v_pk_mul_f32 v[62:63], v[62:63], v[70:71]
	s_nop 0
	v_mul_f32_e32 v66, 0xbfb8aa3b, v64
	v_mul_f32_e32 v67, 0xbfb8aa3b, v65
	v_exp_f32_e32 v66, v66
	v_exp_f32_e32 v67, v67
	v_pk_mul_f32 v[54:55], v[62:63], v[54:55]
	v_add_u32_e32 v68, 0x80, v154
	v_add_f32_e32 v62, 1.0, v66
	v_add_f32_e32 v63, 1.0, v67
	v_mul_f32_e32 v66, 0xbfb8aa3b, v58
	v_mul_f32_e32 v67, 0xbfb8aa3b, v59
	v_rcp_f32_e32 v62, v62
	v_rcp_f32_e32 v63, v63
	v_exp_f32_e32 v66, v66
	v_exp_f32_e32 v67, v67
	v_pk_mul_f32 v[62:63], v[64:65], v[62:63]
	v_add_f32_e32 v64, 1.0, v66
	v_add_f32_e32 v65, 1.0, v67
	v_mul_f32_e32 v66, 0xbfb8aa3b, v60
	v_mul_f32_e32 v67, 0xbfb8aa3b, v61
	v_exp_f32_e32 v66, v66
	v_exp_f32_e32 v67, v67
	v_rcp_f32_e32 v64, v64
	v_rcp_f32_e32 v65, v65
	v_add_f32_e32 v66, 1.0, v66
	v_add_f32_e32 v67, 1.0, v67
	v_rcp_f32_e32 v66, v66
	v_rcp_f32_e32 v67, v67
	v_pk_mul_f32 v[58:59], v[58:59], v[64:65]
	v_pk_mul_f32 v[56:57], v[62:63], v[56:57]
	v_pk_mul_f32 v[58:59], v[58:59], v[50:51]
	v_pk_mul_f32 v[50:51], v[60:61], v[66:67]
	s_nop 0
	v_pk_mul_f32 v[60:61], v[50:51], v[52:53]
	v_mad_i64_i32 v[50:51], s[16:17], v68, s74, v[114:115]
	v_mul_f32_e32 v52, 0xbfb8aa3b, v46
	v_lshl_add_u64 v[50:51], v[50:51], 0, s[14:15]
	v_exp_f32_e32 v53, v52
	v_mul_f32_e32 v52, 0xbfb8aa3b, v47
	v_lshl_add_u64 v[62:63], v[50:51], 0, v[138:139]
	v_cvt_pk_bf16_f32 v50, v54, v55
	v_exp_f32_e32 v55, v52
	v_add_f32_e32 v53, 1.0, v53
	v_rcp_f32_e32 v54, v53
	v_cvt_pk_bf16_f32 v51, v56, v57
	v_add_f32_e32 v53, 1.0, v55
	v_cvt_pk_bf16_f32 v52, v58, v59
	v_rcp_f32_e32 v55, v53
	v_cvt_pk_bf16_f32 v53, v60, v61
	global_store_dwordx4 v[62:63], v[50:53], off nt
	v_pk_mul_f32 v[46:47], v[46:47], v[54:55]
	s_nop 0
	v_mul_f32_e32 v50, 0xbfb8aa3b, v48
	v_mul_f32_e32 v51, 0xbfb8aa3b, v49
	v_exp_f32_e32 v50, v50
	v_exp_f32_e32 v51, v51
	v_pk_mul_f32 v[38:39], v[46:47], v[38:39]
	v_add_u32_e32 v52, 0x90, v154
	v_add_f32_e32 v46, 1.0, v50
	v_add_f32_e32 v47, 1.0, v51
	v_mul_f32_e32 v50, 0xbfb8aa3b, v42
	v_mul_f32_e32 v51, 0xbfb8aa3b, v43
	v_rcp_f32_e32 v46, v46
	v_rcp_f32_e32 v47, v47
	v_exp_f32_e32 v50, v50
	v_exp_f32_e32 v51, v51
	v_pk_mul_f32 v[46:47], v[48:49], v[46:47]
	v_add_f32_e32 v48, 1.0, v50
	v_add_f32_e32 v49, 1.0, v51
	v_mul_f32_e32 v50, 0xbfb8aa3b, v44
	v_mul_f32_e32 v51, 0xbfb8aa3b, v45
	v_exp_f32_e32 v50, v50
	v_exp_f32_e32 v51, v51
	v_rcp_f32_e32 v48, v48
	v_rcp_f32_e32 v49, v49
	v_add_f32_e32 v50, 1.0, v50
	v_add_f32_e32 v51, 1.0, v51
	v_rcp_f32_e32 v50, v50
	v_rcp_f32_e32 v51, v51
	v_pk_mul_f32 v[42:43], v[42:43], v[48:49]
	v_pk_mul_f32 v[40:41], v[46:47], v[40:41]
	v_pk_mul_f32 v[42:43], v[42:43], v[34:35]
	v_pk_mul_f32 v[34:35], v[44:45], v[50:51]
	s_nop 0
	v_pk_mul_f32 v[44:45], v[34:35], v[36:37]
	v_mad_i64_i32 v[34:35], s[16:17], v52, s74, v[114:115]
	v_mul_f32_e32 v36, 0xbfb8aa3b, v30
	v_lshl_add_u64 v[34:35], v[34:35], 0, s[14:15]
	v_exp_f32_e32 v37, v36
	v_mul_f32_e32 v36, 0xbfb8aa3b, v31
	v_lshl_add_u64 v[46:47], v[34:35], 0, v[138:139]
	v_cvt_pk_bf16_f32 v34, v38, v39
	v_exp_f32_e32 v39, v36
	v_add_f32_e32 v37, 1.0, v37
	v_rcp_f32_e32 v38, v37
	v_cvt_pk_bf16_f32 v35, v40, v41
	v_add_f32_e32 v37, 1.0, v39
	v_cvt_pk_bf16_f32 v36, v42, v43
	v_rcp_f32_e32 v39, v37
	v_cvt_pk_bf16_f32 v37, v44, v45
	global_store_dwordx4 v[46:47], v[34:37], off nt
	v_pk_mul_f32 v[30:31], v[30:31], v[38:39]
	s_nop 0
	v_mul_f32_e32 v34, 0xbfb8aa3b, v32
	v_mul_f32_e32 v35, 0xbfb8aa3b, v33
	v_exp_f32_e32 v34, v34
	v_exp_f32_e32 v35, v35
	v_pk_mul_f32 v[22:23], v[30:31], v[22:23]
	v_add_u32_e32 v36, 0xa0, v154
	v_add_f32_e32 v30, 1.0, v34
	v_add_f32_e32 v31, 1.0, v35
	v_mul_f32_e32 v34, 0xbfb8aa3b, v26
	v_mul_f32_e32 v35, 0xbfb8aa3b, v27
	v_rcp_f32_e32 v30, v30
	v_rcp_f32_e32 v31, v31
	v_exp_f32_e32 v34, v34
	v_exp_f32_e32 v35, v35
	v_pk_mul_f32 v[30:31], v[32:33], v[30:31]
	v_add_f32_e32 v32, 1.0, v34
	v_add_f32_e32 v33, 1.0, v35
	v_mul_f32_e32 v34, 0xbfb8aa3b, v28
	v_mul_f32_e32 v35, 0xbfb8aa3b, v29
	v_exp_f32_e32 v34, v34
	v_exp_f32_e32 v35, v35
	v_rcp_f32_e32 v32, v32
	v_rcp_f32_e32 v33, v33
	v_add_f32_e32 v34, 1.0, v34
	v_add_f32_e32 v35, 1.0, v35
	v_rcp_f32_e32 v34, v34
	v_rcp_f32_e32 v35, v35
	v_pk_mul_f32 v[26:27], v[26:27], v[32:33]
	v_pk_mul_f32 v[24:25], v[30:31], v[24:25]
	v_pk_mul_f32 v[26:27], v[26:27], v[18:19]
	v_pk_mul_f32 v[18:19], v[28:29], v[34:35]
	s_nop 0
	v_pk_mul_f32 v[28:29], v[18:19], v[20:21]
	v_mad_i64_i32 v[18:19], s[16:17], v36, s74, v[114:115]
	v_mul_f32_e32 v20, 0xbfb8aa3b, v14
	v_lshl_add_u64 v[18:19], v[18:19], 0, s[14:15]
	v_exp_f32_e32 v21, v20
	v_mul_f32_e32 v20, 0xbfb8aa3b, v15
	v_lshl_add_u64 v[30:31], v[18:19], 0, v[138:139]
	v_cvt_pk_bf16_f32 v18, v22, v23
	v_exp_f32_e32 v23, v20
	v_add_f32_e32 v21, 1.0, v21
	v_rcp_f32_e32 v22, v21
	v_cvt_pk_bf16_f32 v19, v24, v25
	v_add_f32_e32 v21, 1.0, v23
	v_cvt_pk_bf16_f32 v20, v26, v27
	v_rcp_f32_e32 v23, v21
	v_cvt_pk_bf16_f32 v21, v28, v29
	global_store_dwordx4 v[30:31], v[18:21], off nt
	v_pk_mul_f32 v[14:15], v[14:15], v[22:23]
	s_nop 0
	v_mul_f32_e32 v18, 0xbfb8aa3b, v16
	v_mul_f32_e32 v19, 0xbfb8aa3b, v17
	v_exp_f32_e32 v18, v18
	v_exp_f32_e32 v19, v19
	v_pk_mul_f32 v[6:7], v[14:15], v[6:7]
	v_add_u32_e32 v20, 0xb0, v154
	v_add_f32_e32 v14, 1.0, v18
	v_add_f32_e32 v15, 1.0, v19
	v_mul_f32_e32 v18, 0xbfb8aa3b, v10
	v_mul_f32_e32 v19, 0xbfb8aa3b, v11
	v_rcp_f32_e32 v14, v14
	v_rcp_f32_e32 v15, v15
	v_exp_f32_e32 v18, v18
	v_exp_f32_e32 v19, v19
	v_pk_mul_f32 v[14:15], v[16:17], v[14:15]
	v_add_f32_e32 v16, 1.0, v18
	v_add_f32_e32 v17, 1.0, v19
	v_mul_f32_e32 v18, 0xbfb8aa3b, v12
	v_mul_f32_e32 v19, 0xbfb8aa3b, v13
	v_exp_f32_e32 v18, v18
	v_exp_f32_e32 v19, v19
	v_rcp_f32_e32 v16, v16
	v_rcp_f32_e32 v17, v17
	v_add_f32_e32 v18, 1.0, v18
	v_add_f32_e32 v19, 1.0, v19
	v_rcp_f32_e32 v18, v18
	v_rcp_f32_e32 v19, v19
	v_pk_mul_f32 v[10:11], v[10:11], v[16:17]
	v_pk_mul_f32 v[8:9], v[14:15], v[8:9]
	v_pk_mul_f32 v[10:11], v[10:11], v[2:3]
	v_pk_mul_f32 v[2:3], v[12:13], v[18:19]
	s_nop 0
	v_pk_mul_f32 v[12:13], v[2:3], v[4:5]
	v_mad_i64_i32 v[2:3], s[16:17], v20, s74, v[114:115]
	v_lshl_add_u64 v[2:3], v[2:3], 0, s[14:15]
	v_lshl_add_u64 v[14:15], v[2:3], 0, v[138:139]
	v_cvt_pk_bf16_f32 v2, v6, v7
	v_cvt_pk_bf16_f32 v3, v8, v9
	v_cvt_pk_bf16_f32 v4, v10, v11
	v_cvt_pk_bf16_f32 v5, v12, v13
	s_mov_b32 s15, s6
	s_mov_b32 s14, s8
	s_mov_b64 s[16:17], s[10:11]
	global_store_dwordx4 v[14:15], v[2:5], off nt
	s_cbranch_vccz .LBB0_564
	s_waitcnt vmcnt(0)
	s_cmpk_gt_u32 s33, 0xff
	s_cbranch_scc1 .LBB0_571
	s_barrier

.LBB0_1374:
	s_ashr_i32 s41, s40, 31
	s_xor_b64 s[50:51], s[18:19], -1
	s_lshl_b64 s[20:21], s[40:41], 19
	s_add_u32 s48, s65, s20
	s_addc_u32 s49, s66, s21
	s_and_b64 s[20:21], s[18:19], exec
	s_cselect_b32 s3, s49, s35
	s_cselect_b32 s5, s48, s34
	s_ashr_i32 s39, s38, 31
	s_lshl_b64 s[20:21], s[38:39], 19
	s_add_u32 s52, s67, s20
	s_addc_u32 s53, s68, s21
	s_and_b64 s[18:19], s[18:19], exec
	s_cselect_b32 s39, s53, s55
	s_cselect_b32 s41, s52, s54
	s_add_u32 s34, s34, 0x40080
	s_addc_u32 s35, s35, 0
	s_add_u32 s56, s54, 0x100
	s_addc_u32 s57, s55, 0
	s_mov_b32 vcc_lo, -2
	s_waitcnt vmcnt(0)
	ds_read_b128 v[10:13], v225
	ds_read_b128 v[14:17], v225 offset:1024
	ds_read_b128 v[26:29], v225 offset:2048
	ds_read_b128 v[30:33], v225 offset:3072
	s_add_u32 s18, s34, 0xfffc0080
	s_addc_u32 s19, s35, -1
	s_cmp_eq_u32 vcc_lo, 12
	s_cselect_b32 s19, s3, s19
	s_cselect_b32 s18, s5, s18
	s_cselect_b32 s55, s39, s57
	s_cselect_b32 s54, s41, s56
	v_lshl_add_u64 v[202:203], s[34:35], 0, v[178:179]
	s_add_i32 m0, s72, 0xc000
	ds_read_b128 v[34:37], v226
	ds_read_b128 v[38:41], v226 offset:1024
	ds_read_b128 v[50:53], v226 offset:2048
	ds_read_b128 v[54:57], v226 offset:3072
	ds_read_b128 v[186:189], v226 offset:4096
	ds_read_b128 v[190:193], v226 offset:5120
	ds_read_b128 v[194:197], v226 offset:6144
	ds_read_b128 v[198:201], v226 offset:7168
	global_load_lds_dwordx4 v[202:203], off
	v_lshl_add_u64 v[202:203], s[34:35], 0, v[180:181]
	s_add_i32 m0, s72, 0xe000
	s_nop 0
	global_load_lds_dwordx4 v[202:203], off
	ds_read_b128 v[202:205], v227
	ds_read_b128 v[206:209], v227 offset:1024
	ds_read_b128 v[210:213], v227 offset:2048
	ds_read_b128 v[214:217], v227 offset:3072
	s_waitcnt vmcnt(8)
	s_waitcnt lgkmcnt(0)
	s_setprio 1
	s_barrier
	v_mfma_f32_16x16x32_bf16 v[158:161], v[10:13], v[34:37], 0
	v_mfma_f32_16x16x32_bf16 v[154:157], v[26:29], v[34:37], 0
	v_mfma_f32_16x16x32_bf16 v[142:145], v[10:13], v[50:53], 0
	v_mfma_f32_16x16x32_bf16 v[138:141], v[26:29], v[50:53], 0
	v_mfma_f32_16x16x32_bf16 v[126:129], v[10:13], v[186:189], 0
	v_mfma_f32_16x16x32_bf16 v[122:125], v[26:29], v[186:189], 0
	v_mfma_f32_16x16x32_bf16 v[110:113], v[10:13], v[194:197], 0
	v_mfma_f32_16x16x32_bf16 v[106:109], v[26:29], v[194:197], 0
	v_mfma_f32_16x16x32_bf16 v[158:161], v[14:17], v[38:41], v[158:161]
	v_mfma_f32_16x16x32_bf16 v[154:157], v[30:33], v[38:41], v[154:157]
	v_mfma_f32_16x16x32_bf16 v[142:145], v[14:17], v[54:57], v[142:145]
	v_mfma_f32_16x16x32_bf16 v[138:141], v[30:33], v[54:57], v[138:141]
	v_mfma_f32_16x16x32_bf16 v[126:129], v[14:17], v[190:193], v[126:129]
	v_mfma_f32_16x16x32_bf16 v[122:125], v[30:33], v[190:193], v[122:125]
	v_mfma_f32_16x16x32_bf16 v[110:113], v[14:17], v[198:201], v[110:113]
	v_mfma_f32_16x16x32_bf16 v[106:109], v[30:33], v[198:201], v[106:109]
	v_mfma_f32_16x16x32_bf16 v[150:153], v[202:205], v[34:37], 0
	v_mfma_f32_16x16x32_bf16 v[34:37], v[210:213], v[34:37], 0
	v_mfma_f32_16x16x32_bf16 v[150:153], v[206:209], v[38:41], v[150:153]
	v_mfma_f32_16x16x32_bf16 v[34:37], v[214:217], v[38:41], v[34:37]
	v_mfma_f32_16x16x32_bf16 v[38:41], v[202:205], v[50:53], 0
	v_mfma_f32_16x16x32_bf16 v[50:53], v[210:213], v[50:53], 0
	v_mfma_f32_16x16x32_bf16 v[114:117], v[210:213], v[186:189], 0
	v_mfma_f32_16x16x32_bf16 v[102:105], v[202:205], v[194:197], 0
	v_mfma_f32_16x16x32_bf16 v[98:101], v[210:213], v[194:197], 0
	v_mfma_f32_16x16x32_bf16 v[38:41], v[206:209], v[54:57], v[38:41]
	v_mfma_f32_16x16x32_bf16 v[50:53], v[214:217], v[54:57], v[50:53]
	v_mfma_f32_16x16x32_bf16 v[54:57], v[202:205], v[186:189], 0
	v_mfma_f32_16x16x32_bf16 v[114:117], v[214:217], v[190:193], v[114:117]
	v_mfma_f32_16x16x32_bf16 v[102:105], v[206:209], v[198:201], v[102:105]
	v_mfma_f32_16x16x32_bf16 v[98:101], v[214:217], v[198:201], v[98:101]
	v_mfma_f32_16x16x32_bf16 v[54:57], v[206:209], v[190:193], v[54:57]
	s_barrier
	s_setprio 0
	s_add_i32 s20, s33, s71
	v_lshl_add_u64 v[222:223], s[54:55], 0, v[164:165]
	s_mov_b32 m0, s20
	s_nop 0
	global_load_lds_dwordx4 v[222:223], off
	v_lshl_add_u64 v[238:239], s[54:55], 0, v[168:169]
	s_add_i32 m0, s20, 0x2000
	s_nop 0
	global_load_lds_dwordx4 v[238:239], off
	s_mov_b32 m0, s72
	v_lshl_add_u64 v[240:241], s[18:19], 0, v[162:163]
	ds_read_b128 v[118:121], v226 offset:16384
	ds_read_b128 v[130:133], v226 offset:17408
	ds_read_b128 v[134:137], v226 offset:18432
	ds_read_b128 v[146:149], v226 offset:19456
	ds_read_b128 v[186:189], v226 offset:20480
	ds_read_b128 v[190:193], v226 offset:21504
	ds_read_b128 v[194:197], v226 offset:22528
	ds_read_b128 v[198:201], v226 offset:23552
	global_load_lds_dwordx4 v[240:241], off
	v_lshl_add_u64 v[242:243], s[18:19], 0, v[166:167]
	s_mov_b32 m0, s73
	s_nop 0
	global_load_lds_dwordx4 v[242:243], off
	s_add_u32 s20, s54, 0x40000
	s_addc_u32 s21, s55, 0
	s_add_i32 s60, s64, s71
	v_lshl_add_u64 v[246:247], s[20:21], 0, v[164:165]
	s_mov_b32 m0, s60
	s_nop 0
	global_load_lds_dwordx4 v[246:247], off
	v_lshl_add_u64 v[246:247], s[20:21], 0, v[168:169]
	s_add_i32 m0, s60, 0x2000
	s_nop 0
	global_load_lds_dwordx4 v[246:247], off
	s_waitcnt vmcnt(8)
	s_waitcnt lgkmcnt(0)
	s_setprio 1
	s_barrier
	v_mfma_f32_16x16x32_bf16 v[94:97], v[10:13], v[118:121], 0
	v_mfma_f32_16x16x32_bf16 v[90:93], v[26:29], v[118:121], 0
	v_mfma_f32_16x16x32_bf16 v[78:81], v[10:13], v[134:137], 0
	v_mfma_f32_16x16x32_bf16 v[74:77], v[26:29], v[134:137], 0
	v_mfma_f32_16x16x32_bf16 v[62:65], v[10:13], v[186:189], 0
	v_mfma_f32_16x16x32_bf16 v[58:61], v[26:29], v[186:189], 0
	v_mfma_f32_16x16x32_bf16 v[10:13], v[10:13], v[194:197], 0
	v_mfma_f32_16x16x32_bf16 v[94:97], v[14:17], v[130:133], v[94:97]
	v_mfma_f32_16x16x32_bf16 v[90:93], v[30:33], v[130:133], v[90:93]
	v_mfma_f32_16x16x32_bf16 v[78:81], v[14:17], v[146:149], v[78:81]
	v_mfma_f32_16x16x32_bf16 v[74:77], v[30:33], v[146:149], v[74:77]
	v_mfma_f32_16x16x32_bf16 v[62:65], v[14:17], v[190:193], v[62:65]
	v_mfma_f32_16x16x32_bf16 v[58:61], v[30:33], v[190:193], v[58:61]
	v_mfma_f32_16x16x32_bf16 v[10:13], v[14:17], v[198:201], v[10:13]
	v_mfma_f32_16x16x32_bf16 v[14:17], v[26:29], v[194:197], 0
	v_mfma_f32_16x16x32_bf16 v[14:17], v[30:33], v[198:201], v[14:17]
	v_mfma_f32_16x16x32_bf16 v[18:21], v[202:205], v[118:121], 0
	v_mfma_f32_16x16x32_bf16 v[26:29], v[206:209], v[130:133], v[18:21]
	v_mfma_f32_16x16x32_bf16 v[18:21], v[210:213], v[118:121], 0
	v_mfma_f32_16x16x32_bf16 v[30:33], v[214:217], v[130:133], v[18:21]
	v_mfma_f32_16x16x32_bf16 v[18:21], v[202:205], v[134:137], 0
	v_mfma_f32_16x16x32_bf16 v[70:73], v[206:209], v[146:149], v[18:21]
	v_mfma_f32_16x16x32_bf16 v[18:21], v[210:213], v[134:137], 0
	v_mfma_f32_16x16x32_bf16 v[66:69], v[214:217], v[146:149], v[18:21]
	v_mfma_f32_16x16x32_bf16 v[18:21], v[202:205], v[186:189], 0
	v_mfma_f32_16x16x32_bf16 v[46:49], v[206:209], v[190:193], v[18:21]
	v_mfma_f32_16x16x32_bf16 v[18:21], v[210:213], v[186:189], 0
	v_mfma_f32_16x16x32_bf16 v[6:9], v[202:205], v[194:197], 0
	v_mfma_f32_16x16x32_bf16 v[2:5], v[210:213], v[194:197], 0
	v_mfma_f32_16x16x32_bf16 v[42:45], v[214:217], v[190:193], v[18:21]
	v_mfma_f32_16x16x32_bf16 v[6:9], v[206:209], v[198:201], v[6:9]
	v_mfma_f32_16x16x32_bf16 v[2:5], v[214:217], v[198:201], v[2:5]
	s_barrier
	s_setprio 0
	s_add_i32 s20, 0, 0x18000
	v_add_u32_e32 v86, s20, v175
	ds_read_b128 v[18:21], v86
	ds_read_b128 v[22:25], v86 offset:1024
	ds_read_b128 v[82:85], v86 offset:2048
	ds_read_b128 v[86:89], v86 offset:3072
	s_add_u32 s18, s18, 0x40000
	s_addc_u32 s19, s19, 0
	s_mov_b32 m0, s74
	v_lshl_add_u64 v[134:135], s[18:19], 0, v[162:163]
	ds_read_b128 v[118:121], v226 offset:32768
	ds_read_b128 v[130:133], v226 offset:33792
	ds_read_b128 v[186:189], v226 offset:34816
	ds_read_b128 v[190:193], v226 offset:35840
	ds_read_b128 v[194:197], v226 offset:36864
	ds_read_b128 v[198:201], v226 offset:37888
	ds_read_b128 v[202:205], v226 offset:38912
	ds_read_b128 v[206:209], v226 offset:39936
	global_load_lds_dwordx4 v[134:135], off
	v_lshl_add_u64 v[134:135], s[18:19], 0, v[166:167]
	s_mov_b32 m0, s75
	s_nop 0
	global_load_lds_dwordx4 v[134:135], off
	s_add_i32 s21, 0, 0x1c000
	v_add_u32_e32 v244, s21, v175
	ds_read_b128 v[210:213], v244
	ds_read_b128 v[214:217], v244 offset:1024
	ds_read_b128 v[218:221], v244 offset:2048
	ds_read_b128 v[234:237], v244 offset:3072
	s_waitcnt vmcnt(8)
	s_waitcnt lgkmcnt(0)
	s_setprio 1
	s_barrier
	v_mfma_f32_16x16x32_bf16 v[134:137], v[18:21], v[118:121], v[158:161]
	v_mfma_f32_16x16x32_bf16 v[158:161], v[22:25], v[130:133], v[134:137]
	v_mfma_f32_16x16x32_bf16 v[134:137], v[82:85], v[118:121], v[154:157]
	v_mfma_f32_16x16x32_bf16 v[154:157], v[86:89], v[130:133], v[134:137]
	v_mfma_f32_16x16x32_bf16 v[134:137], v[18:21], v[186:189], v[142:145]
	v_mfma_f32_16x16x32_bf16 v[142:145], v[22:25], v[190:193], v[134:137]
	v_mfma_f32_16x16x32_bf16 v[134:137], v[82:85], v[186:189], v[138:141]
	v_mfma_f32_16x16x32_bf16 v[126:129], v[18:21], v[194:197], v[126:129]
	v_mfma_f32_16x16x32_bf16 v[122:125], v[82:85], v[194:197], v[122:125]
	v_mfma_f32_16x16x32_bf16 v[110:113], v[18:21], v[202:205], v[110:113]
	v_mfma_f32_16x16x32_bf16 v[106:109], v[82:85], v[202:205], v[106:109]
	v_mfma_f32_16x16x32_bf16 v[138:141], v[86:89], v[190:193], v[134:137]
	v_mfma_f32_16x16x32_bf16 v[126:129], v[22:25], v[198:201], v[126:129]
	v_mfma_f32_16x16x32_bf16 v[122:125], v[86:89], v[198:201], v[122:125]
	v_mfma_f32_16x16x32_bf16 v[110:113], v[22:25], v[206:209], v[110:113]
	v_mfma_f32_16x16x32_bf16 v[106:109], v[86:89], v[206:209], v[106:109]
	v_mfma_f32_16x16x32_bf16 v[34:37], v[218:221], v[118:121], v[34:37]
	v_mfma_f32_16x16x32_bf16 v[134:137], v[210:213], v[118:121], v[150:153]
	v_mfma_f32_16x16x32_bf16 v[146:149], v[234:237], v[130:133], v[34:37]
	v_mfma_f32_16x16x32_bf16 v[34:37], v[210:213], v[186:189], v[38:41]
	v_mfma_f32_16x16x32_bf16 v[150:153], v[214:217], v[130:133], v[134:137]
	v_mfma_f32_16x16x32_bf16 v[134:137], v[214:217], v[190:193], v[34:37]
	v_mfma_f32_16x16x32_bf16 v[34:37], v[218:221], v[186:189], v[50:53]
	v_mfma_f32_16x16x32_bf16 v[130:133], v[234:237], v[190:193], v[34:37]
	v_mfma_f32_16x16x32_bf16 v[34:37], v[210:213], v[194:197], v[54:57]
	v_mfma_f32_16x16x32_bf16 v[118:121], v[214:217], v[198:201], v[34:37]
	v_mfma_f32_16x16x32_bf16 v[34:37], v[218:221], v[194:197], v[114:117]
	v_mfma_f32_16x16x32_bf16 v[114:117], v[234:237], v[198:201], v[34:37]
	v_mfma_f32_16x16x32_bf16 v[34:37], v[210:213], v[202:205], v[102:105]
	v_mfma_f32_16x16x32_bf16 v[102:105], v[214:217], v[206:209], v[34:37]
	v_mfma_f32_16x16x32_bf16 v[34:37], v[218:221], v[202:205], v[98:101]
	v_mfma_f32_16x16x32_bf16 v[98:101], v[234:237], v[206:209], v[34:37]
	s_barrier
	s_setprio 0
	s_add_i32 s18, s20, s71
	v_lshl_add_u64 v[248:249], v[222:223], 0, s[24:25]
	s_mov_b32 m0, s18
	s_nop 0
	global_load_lds_dwordx4 v[248:249], off
	v_lshl_add_u64 v[248:249], v[238:239], 0, s[24:25]
	s_add_i32 m0, s18, 0x2000
	s_nop 0
	global_load_lds_dwordx4 v[248:249], off
	s_mov_b32 m0, s95
	v_lshl_add_u64 v[202:203], v[240:241], 0, s[24:25]
	s_nop 2
	ds_read_b128 v[34:37], v226 offset:49152
	ds_read_b128 v[38:41], v226 offset:50176
	ds_read_b128 v[50:53], v226 offset:51200
	ds_read_b128 v[54:57], v226 offset:52224
	ds_read_b128 v[186:189], v226 offset:53248
	ds_read_b128 v[190:193], v226 offset:54272
	ds_read_b128 v[194:197], v226 offset:55296
	ds_read_b128 v[198:201], v226 offset:56320
	global_load_lds_dwordx4 v[202:203], off
	v_lshl_add_u64 v[202:203], v[242:243], 0, s[24:25]
	s_mov_b32 m0, s96
	s_nop 0
	global_load_lds_dwordx4 v[202:203], off
	s_add_u32 s18, s54, 0x40080
	s_addc_u32 s19, s55, 0
	s_add_i32 s20, s21, s71
	v_lshl_add_u64 v[250:251], s[18:19], 0, v[164:165]
	s_mov_b32 m0, s20
	s_nop 0
	global_load_lds_dwordx4 v[250:251], off
	v_lshl_add_u64 v[250:251], s[18:19], 0, v[168:169]
	s_add_i32 m0, s20, 0x2000
	s_nop 0
	global_load_lds_dwordx4 v[250:251], off
	s_waitcnt vmcnt(8)
	s_waitcnt lgkmcnt(0)
	s_setprio 1
	s_barrier
	v_mfma_f32_16x16x32_bf16 v[94:97], v[18:21], v[34:37], v[94:97]
	v_mfma_f32_16x16x32_bf16 v[78:81], v[18:21], v[50:53], v[78:81]
	v_mfma_f32_16x16x32_bf16 v[62:65], v[18:21], v[186:189], v[62:65]
	v_mfma_f32_16x16x32_bf16 v[10:13], v[18:21], v[194:197], v[10:13]
	v_mfma_f32_16x16x32_bf16 v[94:97], v[22:25], v[38:41], v[94:97]
	v_mfma_f32_16x16x32_bf16 v[90:93], v[82:85], v[34:37], v[90:93]
	v_mfma_f32_16x16x32_bf16 v[78:81], v[22:25], v[54:57], v[78:81]
	v_mfma_f32_16x16x32_bf16 v[74:77], v[82:85], v[50:53], v[74:77]
	v_mfma_f32_16x16x32_bf16 v[62:65], v[22:25], v[190:193], v[62:65]
	v_mfma_f32_16x16x32_bf16 v[58:61], v[82:85], v[186:189], v[58:61]
	v_mfma_f32_16x16x32_bf16 v[22:25], v[22:25], v[198:201], v[10:13]
	v_mfma_f32_16x16x32_bf16 v[10:13], v[82:85], v[194:197], v[14:17]
	v_mfma_f32_16x16x32_bf16 v[90:93], v[86:89], v[38:41], v[90:93]
	v_mfma_f32_16x16x32_bf16 v[74:77], v[86:89], v[54:57], v[74:77]
	v_mfma_f32_16x16x32_bf16 v[58:61], v[86:89], v[190:193], v[58:61]
	v_mfma_f32_16x16x32_bf16 v[18:21], v[86:89], v[198:201], v[10:13]
	v_mfma_f32_16x16x32_bf16 v[10:13], v[210:213], v[34:37], v[26:29]
	v_mfma_f32_16x16x32_bf16 v[86:89], v[214:217], v[38:41], v[10:13]
	v_mfma_f32_16x16x32_bf16 v[10:13], v[218:221], v[34:37], v[30:33]
	v_mfma_f32_16x16x32_bf16 v[82:85], v[234:237], v[38:41], v[10:13]
	v_mfma_f32_16x16x32_bf16 v[10:13], v[210:213], v[50:53], v[70:73]
	v_mfma_f32_16x16x32_bf16 v[70:73], v[214:217], v[54:57], v[10:13]
	v_mfma_f32_16x16x32_bf16 v[10:13], v[218:221], v[50:53], v[66:69]
	v_mfma_f32_16x16x32_bf16 v[66:69], v[234:237], v[54:57], v[10:13]
	v_mfma_f32_16x16x32_bf16 v[10:13], v[210:213], v[186:189], v[46:49]
	v_mfma_f32_16x16x32_bf16 v[46:49], v[214:217], v[190:193], v[10:13]
	v_mfma_f32_16x16x32_bf16 v[10:13], v[218:221], v[186:189], v[42:45]
	v_mfma_f32_16x16x32_bf16 v[6:9], v[210:213], v[194:197], v[6:9]
	v_mfma_f32_16x16x32_bf16 v[2:5], v[218:221], v[194:197], v[2:5]
	v_mfma_f32_16x16x32_bf16 v[42:45], v[234:237], v[190:193], v[10:13]
	v_mfma_f32_16x16x32_bf16 v[6:9], v[214:217], v[198:201], v[6:9]
	v_mfma_f32_16x16x32_bf16 v[2:5], v[234:237], v[198:201], v[2:5]
	s_barrier
	s_setprio 0
	s_add_i32 vcc_lo, vcc_lo, 2
	s_add_u32 s34, s34, 0x100
	s_addc_u32 s35, s35, 0
	s_add_u32 s56, s56, 0x100
	s_addc_u32 s57, s57, 0
	s_cmp_gt_u32 vcc_lo, 13
.LBB0_1375:
	ds_read_b128 v[10:13], v225
	ds_read_b128 v[14:17], v225 offset:1024
	ds_read_b128 v[26:29], v225 offset:2048
	ds_read_b128 v[30:33], v225 offset:3072
	s_add_u32 s18, s34, 0xfffc0080
	s_addc_u32 s19, s35, -1
	s_cmp_eq_u32 vcc_lo, 12
	s_cselect_b32 s19, s3, s19
	s_cselect_b32 s18, s5, s18
	s_cselect_b32 s55, s39, s57
	s_cselect_b32 s54, s41, s56
	v_lshl_add_u64 v[202:203], s[34:35], 0, v[178:179]
	s_add_i32 m0, s72, 0xc000
	ds_read_b128 v[34:37], v226
	ds_read_b128 v[38:41], v226 offset:1024
	ds_read_b128 v[50:53], v226 offset:2048
	ds_read_b128 v[54:57], v226 offset:3072
	ds_read_b128 v[186:189], v226 offset:4096
	ds_read_b128 v[190:193], v226 offset:5120
	ds_read_b128 v[194:197], v226 offset:6144
	ds_read_b128 v[198:201], v226 offset:7168
	global_load_lds_dwordx4 v[202:203], off
	v_lshl_add_u64 v[202:203], s[34:35], 0, v[180:181]
	s_add_i32 m0, s72, 0xe000
	s_nop 0
	global_load_lds_dwordx4 v[202:203], off
	ds_read_b128 v[202:205], v227
	ds_read_b128 v[206:209], v227 offset:1024
	ds_read_b128 v[210:213], v227 offset:2048
	ds_read_b128 v[214:217], v227 offset:3072
	s_waitcnt vmcnt(8)
	s_waitcnt lgkmcnt(0)
	s_setprio 1
	s_barrier
	v_mfma_f32_16x16x32_bf16 v[158:161], v[10:13], v[34:37], v[158:161]
	v_mfma_f32_16x16x32_bf16 v[154:157], v[26:29], v[34:37], v[154:157]
	v_mfma_f32_16x16x32_bf16 v[142:145], v[10:13], v[50:53], v[142:145]
	v_mfma_f32_16x16x32_bf16 v[138:141], v[26:29], v[50:53], v[138:141]
	v_mfma_f32_16x16x32_bf16 v[126:129], v[10:13], v[186:189], v[126:129]
	v_mfma_f32_16x16x32_bf16 v[122:125], v[26:29], v[186:189], v[122:125]
	v_mfma_f32_16x16x32_bf16 v[110:113], v[10:13], v[194:197], v[110:113]
	v_mfma_f32_16x16x32_bf16 v[106:109], v[26:29], v[194:197], v[106:109]
	v_mfma_f32_16x16x32_bf16 v[158:161], v[14:17], v[38:41], v[158:161]
	v_mfma_f32_16x16x32_bf16 v[154:157], v[30:33], v[38:41], v[154:157]
	v_mfma_f32_16x16x32_bf16 v[142:145], v[14:17], v[54:57], v[142:145]
	v_mfma_f32_16x16x32_bf16 v[138:141], v[30:33], v[54:57], v[138:141]
	v_mfma_f32_16x16x32_bf16 v[126:129], v[14:17], v[190:193], v[126:129]
	v_mfma_f32_16x16x32_bf16 v[122:125], v[30:33], v[190:193], v[122:125]
	v_mfma_f32_16x16x32_bf16 v[110:113], v[14:17], v[198:201], v[110:113]
	v_mfma_f32_16x16x32_bf16 v[106:109], v[30:33], v[198:201], v[106:109]
	v_mfma_f32_16x16x32_bf16 v[150:153], v[202:205], v[34:37], v[150:153]
	v_mfma_f32_16x16x32_bf16 v[34:37], v[210:213], v[34:37], v[146:149]
	v_mfma_f32_16x16x32_bf16 v[150:153], v[206:209], v[38:41], v[150:153]
	v_mfma_f32_16x16x32_bf16 v[34:37], v[214:217], v[38:41], v[34:37]
	v_mfma_f32_16x16x32_bf16 v[38:41], v[202:205], v[50:53], v[134:137]
	v_mfma_f32_16x16x32_bf16 v[50:53], v[210:213], v[50:53], v[130:133]
	v_mfma_f32_16x16x32_bf16 v[114:117], v[210:213], v[186:189], v[114:117]
	v_mfma_f32_16x16x32_bf16 v[102:105], v[202:205], v[194:197], v[102:105]
	v_mfma_f32_16x16x32_bf16 v[98:101], v[210:213], v[194:197], v[98:101]
	v_mfma_f32_16x16x32_bf16 v[38:41], v[206:209], v[54:57], v[38:41]
	v_mfma_f32_16x16x32_bf16 v[50:53], v[214:217], v[54:57], v[50:53]
	v_mfma_f32_16x16x32_bf16 v[54:57], v[202:205], v[186:189], v[118:121]
	v_mfma_f32_16x16x32_bf16 v[114:117], v[214:217], v[190:193], v[114:117]
	v_mfma_f32_16x16x32_bf16 v[102:105], v[206:209], v[198:201], v[102:105]
	v_mfma_f32_16x16x32_bf16 v[98:101], v[214:217], v[198:201], v[98:101]
	v_mfma_f32_16x16x32_bf16 v[54:57], v[206:209], v[190:193], v[54:57]
	s_barrier
	s_setprio 0
	s_add_i32 s20, s33, s71
	v_lshl_add_u64 v[222:223], s[54:55], 0, v[164:165]
	s_mov_b32 m0, s20
	s_nop 0
	global_load_lds_dwordx4 v[222:223], off
	v_lshl_add_u64 v[238:239], s[54:55], 0, v[168:169]
	s_add_i32 m0, s20, 0x2000
	s_nop 0
	global_load_lds_dwordx4 v[238:239], off
	s_mov_b32 m0, s72
	v_lshl_add_u64 v[240:241], s[18:19], 0, v[162:163]
	ds_read_b128 v[118:121], v226 offset:16384
	ds_read_b128 v[130:133], v226 offset:17408
	ds_read_b128 v[134:137], v226 offset:18432
	ds_read_b128 v[146:149], v226 offset:19456
	ds_read_b128 v[186:189], v226 offset:20480
	ds_read_b128 v[190:193], v226 offset:21504
	ds_read_b128 v[194:197], v226 offset:22528
	ds_read_b128 v[198:201], v226 offset:23552
	global_load_lds_dwordx4 v[240:241], off
	v_lshl_add_u64 v[242:243], s[18:19], 0, v[166:167]
	s_mov_b32 m0, s73
	s_nop 0
	global_load_lds_dwordx4 v[242:243], off
	s_add_u32 s20, s54, 0x40000
	s_addc_u32 s21, s55, 0
	s_add_i32 s60, s64, s71
	v_lshl_add_u64 v[246:247], s[20:21], 0, v[164:165]
	s_mov_b32 m0, s60
	s_nop 0
	global_load_lds_dwordx4 v[246:247], off
	v_lshl_add_u64 v[246:247], s[20:21], 0, v[168:169]
	s_add_i32 m0, s60, 0x2000
	s_nop 0
	global_load_lds_dwordx4 v[246:247], off
	s_waitcnt vmcnt(8)
	s_waitcnt lgkmcnt(0)
	s_setprio 1
	s_barrier
	v_mfma_f32_16x16x32_bf16 v[94:97], v[10:13], v[118:121], v[94:97]
	v_mfma_f32_16x16x32_bf16 v[90:93], v[26:29], v[118:121], v[90:93]
	v_mfma_f32_16x16x32_bf16 v[78:81], v[10:13], v[134:137], v[78:81]
	v_mfma_f32_16x16x32_bf16 v[74:77], v[26:29], v[134:137], v[74:77]
	v_mfma_f32_16x16x32_bf16 v[62:65], v[10:13], v[186:189], v[62:65]
	v_mfma_f32_16x16x32_bf16 v[58:61], v[26:29], v[186:189], v[58:61]
	v_mfma_f32_16x16x32_bf16 v[10:13], v[10:13], v[194:197], v[22:25]
	v_mfma_f32_16x16x32_bf16 v[94:97], v[14:17], v[130:133], v[94:97]
	v_mfma_f32_16x16x32_bf16 v[90:93], v[30:33], v[130:133], v[90:93]
	v_mfma_f32_16x16x32_bf16 v[78:81], v[14:17], v[146:149], v[78:81]
	v_mfma_f32_16x16x32_bf16 v[74:77], v[30:33], v[146:149], v[74:77]
	v_mfma_f32_16x16x32_bf16 v[62:65], v[14:17], v[190:193], v[62:65]
	v_mfma_f32_16x16x32_bf16 v[58:61], v[30:33], v[190:193], v[58:61]
	v_mfma_f32_16x16x32_bf16 v[10:13], v[14:17], v[198:201], v[10:13]
	v_mfma_f32_16x16x32_bf16 v[14:17], v[26:29], v[194:197], v[18:21]
	v_mfma_f32_16x16x32_bf16 v[14:17], v[30:33], v[198:201], v[14:17]
	v_mfma_f32_16x16x32_bf16 v[18:21], v[202:205], v[118:121], v[86:89]
	v_mfma_f32_16x16x32_bf16 v[26:29], v[206:209], v[130:133], v[18:21]
	v_mfma_f32_16x16x32_bf16 v[18:21], v[210:213], v[118:121], v[82:85]
	v_mfma_f32_16x16x32_bf16 v[30:33], v[214:217], v[130:133], v[18:21]
	v_mfma_f32_16x16x32_bf16 v[18:21], v[202:205], v[134:137], v[70:73]
	v_mfma_f32_16x16x32_bf16 v[70:73], v[206:209], v[146:149], v[18:21]
	v_mfma_f32_16x16x32_bf16 v[18:21], v[210:213], v[134:137], v[66:69]
	v_mfma_f32_16x16x32_bf16 v[66:69], v[214:217], v[146:149], v[18:21]
	v_mfma_f32_16x16x32_bf16 v[18:21], v[202:205], v[186:189], v[46:49]
	v_mfma_f32_16x16x32_bf16 v[46:49], v[206:209], v[190:193], v[18:21]
	v_mfma_f32_16x16x32_bf16 v[18:21], v[210:213], v[186:189], v[42:45]
	v_mfma_f32_16x16x32_bf16 v[6:9], v[202:205], v[194:197], v[6:9]
	v_mfma_f32_16x16x32_bf16 v[2:5], v[210:213], v[194:197], v[2:5]
	v_mfma_f32_16x16x32_bf16 v[42:45], v[214:217], v[190:193], v[18:21]
	v_mfma_f32_16x16x32_bf16 v[6:9], v[206:209], v[198:201], v[6:9]
	v_mfma_f32_16x16x32_bf16 v[2:5], v[214:217], v[198:201], v[2:5]
	s_barrier
	s_setprio 0
	s_add_i32 s20, 0, 0x18000
	v_add_u32_e32 v86, s20, v175
	ds_read_b128 v[18:21], v86
	ds_read_b128 v[22:25], v86 offset:1024
	ds_read_b128 v[82:85], v86 offset:2048
	ds_read_b128 v[86:89], v86 offset:3072
	s_add_u32 s18, s18, 0x40000
	s_addc_u32 s19, s19, 0
	s_mov_b32 m0, s74
	v_lshl_add_u64 v[134:135], s[18:19], 0, v[162:163]
	ds_read_b128 v[118:121], v226 offset:32768
	ds_read_b128 v[130:133], v226 offset:33792
	ds_read_b128 v[186:189], v226 offset:34816
	ds_read_b128 v[190:193], v226 offset:35840
	ds_read_b128 v[194:197], v226 offset:36864
	ds_read_b128 v[198:201], v226 offset:37888
	ds_read_b128 v[202:205], v226 offset:38912
	ds_read_b128 v[206:209], v226 offset:39936
	global_load_lds_dwordx4 v[134:135], off
	v_lshl_add_u64 v[134:135], s[18:19], 0, v[166:167]
	s_mov_b32 m0, s75
	s_nop 0
	global_load_lds_dwordx4 v[134:135], off
	s_add_i32 s21, 0, 0x1c000
	v_add_u32_e32 v244, s21, v175
	ds_read_b128 v[210:213], v244
	ds_read_b128 v[214:217], v244 offset:1024
	ds_read_b128 v[218:221], v244 offset:2048
	ds_read_b128 v[234:237], v244 offset:3072
	s_waitcnt vmcnt(8)
	s_waitcnt lgkmcnt(0)
	s_setprio 1
	s_barrier
	v_mfma_f32_16x16x32_bf16 v[134:137], v[18:21], v[118:121], v[158:161]
	v_mfma_f32_16x16x32_bf16 v[158:161], v[22:25], v[130:133], v[134:137]
	v_mfma_f32_16x16x32_bf16 v[134:137], v[82:85], v[118:121], v[154:157]
	v_mfma_f32_16x16x32_bf16 v[154:157], v[86:89], v[130:133], v[134:137]
	v_mfma_f32_16x16x32_bf16 v[134:137], v[18:21], v[186:189], v[142:145]
	v_mfma_f32_16x16x32_bf16 v[142:145], v[22:25], v[190:193], v[134:137]
	v_mfma_f32_16x16x32_bf16 v[134:137], v[82:85], v[186:189], v[138:141]
	v_mfma_f32_16x16x32_bf16 v[126:129], v[18:21], v[194:197], v[126:129]
	v_mfma_f32_16x16x32_bf16 v[122:125], v[82:85], v[194:197], v[122:125]
	v_mfma_f32_16x16x32_bf16 v[110:113], v[18:21], v[202:205], v[110:113]
	v_mfma_f32_16x16x32_bf16 v[106:109], v[82:85], v[202:205], v[106:109]
	v_mfma_f32_16x16x32_bf16 v[138:141], v[86:89], v[190:193], v[134:137]
	v_mfma_f32_16x16x32_bf16 v[126:129], v[22:25], v[198:201], v[126:129]
	v_mfma_f32_16x16x32_bf16 v[122:125], v[86:89], v[198:201], v[122:125]
	v_mfma_f32_16x16x32_bf16 v[110:113], v[22:25], v[206:209], v[110:113]
	v_mfma_f32_16x16x32_bf16 v[106:109], v[86:89], v[206:209], v[106:109]
	v_mfma_f32_16x16x32_bf16 v[34:37], v[218:221], v[118:121], v[34:37]
	v_mfma_f32_16x16x32_bf16 v[134:137], v[210:213], v[118:121], v[150:153]
	v_mfma_f32_16x16x32_bf16 v[146:149], v[234:237], v[130:133], v[34:37]
	v_mfma_f32_16x16x32_bf16 v[34:37], v[210:213], v[186:189], v[38:41]
	v_mfma_f32_16x16x32_bf16 v[150:153], v[214:217], v[130:133], v[134:137]
	v_mfma_f32_16x16x32_bf16 v[134:137], v[214:217], v[190:193], v[34:37]
	v_mfma_f32_16x16x32_bf16 v[34:37], v[218:221], v[186:189], v[50:53]
	v_mfma_f32_16x16x32_bf16 v[130:133], v[234:237], v[190:193], v[34:37]
	v_mfma_f32_16x16x32_bf16 v[34:37], v[210:213], v[194:197], v[54:57]
	v_mfma_f32_16x16x32_bf16 v[118:121], v[214:217], v[198:201], v[34:37]
	v_mfma_f32_16x16x32_bf16 v[34:37], v[218:221], v[194:197], v[114:117]
	v_mfma_f32_16x16x32_bf16 v[114:117], v[234:237], v[198:201], v[34:37]
	v_mfma_f32_16x16x32_bf16 v[34:37], v[210:213], v[202:205], v[102:105]
	v_mfma_f32_16x16x32_bf16 v[102:105], v[214:217], v[206:209], v[34:37]
	v_mfma_f32_16x16x32_bf16 v[34:37], v[218:221], v[202:205], v[98:101]
	v_mfma_f32_16x16x32_bf16 v[98:101], v[234:237], v[206:209], v[34:37]
	s_barrier
	s_setprio 0
	s_add_i32 s18, s20, s71
	v_lshl_add_u64 v[248:249], v[222:223], 0, s[24:25]
	s_mov_b32 m0, s18
	s_nop 0
	global_load_lds_dwordx4 v[248:249], off
	v_lshl_add_u64 v[248:249], v[238:239], 0, s[24:25]
	s_add_i32 m0, s18, 0x2000
	s_nop 0
	global_load_lds_dwordx4 v[248:249], off
	s_mov_b32 m0, s95
	v_lshl_add_u64 v[202:203], v[240:241], 0, s[24:25]
	s_nop 2
	ds_read_b128 v[34:37], v226 offset:49152
	ds_read_b128 v[38:41], v226 offset:50176
	ds_read_b128 v[50:53], v226 offset:51200
	ds_read_b128 v[54:57], v226 offset:52224
	ds_read_b128 v[186:189], v226 offset:53248
	ds_read_b128 v[190:193], v226 offset:54272
	ds_read_b128 v[194:197], v226 offset:55296
	ds_read_b128 v[198:201], v226 offset:56320
	global_load_lds_dwordx4 v[202:203], off
	v_lshl_add_u64 v[202:203], v[242:243], 0, s[24:25]
	s_mov_b32 m0, s96
	s_nop 0
	global_load_lds_dwordx4 v[202:203], off
	s_add_u32 s18, s54, 0x40080
	s_addc_u32 s19, s55, 0
	s_add_i32 s20, s21, s71
	v_lshl_add_u64 v[250:251], s[18:19], 0, v[164:165]
	s_mov_b32 m0, s20
	s_nop 0
	global_load_lds_dwordx4 v[250:251], off
	v_lshl_add_u64 v[250:251], s[18:19], 0, v[168:169]
	s_add_i32 m0, s20, 0x2000
	s_nop 0
	global_load_lds_dwordx4 v[250:251], off
	s_waitcnt vmcnt(8)
	s_waitcnt lgkmcnt(0)
	s_setprio 1
	s_barrier
	v_mfma_f32_16x16x32_bf16 v[94:97], v[18:21], v[34:37], v[94:97]
	v_mfma_f32_16x16x32_bf16 v[78:81], v[18:21], v[50:53], v[78:81]
	v_mfma_f32_16x16x32_bf16 v[62:65], v[18:21], v[186:189], v[62:65]
	v_mfma_f32_16x16x32_bf16 v[10:13], v[18:21], v[194:197], v[10:13]
	v_mfma_f32_16x16x32_bf16 v[94:97], v[22:25], v[38:41], v[94:97]
	v_mfma_f32_16x16x32_bf16 v[90:93], v[82:85], v[34:37], v[90:93]
	v_mfma_f32_16x16x32_bf16 v[78:81], v[22:25], v[54:57], v[78:81]
	v_mfma_f32_16x16x32_bf16 v[74:77], v[82:85], v[50:53], v[74:77]
	v_mfma_f32_16x16x32_bf16 v[62:65], v[22:25], v[190:193], v[62:65]
	v_mfma_f32_16x16x32_bf16 v[58:61], v[82:85], v[186:189], v[58:61]
	v_mfma_f32_16x16x32_bf16 v[22:25], v[22:25], v[198:201], v[10:13]
	v_mfma_f32_16x16x32_bf16 v[10:13], v[82:85], v[194:197], v[14:17]
	v_mfma_f32_16x16x32_bf16 v[90:93], v[86:89], v[38:41], v[90:93]
	v_mfma_f32_16x16x32_bf16 v[74:77], v[86:89], v[54:57], v[74:77]
	v_mfma_f32_16x16x32_bf16 v[58:61], v[86:89], v[190:193], v[58:61]
	v_mfma_f32_16x16x32_bf16 v[18:21], v[86:89], v[198:201], v[10:13]
	v_mfma_f32_16x16x32_bf16 v[10:13], v[210:213], v[34:37], v[26:29]
	v_mfma_f32_16x16x32_bf16 v[86:89], v[214:217], v[38:41], v[10:13]
	v_mfma_f32_16x16x32_bf16 v[10:13], v[218:221], v[34:37], v[30:33]
	v_mfma_f32_16x16x32_bf16 v[82:85], v[234:237], v[38:41], v[10:13]
	v_mfma_f32_16x16x32_bf16 v[10:13], v[210:213], v[50:53], v[70:73]
	v_mfma_f32_16x16x32_bf16 v[70:73], v[214:217], v[54:57], v[10:13]
	v_mfma_f32_16x16x32_bf16 v[10:13], v[218:221], v[50:53], v[66:69]
	v_mfma_f32_16x16x32_bf16 v[66:69], v[234:237], v[54:57], v[10:13]
	v_mfma_f32_16x16x32_bf16 v[10:13], v[210:213], v[186:189], v[46:49]
	v_mfma_f32_16x16x32_bf16 v[46:49], v[214:217], v[190:193], v[10:13]
	v_mfma_f32_16x16x32_bf16 v[10:13], v[218:221], v[186:189], v[42:45]
	v_mfma_f32_16x16x32_bf16 v[6:9], v[210:213], v[194:197], v[6:9]
	v_mfma_f32_16x16x32_bf16 v[2:5], v[218:221], v[194:197], v[2:5]
	v_mfma_f32_16x16x32_bf16 v[42:45], v[234:237], v[190:193], v[10:13]
	v_mfma_f32_16x16x32_bf16 v[6:9], v[214:217], v[198:201], v[6:9]
	v_mfma_f32_16x16x32_bf16 v[2:5], v[234:237], v[198:201], v[2:5]
	s_barrier
	s_setprio 0
	s_add_i32 vcc_lo, vcc_lo, 2
	s_add_u32 s34, s34, 0x100
	s_addc_u32 s35, s35, 0
	s_add_u32 s56, s56, 0x100
	s_addc_u32 s57, s57, 0
	s_cmp_gt_u32 vcc_lo, 13
	s_cbranch_scc0 .LBB0_1375
	s_min_i32 s3, s4, 0x80
	s_ashr_i32 s5, s3, 3
	s_lshl_b32 s3, s2, 8
	s_mul_hi_i32 s19, s5, 0x6000
	s_mulk_i32 s5, 0x6000
	v_or_b32_e32 v186, s3, v224
	s_add_u32 s18, s77, s5
	s_addc_u32 s19, s78, s19
	v_ashrrev_i32_e32 v187, 31, v186
	v_lshl_add_u64 v[10:11], v[186:187], 2, s[18:19]
	global_load_dwordx4 v[50:53], v[10:11], off offset:16
	global_load_dwordx4 v[54:57], v[10:11], off
	global_load_dwordx4 v[26:29], v[10:11], off offset:528
	global_load_dwordx4 v[30:33], v[10:11], off offset:512
	s_add_i32 s5, s2, -2
	s_cmp_gt_u32 s5, 3
	s_cbranch_scc1 .LBB0_1378
	v_lshl_add_u64 v[14:15], v[186:187], 2, s[6:7]
	global_load_dwordx4 v[38:41], v[14:15], off offset:-2048
	global_load_dwordx4 v[34:37], v[14:15], off offset:-2032
	global_load_dwordx4 v[10:13], v[14:15], off offset:-1536
	s_nop 0
	global_load_dwordx4 v[14:17], v[14:15], off offset:-1520

.LBB0_2844:
	s_ashr_i32 s37, s36, 31
	v_cmp_lt_i64_e32 vcc, s[18:19], v[192:193]
	s_lshl_b64 s[18:19], s[36:37], 19
	s_add_u32 s38, s48, s18
	s_addc_u32 s39, s49, s19
	s_and_b64 s[18:19], vcc, exec
	s_cselect_b32 s37, s39, s45
	s_cselect_b32 s43, s38, s44
	s_ashr_i32 s35, s34, 31
	s_lshl_b64 s[18:19], s[34:35], 19
	s_add_u32 s40, s50, s18
	s_addc_u32 s41, s51, s19
	s_and_b64 s[18:19], vcc, exec
	s_cselect_b32 s35, s41, s47
	s_cselect_b32 s70, s40, s46
	s_add_u32 s44, s44, 0x40080
	s_addc_u32 s45, s45, 0
	s_add_u32 s71, s46, 0x100
	s_addc_u32 s72, s47, 0
	s_mov_b32 s73, -2
	s_waitcnt lgkmcnt(0)
	s_waitcnt vmcnt(0)
	ds_read_b128 v[98:101], v173
	ds_read_b128 v[102:105], v173 offset:1024
	ds_read_b128 v[106:109], v173 offset:2048
	ds_read_b128 v[110:113], v173 offset:3072
	s_add_u32 s18, s44, 0xfffc0080
	s_addc_u32 s19, s45, -1
	s_cmp_eq_u32 s73, 12
	s_cselect_b32 s19, s37, s19
	s_cselect_b32 s18, s43, s18
	s_cselect_b32 s47, s35, s72
	s_cselect_b32 s46, s70, s71
	v_lshl_add_u64 v[204:205], s[44:45], 0, v[188:189]
	s_add_i32 m0, s53, 0xc000
	ds_read_b128 v[146:149], v185
	ds_read_b128 v[150:153], v185 offset:1024
	ds_read_b128 v[154:157], v185 offset:2048
	ds_read_b128 v[158:161], v185 offset:3072
	ds_read_b128 v[162:165], v185 offset:4096
	ds_read_b128 v[166:169], v185 offset:5120
	ds_read_b128 v[196:199], v185 offset:6144
	ds_read_b128 v[200:203], v185 offset:7168
	global_load_lds_dwordx4 v[204:205], off
	v_lshl_add_u64 v[204:205], s[44:45], 0, v[190:191]
	s_add_i32 m0, s53, 0xe000
	s_nop 0
	global_load_lds_dwordx4 v[204:205], off
	ds_read_b128 v[204:207], v222
	ds_read_b128 v[208:211], v222 offset:1024
	ds_read_b128 v[212:215], v222 offset:2048
	ds_read_b128 v[216:219], v222 offset:3072
	s_waitcnt vmcnt(8)
	s_waitcnt lgkmcnt(0)
	s_setprio 1
	s_barrier
	v_mfma_f32_16x16x32_bf16 v[142:145], v[98:101], v[146:149], 0
	v_mfma_f32_16x16x32_bf16 v[138:141], v[106:109], v[146:149], 0
	v_mfma_f32_16x16x32_bf16 v[126:129], v[98:101], v[154:157], 0
	v_mfma_f32_16x16x32_bf16 v[122:125], v[106:109], v[154:157], 0
	v_mfma_f32_16x16x32_bf16 v[94:97], v[98:101], v[162:165], 0
	v_mfma_f32_16x16x32_bf16 v[90:93], v[106:109], v[162:165], 0
	v_mfma_f32_16x16x32_bf16 v[78:81], v[98:101], v[196:199], 0
	v_mfma_f32_16x16x32_bf16 v[74:77], v[106:109], v[196:199], 0
	v_mfma_f32_16x16x32_bf16 v[142:145], v[102:105], v[150:153], v[142:145]
	v_mfma_f32_16x16x32_bf16 v[138:141], v[110:113], v[150:153], v[138:141]
	v_mfma_f32_16x16x32_bf16 v[126:129], v[102:105], v[158:161], v[126:129]
	v_mfma_f32_16x16x32_bf16 v[122:125], v[110:113], v[158:161], v[122:125]
	v_mfma_f32_16x16x32_bf16 v[94:97], v[102:105], v[166:169], v[94:97]
	v_mfma_f32_16x16x32_bf16 v[90:93], v[110:113], v[166:169], v[90:93]
	v_mfma_f32_16x16x32_bf16 v[78:81], v[102:105], v[200:203], v[78:81]
	v_mfma_f32_16x16x32_bf16 v[74:77], v[110:113], v[200:203], v[74:77]
	v_mfma_f32_16x16x32_bf16 v[134:137], v[204:207], v[146:149], 0
	v_mfma_f32_16x16x32_bf16 v[130:133], v[212:215], v[146:149], 0
	v_mfma_f32_16x16x32_bf16 v[118:121], v[204:207], v[154:157], 0
	v_mfma_f32_16x16x32_bf16 v[114:117], v[212:215], v[154:157], 0
	v_mfma_f32_16x16x32_bf16 v[86:89], v[204:207], v[162:165], 0
	v_mfma_f32_16x16x32_bf16 v[82:85], v[212:215], v[162:165], 0
	v_mfma_f32_16x16x32_bf16 v[70:73], v[204:207], v[196:199], 0
	v_mfma_f32_16x16x32_bf16 v[66:69], v[212:215], v[196:199], 0
	v_mfma_f32_16x16x32_bf16 v[134:137], v[208:211], v[150:153], v[134:137]
	v_mfma_f32_16x16x32_bf16 v[130:133], v[216:219], v[150:153], v[130:133]
	v_mfma_f32_16x16x32_bf16 v[118:121], v[208:211], v[158:161], v[118:121]
	v_mfma_f32_16x16x32_bf16 v[114:117], v[216:219], v[158:161], v[114:117]
	v_mfma_f32_16x16x32_bf16 v[86:89], v[208:211], v[166:169], v[86:89]
	v_mfma_f32_16x16x32_bf16 v[82:85], v[216:219], v[166:169], v[82:85]
	v_mfma_f32_16x16x32_bf16 v[70:73], v[208:211], v[200:203], v[70:73]
	v_mfma_f32_16x16x32_bf16 v[66:69], v[216:219], v[200:203], v[66:69]
	s_barrier
	s_setprio 0
	s_add_i32 s20, s65, s52
	v_lshl_add_u64 v[220:221], s[46:47], 0, v[176:177]
	s_mov_b32 m0, s20
	s_nop 0
	global_load_lds_dwordx4 v[220:221], off
	v_lshl_add_u64 v[224:225], s[46:47], 0, v[180:181]
	s_add_i32 m0, s20, 0x2000
	s_nop 0
	global_load_lds_dwordx4 v[224:225], off
	s_mov_b32 m0, s53
	v_lshl_add_u64 v[226:227], s[18:19], 0, v[174:175]
	ds_read_b128 v[146:149], v185 offset:16384
	ds_read_b128 v[150:153], v185 offset:17408
	ds_read_b128 v[154:157], v185 offset:18432
	ds_read_b128 v[158:161], v185 offset:19456
	ds_read_b128 v[162:165], v185 offset:20480
	ds_read_b128 v[166:169], v185 offset:21504
	ds_read_b128 v[196:199], v185 offset:22528
	ds_read_b128 v[200:203], v185 offset:23552
	global_load_lds_dwordx4 v[226:227], off
	v_lshl_add_u64 v[228:229], s[18:19], 0, v[178:179]
	s_mov_b32 m0, s54
	s_nop 0
	global_load_lds_dwordx4 v[228:229], off
	s_add_u32 s20, s46, 0x40000
	s_addc_u32 s21, s47, 0
	s_add_i32 s74, s66, s52
	v_lshl_add_u64 v[246:247], s[20:21], 0, v[176:177]
	s_mov_b32 m0, s74
	s_nop 0
	global_load_lds_dwordx4 v[246:247], off
	v_lshl_add_u64 v[246:247], s[20:21], 0, v[180:181]
	s_add_i32 m0, s74, 0x2000
	s_nop 0
	global_load_lds_dwordx4 v[246:247], off
	s_waitcnt vmcnt(8)
	s_waitcnt lgkmcnt(0)
	s_setprio 1
	s_barrier
	v_mfma_f32_16x16x32_bf16 v[62:65], v[98:101], v[146:149], 0
	v_mfma_f32_16x16x32_bf16 v[58:61], v[106:109], v[146:149], 0
	v_mfma_f32_16x16x32_bf16 v[46:49], v[98:101], v[154:157], 0
	v_mfma_f32_16x16x32_bf16 v[42:45], v[106:109], v[154:157], 0
	v_mfma_f32_16x16x32_bf16 v[30:33], v[98:101], v[162:165], 0
	v_mfma_f32_16x16x32_bf16 v[26:29], v[106:109], v[162:165], 0
	v_mfma_f32_16x16x32_bf16 v[14:17], v[98:101], v[196:199], 0
	v_mfma_f32_16x16x32_bf16 v[10:13], v[106:109], v[196:199], 0
	v_mfma_f32_16x16x32_bf16 v[62:65], v[102:105], v[150:153], v[62:65]
	v_mfma_f32_16x16x32_bf16 v[58:61], v[110:113], v[150:153], v[58:61]
	v_mfma_f32_16x16x32_bf16 v[46:49], v[102:105], v[158:161], v[46:49]
	v_mfma_f32_16x16x32_bf16 v[42:45], v[110:113], v[158:161], v[42:45]
	v_mfma_f32_16x16x32_bf16 v[30:33], v[102:105], v[166:169], v[30:33]
	v_mfma_f32_16x16x32_bf16 v[26:29], v[110:113], v[166:169], v[26:29]
	v_mfma_f32_16x16x32_bf16 v[14:17], v[102:105], v[200:203], v[14:17]
	v_mfma_f32_16x16x32_bf16 v[10:13], v[110:113], v[200:203], v[10:13]
	v_mfma_f32_16x16x32_bf16 v[54:57], v[204:207], v[146:149], 0
	v_mfma_f32_16x16x32_bf16 v[50:53], v[212:215], v[146:149], 0
	v_mfma_f32_16x16x32_bf16 v[38:41], v[204:207], v[154:157], 0
	v_mfma_f32_16x16x32_bf16 v[34:37], v[212:215], v[154:157], 0
	v_mfma_f32_16x16x32_bf16 v[22:25], v[204:207], v[162:165], 0
	v_mfma_f32_16x16x32_bf16 v[18:21], v[212:215], v[162:165], 0
	v_mfma_f32_16x16x32_bf16 v[6:9], v[204:207], v[196:199], 0
	v_mfma_f32_16x16x32_bf16 v[2:5], v[212:215], v[196:199], 0
	v_mfma_f32_16x16x32_bf16 v[54:57], v[208:211], v[150:153], v[54:57]
	v_mfma_f32_16x16x32_bf16 v[50:53], v[216:219], v[150:153], v[50:53]
	v_mfma_f32_16x16x32_bf16 v[38:41], v[208:211], v[158:161], v[38:41]
	v_mfma_f32_16x16x32_bf16 v[34:37], v[216:219], v[158:161], v[34:37]
	v_mfma_f32_16x16x32_bf16 v[22:25], v[208:211], v[166:169], v[22:25]
	v_mfma_f32_16x16x32_bf16 v[18:21], v[216:219], v[166:169], v[18:21]
	v_mfma_f32_16x16x32_bf16 v[6:9], v[208:211], v[200:203], v[6:9]
	v_mfma_f32_16x16x32_bf16 v[2:5], v[216:219], v[200:203], v[2:5]
	s_barrier
	s_setprio 0
	s_add_i32 s20, 0, 0x18000
	v_add_u32_e32 v110, s20, v171
	ds_read_b128 v[98:101], v110
	ds_read_b128 v[102:105], v110 offset:1024
	ds_read_b128 v[106:109], v110 offset:2048
	ds_read_b128 v[110:113], v110 offset:3072
	s_add_u32 s18, s18, 0x40000
	s_addc_u32 s19, s19, 0
	s_mov_b32 m0, s55
	v_lshl_add_u64 v[204:205], s[18:19], 0, v[174:175]
	ds_read_b128 v[146:149], v185 offset:32768
	ds_read_b128 v[150:153], v185 offset:33792
	ds_read_b128 v[154:157], v185 offset:34816
	ds_read_b128 v[158:161], v185 offset:35840
	ds_read_b128 v[162:165], v185 offset:36864
	ds_read_b128 v[166:169], v185 offset:37888
	ds_read_b128 v[196:199], v185 offset:38912
	ds_read_b128 v[200:203], v185 offset:39936
	global_load_lds_dwordx4 v[204:205], off
	v_lshl_add_u64 v[204:205], s[18:19], 0, v[178:179]
	s_mov_b32 m0, s56
	s_nop 0
	global_load_lds_dwordx4 v[204:205], off
	s_add_i32 s21, 0, 0x1c000
	v_add_u32_e32 v182, s21, v171
	ds_read_b128 v[204:207], v182
	ds_read_b128 v[208:211], v182 offset:1024
	ds_read_b128 v[212:215], v182 offset:2048
	ds_read_b128 v[216:219], v182 offset:3072
	s_waitcnt vmcnt(8)
	s_waitcnt lgkmcnt(0)
	s_setprio 1
	s_barrier
	v_mfma_f32_16x16x32_bf16 v[142:145], v[98:101], v[146:149], v[142:145]
	v_mfma_f32_16x16x32_bf16 v[138:141], v[106:109], v[146:149], v[138:141]
	v_mfma_f32_16x16x32_bf16 v[126:129], v[98:101], v[154:157], v[126:129]
	v_mfma_f32_16x16x32_bf16 v[122:125], v[106:109], v[154:157], v[122:125]
	v_mfma_f32_16x16x32_bf16 v[94:97], v[98:101], v[162:165], v[94:97]
	v_mfma_f32_16x16x32_bf16 v[90:93], v[106:109], v[162:165], v[90:93]
	v_mfma_f32_16x16x32_bf16 v[78:81], v[98:101], v[196:199], v[78:81]
	v_mfma_f32_16x16x32_bf16 v[74:77], v[106:109], v[196:199], v[74:77]
	v_mfma_f32_16x16x32_bf16 v[142:145], v[102:105], v[150:153], v[142:145]
	v_mfma_f32_16x16x32_bf16 v[138:141], v[110:113], v[150:153], v[138:141]
	v_mfma_f32_16x16x32_bf16 v[126:129], v[102:105], v[158:161], v[126:129]
	v_mfma_f32_16x16x32_bf16 v[122:125], v[110:113], v[158:161], v[122:125]
	v_mfma_f32_16x16x32_bf16 v[94:97], v[102:105], v[166:169], v[94:97]
	v_mfma_f32_16x16x32_bf16 v[90:93], v[110:113], v[166:169], v[90:93]
	v_mfma_f32_16x16x32_bf16 v[78:81], v[102:105], v[200:203], v[78:81]
	v_mfma_f32_16x16x32_bf16 v[74:77], v[110:113], v[200:203], v[74:77]
	v_mfma_f32_16x16x32_bf16 v[134:137], v[204:207], v[146:149], v[134:137]
	v_mfma_f32_16x16x32_bf16 v[130:133], v[212:215], v[146:149], v[130:133]
	v_mfma_f32_16x16x32_bf16 v[118:121], v[204:207], v[154:157], v[118:121]
	v_mfma_f32_16x16x32_bf16 v[114:117], v[212:215], v[154:157], v[114:117]
	v_mfma_f32_16x16x32_bf16 v[86:89], v[204:207], v[162:165], v[86:89]
	v_mfma_f32_16x16x32_bf16 v[82:85], v[212:215], v[162:165], v[82:85]
	v_mfma_f32_16x16x32_bf16 v[70:73], v[204:207], v[196:199], v[70:73]
	v_mfma_f32_16x16x32_bf16 v[66:69], v[212:215], v[196:199], v[66:69]
	v_mfma_f32_16x16x32_bf16 v[134:137], v[208:211], v[150:153], v[134:137]
	v_mfma_f32_16x16x32_bf16 v[130:133], v[216:219], v[150:153], v[130:133]
	v_mfma_f32_16x16x32_bf16 v[118:121], v[208:211], v[158:161], v[118:121]
	v_mfma_f32_16x16x32_bf16 v[114:117], v[216:219], v[158:161], v[114:117]
	v_mfma_f32_16x16x32_bf16 v[86:89], v[208:211], v[166:169], v[86:89]
	v_mfma_f32_16x16x32_bf16 v[82:85], v[216:219], v[166:169], v[82:85]
	v_mfma_f32_16x16x32_bf16 v[70:73], v[208:211], v[200:203], v[70:73]
	v_mfma_f32_16x16x32_bf16 v[66:69], v[216:219], v[200:203], v[66:69]
	s_barrier
	s_setprio 0
	s_add_i32 s18, s20, s52
	v_lshl_add_u64 v[220:221], v[220:221], 0, s[10:11]
	s_mov_b32 m0, s18
	s_nop 0
	global_load_lds_dwordx4 v[220:221], off
	v_lshl_add_u64 v[220:221], v[224:225], 0, s[10:11]
	s_add_i32 m0, s18, 0x2000
	s_nop 0
	global_load_lds_dwordx4 v[220:221], off
	s_mov_b32 m0, s62
	v_lshl_add_u64 v[220:221], v[226:227], 0, s[10:11]
	ds_read_b128 v[146:149], v185 offset:49152
	ds_read_b128 v[150:153], v185 offset:50176
	ds_read_b128 v[154:157], v185 offset:51200
	ds_read_b128 v[158:161], v185 offset:52224
	ds_read_b128 v[162:165], v185 offset:53248
	ds_read_b128 v[166:169], v185 offset:54272
	ds_read_b128 v[196:199], v185 offset:55296
	ds_read_b128 v[200:203], v185 offset:56320
	global_load_lds_dwordx4 v[220:221], off
	v_lshl_add_u64 v[220:221], v[228:229], 0, s[10:11]
	s_mov_b32 m0, s63
	s_nop 0
	global_load_lds_dwordx4 v[220:221], off
	s_add_u32 s18, s46, 0x40080
	s_addc_u32 s19, s47, 0
	s_add_i32 s20, s21, s52
	v_lshl_add_u64 v[248:249], s[18:19], 0, v[176:177]
	s_mov_b32 m0, s20
	s_nop 0
	global_load_lds_dwordx4 v[248:249], off
	v_lshl_add_u64 v[248:249], s[18:19], 0, v[180:181]
	s_add_i32 m0, s20, 0x2000
	s_nop 0
	global_load_lds_dwordx4 v[248:249], off
	s_waitcnt vmcnt(8)
	s_waitcnt lgkmcnt(0)
	s_setprio 1
	s_barrier
	v_mfma_f32_16x16x32_bf16 v[62:65], v[98:101], v[146:149], v[62:65]
	v_mfma_f32_16x16x32_bf16 v[58:61], v[106:109], v[146:149], v[58:61]
	v_mfma_f32_16x16x32_bf16 v[46:49], v[98:101], v[154:157], v[46:49]
	v_mfma_f32_16x16x32_bf16 v[42:45], v[106:109], v[154:157], v[42:45]
	v_mfma_f32_16x16x32_bf16 v[30:33], v[98:101], v[162:165], v[30:33]
	v_mfma_f32_16x16x32_bf16 v[26:29], v[106:109], v[162:165], v[26:29]
	v_mfma_f32_16x16x32_bf16 v[14:17], v[98:101], v[196:199], v[14:17]
	v_mfma_f32_16x16x32_bf16 v[10:13], v[106:109], v[196:199], v[10:13]
	v_mfma_f32_16x16x32_bf16 v[62:65], v[102:105], v[150:153], v[62:65]
	v_mfma_f32_16x16x32_bf16 v[58:61], v[110:113], v[150:153], v[58:61]
	v_mfma_f32_16x16x32_bf16 v[46:49], v[102:105], v[158:161], v[46:49]
	v_mfma_f32_16x16x32_bf16 v[42:45], v[110:113], v[158:161], v[42:45]
	v_mfma_f32_16x16x32_bf16 v[30:33], v[102:105], v[166:169], v[30:33]
	v_mfma_f32_16x16x32_bf16 v[26:29], v[110:113], v[166:169], v[26:29]
	v_mfma_f32_16x16x32_bf16 v[14:17], v[102:105], v[200:203], v[14:17]
	v_mfma_f32_16x16x32_bf16 v[10:13], v[110:113], v[200:203], v[10:13]
	v_mfma_f32_16x16x32_bf16 v[54:57], v[204:207], v[146:149], v[54:57]
	v_mfma_f32_16x16x32_bf16 v[50:53], v[212:215], v[146:149], v[50:53]
	v_mfma_f32_16x16x32_bf16 v[38:41], v[204:207], v[154:157], v[38:41]
	v_mfma_f32_16x16x32_bf16 v[34:37], v[212:215], v[154:157], v[34:37]
	v_mfma_f32_16x16x32_bf16 v[22:25], v[204:207], v[162:165], v[22:25]
	v_mfma_f32_16x16x32_bf16 v[18:21], v[212:215], v[162:165], v[18:21]
	v_mfma_f32_16x16x32_bf16 v[6:9], v[204:207], v[196:199], v[6:9]
	v_mfma_f32_16x16x32_bf16 v[2:5], v[212:215], v[196:199], v[2:5]
	v_mfma_f32_16x16x32_bf16 v[54:57], v[208:211], v[150:153], v[54:57]
	v_mfma_f32_16x16x32_bf16 v[50:53], v[216:219], v[150:153], v[50:53]
	v_mfma_f32_16x16x32_bf16 v[38:41], v[208:211], v[158:161], v[38:41]
	v_mfma_f32_16x16x32_bf16 v[34:37], v[216:219], v[158:161], v[34:37]
	v_mfma_f32_16x16x32_bf16 v[22:25], v[208:211], v[166:169], v[22:25]
	v_mfma_f32_16x16x32_bf16 v[18:21], v[216:219], v[166:169], v[18:21]
	v_mfma_f32_16x16x32_bf16 v[6:9], v[208:211], v[200:203], v[6:9]
	v_mfma_f32_16x16x32_bf16 v[2:5], v[216:219], v[200:203], v[2:5]
	s_barrier
	s_setprio 0
	s_add_i32 s73, s73, 2
	s_add_u32 s44, s44, 0x100
	s_addc_u32 s45, s45, 0
	s_add_u32 s71, s71, 0x100
	s_addc_u32 s72, s72, 0
	s_cmp_gt_u32 s73, 13
.LBB0_2845:
	ds_read_b128 v[98:101], v173
	ds_read_b128 v[102:105], v173 offset:1024
	ds_read_b128 v[106:109], v173 offset:2048
	ds_read_b128 v[110:113], v173 offset:3072
	s_add_u32 s18, s44, 0xfffc0080
	s_addc_u32 s19, s45, -1
	s_cmp_eq_u32 s73, 12
	s_cselect_b32 s19, s37, s19
	s_cselect_b32 s18, s43, s18
	s_cselect_b32 s47, s35, s72
	s_cselect_b32 s46, s70, s71
	v_lshl_add_u64 v[204:205], s[44:45], 0, v[188:189]
	s_add_i32 m0, s53, 0xc000
	ds_read_b128 v[146:149], v185
	ds_read_b128 v[150:153], v185 offset:1024
	ds_read_b128 v[154:157], v185 offset:2048
	ds_read_b128 v[158:161], v185 offset:3072
	ds_read_b128 v[162:165], v185 offset:4096
	ds_read_b128 v[166:169], v185 offset:5120
	ds_read_b128 v[196:199], v185 offset:6144
	ds_read_b128 v[200:203], v185 offset:7168
	global_load_lds_dwordx4 v[204:205], off
	v_lshl_add_u64 v[204:205], s[44:45], 0, v[190:191]
	s_add_i32 m0, s53, 0xe000
	s_nop 0
	global_load_lds_dwordx4 v[204:205], off
	ds_read_b128 v[204:207], v222
	ds_read_b128 v[208:211], v222 offset:1024
	ds_read_b128 v[212:215], v222 offset:2048
	ds_read_b128 v[216:219], v222 offset:3072
	s_waitcnt vmcnt(8)
	s_waitcnt lgkmcnt(0)
	s_setprio 1
	s_barrier
	v_mfma_f32_16x16x32_bf16 v[142:145], v[98:101], v[146:149], v[142:145]
	v_mfma_f32_16x16x32_bf16 v[138:141], v[106:109], v[146:149], v[138:141]
	v_mfma_f32_16x16x32_bf16 v[126:129], v[98:101], v[154:157], v[126:129]
	v_mfma_f32_16x16x32_bf16 v[122:125], v[106:109], v[154:157], v[122:125]
	v_mfma_f32_16x16x32_bf16 v[94:97], v[98:101], v[162:165], v[94:97]
	v_mfma_f32_16x16x32_bf16 v[90:93], v[106:109], v[162:165], v[90:93]
	v_mfma_f32_16x16x32_bf16 v[78:81], v[98:101], v[196:199], v[78:81]
	v_mfma_f32_16x16x32_bf16 v[74:77], v[106:109], v[196:199], v[74:77]
	v_mfma_f32_16x16x32_bf16 v[142:145], v[102:105], v[150:153], v[142:145]
	v_mfma_f32_16x16x32_bf16 v[138:141], v[110:113], v[150:153], v[138:141]
	v_mfma_f32_16x16x32_bf16 v[126:129], v[102:105], v[158:161], v[126:129]
	v_mfma_f32_16x16x32_bf16 v[122:125], v[110:113], v[158:161], v[122:125]
	v_mfma_f32_16x16x32_bf16 v[94:97], v[102:105], v[166:169], v[94:97]
	v_mfma_f32_16x16x32_bf16 v[90:93], v[110:113], v[166:169], v[90:93]
	v_mfma_f32_16x16x32_bf16 v[78:81], v[102:105], v[200:203], v[78:81]
	v_mfma_f32_16x16x32_bf16 v[74:77], v[110:113], v[200:203], v[74:77]
	v_mfma_f32_16x16x32_bf16 v[134:137], v[204:207], v[146:149], v[134:137]
	v_mfma_f32_16x16x32_bf16 v[130:133], v[212:215], v[146:149], v[130:133]
	v_mfma_f32_16x16x32_bf16 v[118:121], v[204:207], v[154:157], v[118:121]
	v_mfma_f32_16x16x32_bf16 v[114:117], v[212:215], v[154:157], v[114:117]
	v_mfma_f32_16x16x32_bf16 v[86:89], v[204:207], v[162:165], v[86:89]
	v_mfma_f32_16x16x32_bf16 v[82:85], v[212:215], v[162:165], v[82:85]
	v_mfma_f32_16x16x32_bf16 v[70:73], v[204:207], v[196:199], v[70:73]
	v_mfma_f32_16x16x32_bf16 v[66:69], v[212:215], v[196:199], v[66:69]
	v_mfma_f32_16x16x32_bf16 v[134:137], v[208:211], v[150:153], v[134:137]
	v_mfma_f32_16x16x32_bf16 v[130:133], v[216:219], v[150:153], v[130:133]
	v_mfma_f32_16x16x32_bf16 v[118:121], v[208:211], v[158:161], v[118:121]
	v_mfma_f32_16x16x32_bf16 v[114:117], v[216:219], v[158:161], v[114:117]
	v_mfma_f32_16x16x32_bf16 v[86:89], v[208:211], v[166:169], v[86:89]
	v_mfma_f32_16x16x32_bf16 v[82:85], v[216:219], v[166:169], v[82:85]
	v_mfma_f32_16x16x32_bf16 v[70:73], v[208:211], v[200:203], v[70:73]
	v_mfma_f32_16x16x32_bf16 v[66:69], v[216:219], v[200:203], v[66:69]
	s_barrier
	s_setprio 0
	s_add_i32 s20, s65, s52
	v_lshl_add_u64 v[220:221], s[46:47], 0, v[176:177]
	s_mov_b32 m0, s20
	s_nop 0
	global_load_lds_dwordx4 v[220:221], off
	v_lshl_add_u64 v[224:225], s[46:47], 0, v[180:181]
	s_add_i32 m0, s20, 0x2000
	s_nop 0
	global_load_lds_dwordx4 v[224:225], off
	s_mov_b32 m0, s53
	v_lshl_add_u64 v[226:227], s[18:19], 0, v[174:175]
	ds_read_b128 v[146:149], v185 offset:16384
	ds_read_b128 v[150:153], v185 offset:17408
	ds_read_b128 v[154:157], v185 offset:18432
	ds_read_b128 v[158:161], v185 offset:19456
	ds_read_b128 v[162:165], v185 offset:20480
	ds_read_b128 v[166:169], v185 offset:21504
	ds_read_b128 v[196:199], v185 offset:22528
	ds_read_b128 v[200:203], v185 offset:23552
	global_load_lds_dwordx4 v[226:227], off
	v_lshl_add_u64 v[228:229], s[18:19], 0, v[178:179]
	s_mov_b32 m0, s54
	s_nop 0
	global_load_lds_dwordx4 v[228:229], off
	s_add_u32 s20, s46, 0x40000
	s_addc_u32 s21, s47, 0
	s_add_i32 s74, s66, s52
	v_lshl_add_u64 v[246:247], s[20:21], 0, v[176:177]
	s_mov_b32 m0, s74
	s_nop 0
	global_load_lds_dwordx4 v[246:247], off
	v_lshl_add_u64 v[246:247], s[20:21], 0, v[180:181]
	s_add_i32 m0, s74, 0x2000
	s_nop 0
	global_load_lds_dwordx4 v[246:247], off
	s_waitcnt vmcnt(8)
	s_waitcnt lgkmcnt(0)
	s_setprio 1
	s_barrier
	v_mfma_f32_16x16x32_bf16 v[62:65], v[98:101], v[146:149], v[62:65]
	v_mfma_f32_16x16x32_bf16 v[58:61], v[106:109], v[146:149], v[58:61]
	v_mfma_f32_16x16x32_bf16 v[46:49], v[98:101], v[154:157], v[46:49]
	v_mfma_f32_16x16x32_bf16 v[42:45], v[106:109], v[154:157], v[42:45]
	v_mfma_f32_16x16x32_bf16 v[30:33], v[98:101], v[162:165], v[30:33]
	v_mfma_f32_16x16x32_bf16 v[26:29], v[106:109], v[162:165], v[26:29]
	v_mfma_f32_16x16x32_bf16 v[14:17], v[98:101], v[196:199], v[14:17]
	v_mfma_f32_16x16x32_bf16 v[10:13], v[106:109], v[196:199], v[10:13]
	v_mfma_f32_16x16x32_bf16 v[62:65], v[102:105], v[150:153], v[62:65]
	v_mfma_f32_16x16x32_bf16 v[58:61], v[110:113], v[150:153], v[58:61]
	v_mfma_f32_16x16x32_bf16 v[46:49], v[102:105], v[158:161], v[46:49]
	v_mfma_f32_16x16x32_bf16 v[42:45], v[110:113], v[158:161], v[42:45]
	v_mfma_f32_16x16x32_bf16 v[30:33], v[102:105], v[166:169], v[30:33]
	v_mfma_f32_16x16x32_bf16 v[26:29], v[110:113], v[166:169], v[26:29]
	v_mfma_f32_16x16x32_bf16 v[14:17], v[102:105], v[200:203], v[14:17]
	v_mfma_f32_16x16x32_bf16 v[10:13], v[110:113], v[200:203], v[10:13]
	v_mfma_f32_16x16x32_bf16 v[54:57], v[204:207], v[146:149], v[54:57]
	v_mfma_f32_16x16x32_bf16 v[50:53], v[212:215], v[146:149], v[50:53]
	v_mfma_f32_16x16x32_bf16 v[38:41], v[204:207], v[154:157], v[38:41]
	v_mfma_f32_16x16x32_bf16 v[34:37], v[212:215], v[154:157], v[34:37]
	v_mfma_f32_16x16x32_bf16 v[22:25], v[204:207], v[162:165], v[22:25]
	v_mfma_f32_16x16x32_bf16 v[18:21], v[212:215], v[162:165], v[18:21]
	v_mfma_f32_16x16x32_bf16 v[6:9], v[204:207], v[196:199], v[6:9]
	v_mfma_f32_16x16x32_bf16 v[2:5], v[212:215], v[196:199], v[2:5]
	v_mfma_f32_16x16x32_bf16 v[54:57], v[208:211], v[150:153], v[54:57]
	v_mfma_f32_16x16x32_bf16 v[50:53], v[216:219], v[150:153], v[50:53]
	v_mfma_f32_16x16x32_bf16 v[38:41], v[208:211], v[158:161], v[38:41]
	v_mfma_f32_16x16x32_bf16 v[34:37], v[216:219], v[158:161], v[34:37]
	v_mfma_f32_16x16x32_bf16 v[22:25], v[208:211], v[166:169], v[22:25]
	v_mfma_f32_16x16x32_bf16 v[18:21], v[216:219], v[166:169], v[18:21]
	v_mfma_f32_16x16x32_bf16 v[6:9], v[208:211], v[200:203], v[6:9]
	v_mfma_f32_16x16x32_bf16 v[2:5], v[216:219], v[200:203], v[2:5]
	s_barrier
	s_setprio 0
	s_add_i32 s20, 0, 0x18000
	v_add_u32_e32 v110, s20, v171
	ds_read_b128 v[98:101], v110
	ds_read_b128 v[102:105], v110 offset:1024
	ds_read_b128 v[106:109], v110 offset:2048
	ds_read_b128 v[110:113], v110 offset:3072
	s_add_u32 s18, s18, 0x40000
	s_addc_u32 s19, s19, 0
	s_mov_b32 m0, s55
	v_lshl_add_u64 v[204:205], s[18:19], 0, v[174:175]
	ds_read_b128 v[146:149], v185 offset:32768
	ds_read_b128 v[150:153], v185 offset:33792
	ds_read_b128 v[154:157], v185 offset:34816
	ds_read_b128 v[158:161], v185 offset:35840
	ds_read_b128 v[162:165], v185 offset:36864
	ds_read_b128 v[166:169], v185 offset:37888
	ds_read_b128 v[196:199], v185 offset:38912
	ds_read_b128 v[200:203], v185 offset:39936
	global_load_lds_dwordx4 v[204:205], off
	v_lshl_add_u64 v[204:205], s[18:19], 0, v[178:179]
	s_mov_b32 m0, s56
	s_nop 0
	global_load_lds_dwordx4 v[204:205], off
	s_add_i32 s21, 0, 0x1c000
	v_add_u32_e32 v182, s21, v171
	ds_read_b128 v[204:207], v182
	ds_read_b128 v[208:211], v182 offset:1024
	ds_read_b128 v[212:215], v182 offset:2048
	ds_read_b128 v[216:219], v182 offset:3072
	s_waitcnt vmcnt(8)
	s_waitcnt lgkmcnt(0)
	s_setprio 1
	s_barrier
	v_mfma_f32_16x16x32_bf16 v[142:145], v[98:101], v[146:149], v[142:145]
	v_mfma_f32_16x16x32_bf16 v[138:141], v[106:109], v[146:149], v[138:141]
	v_mfma_f32_16x16x32_bf16 v[126:129], v[98:101], v[154:157], v[126:129]
	v_mfma_f32_16x16x32_bf16 v[122:125], v[106:109], v[154:157], v[122:125]
	v_mfma_f32_16x16x32_bf16 v[94:97], v[98:101], v[162:165], v[94:97]
	v_mfma_f32_16x16x32_bf16 v[90:93], v[106:109], v[162:165], v[90:93]
	v_mfma_f32_16x16x32_bf16 v[78:81], v[98:101], v[196:199], v[78:81]
	v_mfma_f32_16x16x32_bf16 v[74:77], v[106:109], v[196:199], v[74:77]
	v_mfma_f32_16x16x32_bf16 v[142:145], v[102:105], v[150:153], v[142:145]
	v_mfma_f32_16x16x32_bf16 v[138:141], v[110:113], v[150:153], v[138:141]
	v_mfma_f32_16x16x32_bf16 v[126:129], v[102:105], v[158:161], v[126:129]
	v_mfma_f32_16x16x32_bf16 v[122:125], v[110:113], v[158:161], v[122:125]
	v_mfma_f32_16x16x32_bf16 v[94:97], v[102:105], v[166:169], v[94:97]
	v_mfma_f32_16x16x32_bf16 v[90:93], v[110:113], v[166:169], v[90:93]
	v_mfma_f32_16x16x32_bf16 v[78:81], v[102:105], v[200:203], v[78:81]
	v_mfma_f32_16x16x32_bf16 v[74:77], v[110:113], v[200:203], v[74:77]
	v_mfma_f32_16x16x32_bf16 v[134:137], v[204:207], v[146:149], v[134:137]
	v_mfma_f32_16x16x32_bf16 v[130:133], v[212:215], v[146:149], v[130:133]
	v_mfma_f32_16x16x32_bf16 v[118:121], v[204:207], v[154:157], v[118:121]
	v_mfma_f32_16x16x32_bf16 v[114:117], v[212:215], v[154:157], v[114:117]
	v_mfma_f32_16x16x32_bf16 v[86:89], v[204:207], v[162:165], v[86:89]
	v_mfma_f32_16x16x32_bf16 v[82:85], v[212:215], v[162:165], v[82:85]
	v_mfma_f32_16x16x32_bf16 v[70:73], v[204:207], v[196:199], v[70:73]
	v_mfma_f32_16x16x32_bf16 v[66:69], v[212:215], v[196:199], v[66:69]
	v_mfma_f32_16x16x32_bf16 v[134:137], v[208:211], v[150:153], v[134:137]
	v_mfma_f32_16x16x32_bf16 v[130:133], v[216:219], v[150:153], v[130:133]
	v_mfma_f32_16x16x32_bf16 v[118:121], v[208:211], v[158:161], v[118:121]
	v_mfma_f32_16x16x32_bf16 v[114:117], v[216:219], v[158:161], v[114:117]
	v_mfma_f32_16x16x32_bf16 v[86:89], v[208:211], v[166:169], v[86:89]
	v_mfma_f32_16x16x32_bf16 v[82:85], v[216:219], v[166:169], v[82:85]
	v_mfma_f32_16x16x32_bf16 v[70:73], v[208:211], v[200:203], v[70:73]
	v_mfma_f32_16x16x32_bf16 v[66:69], v[216:219], v[200:203], v[66:69]
	s_barrier
	s_setprio 0
	s_add_i32 s18, s20, s52
	v_lshl_add_u64 v[220:221], v[220:221], 0, s[10:11]
	s_mov_b32 m0, s18
	s_nop 0
	global_load_lds_dwordx4 v[220:221], off
	v_lshl_add_u64 v[220:221], v[224:225], 0, s[10:11]
	s_add_i32 m0, s18, 0x2000
	s_nop 0
	global_load_lds_dwordx4 v[220:221], off
	s_mov_b32 m0, s62
	v_lshl_add_u64 v[220:221], v[226:227], 0, s[10:11]
	ds_read_b128 v[146:149], v185 offset:49152
	ds_read_b128 v[150:153], v185 offset:50176
	ds_read_b128 v[154:157], v185 offset:51200
	ds_read_b128 v[158:161], v185 offset:52224
	ds_read_b128 v[162:165], v185 offset:53248
	ds_read_b128 v[166:169], v185 offset:54272
	ds_read_b128 v[196:199], v185 offset:55296
	ds_read_b128 v[200:203], v185 offset:56320
	global_load_lds_dwordx4 v[220:221], off
	v_lshl_add_u64 v[220:221], v[228:229], 0, s[10:11]
	s_mov_b32 m0, s63
	s_nop 0
	global_load_lds_dwordx4 v[220:221], off
	s_add_u32 s18, s46, 0x40080
	s_addc_u32 s19, s47, 0
	s_add_i32 s20, s21, s52
	v_lshl_add_u64 v[248:249], s[18:19], 0, v[176:177]
	s_mov_b32 m0, s20
	s_nop 0
	global_load_lds_dwordx4 v[248:249], off
	v_lshl_add_u64 v[248:249], s[18:19], 0, v[180:181]
	s_add_i32 m0, s20, 0x2000
	s_nop 0
	global_load_lds_dwordx4 v[248:249], off
	s_waitcnt vmcnt(8)
	s_waitcnt lgkmcnt(0)
	s_setprio 1
	s_barrier
	v_mfma_f32_16x16x32_bf16 v[62:65], v[98:101], v[146:149], v[62:65]
	v_mfma_f32_16x16x32_bf16 v[58:61], v[106:109], v[146:149], v[58:61]
	v_mfma_f32_16x16x32_bf16 v[46:49], v[98:101], v[154:157], v[46:49]
	v_mfma_f32_16x16x32_bf16 v[42:45], v[106:109], v[154:157], v[42:45]
	v_mfma_f32_16x16x32_bf16 v[30:33], v[98:101], v[162:165], v[30:33]
	v_mfma_f32_16x16x32_bf16 v[26:29], v[106:109], v[162:165], v[26:29]
	v_mfma_f32_16x16x32_bf16 v[14:17], v[98:101], v[196:199], v[14:17]
	v_mfma_f32_16x16x32_bf16 v[10:13], v[106:109], v[196:199], v[10:13]
	v_mfma_f32_16x16x32_bf16 v[62:65], v[102:105], v[150:153], v[62:65]
	v_mfma_f32_16x16x32_bf16 v[58:61], v[110:113], v[150:153], v[58:61]
	v_mfma_f32_16x16x32_bf16 v[46:49], v[102:105], v[158:161], v[46:49]
	v_mfma_f32_16x16x32_bf16 v[42:45], v[110:113], v[158:161], v[42:45]
	v_mfma_f32_16x16x32_bf16 v[30:33], v[102:105], v[166:169], v[30:33]
	v_mfma_f32_16x16x32_bf16 v[26:29], v[110:113], v[166:169], v[26:29]
	v_mfma_f32_16x16x32_bf16 v[14:17], v[102:105], v[200:203], v[14:17]
	v_mfma_f32_16x16x32_bf16 v[10:13], v[110:113], v[200:203], v[10:13]
	v_mfma_f32_16x16x32_bf16 v[54:57], v[204:207], v[146:149], v[54:57]
	v_mfma_f32_16x16x32_bf16 v[50:53], v[212:215], v[146:149], v[50:53]
	v_mfma_f32_16x16x32_bf16 v[38:41], v[204:207], v[154:157], v[38:41]
	v_mfma_f32_16x16x32_bf16 v[34:37], v[212:215], v[154:157], v[34:37]
	v_mfma_f32_16x16x32_bf16 v[22:25], v[204:207], v[162:165], v[22:25]
	v_mfma_f32_16x16x32_bf16 v[18:21], v[212:215], v[162:165], v[18:21]
	v_mfma_f32_16x16x32_bf16 v[6:9], v[204:207], v[196:199], v[6:9]
	v_mfma_f32_16x16x32_bf16 v[2:5], v[212:215], v[196:199], v[2:5]
	v_mfma_f32_16x16x32_bf16 v[54:57], v[208:211], v[150:153], v[54:57]
	v_mfma_f32_16x16x32_bf16 v[50:53], v[216:219], v[150:153], v[50:53]
	v_mfma_f32_16x16x32_bf16 v[38:41], v[208:211], v[158:161], v[38:41]
	v_mfma_f32_16x16x32_bf16 v[34:37], v[216:219], v[158:161], v[34:37]
	v_mfma_f32_16x16x32_bf16 v[22:25], v[208:211], v[166:169], v[22:25]
	v_mfma_f32_16x16x32_bf16 v[18:21], v[216:219], v[166:169], v[18:21]
	v_mfma_f32_16x16x32_bf16 v[6:9], v[208:211], v[200:203], v[6:9]
	v_mfma_f32_16x16x32_bf16 v[2:5], v[216:219], v[200:203], v[2:5]
	s_barrier
	s_setprio 0
	s_add_i32 s73, s73, 2
	s_add_u32 s44, s44, 0x100
	s_addc_u32 s45, s45, 0
	s_add_u32 s71, s71, 0x100
	s_addc_u32 s72, s72, 0
	s_cmp_gt_u32 s73, 13
	s_cbranch_scc0 .LBB0_2845
	s_ashr_i32 s18, s42, 3
	s_mul_hi_i32 s19, s18, 0x9000
	s_mul_i32 s18, s18, 0x9000
	s_add_u32 s20, s58, s18
	s_addc_u32 s21, s59, s19
	s_lshl_b32 s44, s0, 8
	v_lshl_add_u32 v220, s42, 8, v1
	s_ashr_i32 s45, s44, 31
	s_lshl_b64 s[18:19], s[44:45], 2
	v_ashrrev_i32_e32 v221, 31, v220
	v_lshl_add_u64 v[146:147], s[44:45], 1, v[186:187]
	v_lshlrev_b64 v[98:99], 11, v[220:221]
	s_add_u32 s18, s20, s18
	v_lshl_add_u64 v[98:99], v[146:147], 0, v[98:99]
	s_addc_u32 s19, s21, s19
	v_lshlrev_b32_e32 v182, 2, v184
	global_load_dwordx4 v[224:227], v[98:99], off
	global_load_dwordx4 v[234:237], v[98:99], off offset:256
	v_lshl_add_u64 v[98:99], s[18:19], 0, v[182:183]
	v_add_co_u32_e32 v102, vcc, s68, v98
	v_lshl_add_u64 v[100:101], v[98:99], 0, s[16:17]
	s_nop 0
	v_addc_co_u32_e32 v103, vcc, 0, v99, vcc
	global_load_dwordx4 v[198:201], v[102:103], off
	global_load_dwordx4 v[238:241], v[100:101], off offset:16
	global_load_dwordx4 v[202:205], v[102:103], off offset:512
	v_lshl_add_u64 v[100:101], v[98:99], 0, s[24:25]
	global_load_dwordx4 v[242:245], v[100:101], off offset:16
	v_add_co_u32_e32 v100, vcc, s67, v98
	v_or_b32_e32 v218, 16, v220
	s_nop 0
	v_addc_co_u32_e32 v101, vcc, 0, v99, vcc
	global_load_dwordx4 v[110:113], v[100:101], off
	global_load_dwordx4 v[106:109], v[100:101], off offset:512
	v_lshl_add_u64 v[100:101], v[98:99], 0, s[12:13]
	v_lshl_add_u64 v[98:99], v[98:99], 0, s[14:15]
	global_load_dwordx4 v[102:105], v[100:101], off offset:16
	v_or_b32_e32 v216, 32, v220
	global_load_dwordx4 v[98:101], v[98:99], off offset:16
	v_or_b32_e32 v214, 48, v220
	v_ashrrev_i32_e32 v219, 31, v218
	v_ashrrev_i32_e32 v217, 31, v216
	v_ashrrev_i32_e32 v215, 31, v214
	v_lshlrev_b64 v[148:149], 11, v[218:219]
	v_lshlrev_b64 v[150:151], 11, v[216:217]
	v_lshlrev_b64 v[152:153], 11, v[214:215]
	v_lshl_add_u64 v[148:149], v[146:147], 0, v[148:149]
	v_lshl_add_u64 v[150:151], v[146:147], 0, v[150:151]
	v_lshl_add_u64 v[146:147], v[146:147], 0, v[152:153]
	global_load_dwordx4 v[166:169], v[148:149], off
	global_load_dwordx4 v[162:165], v[148:149], off offset:256
	global_load_dwordx4 v[158:161], v[150:151], off
	global_load_dwordx4 v[154:157], v[150:151], off offset:256
	s_nop 0
	global_load_dwordx4 v[150:153], v[146:147], off
	s_nop 0
	global_load_dwordx4 v[146:149], v[146:147], off offset:256
	v_or_b32_e32 v196, s44, v184
	v_mov_b32_e32 v197, s45
	s_lshl_b32 s42, s0, 2
	s_ashr_i32 s43, s42, 31
	s_waitcnt vmcnt(0)
	v_lshlrev_b32_e32 v228, 16, v224
	v_and_b32_e32 v229, 0xffff0000, v224
	v_lshlrev_b32_e32 v224, 16, v225
	v_and_b32_e32 v225, 0xffff0000, v225
	v_lshlrev_b32_e32 v250, 16, v236
	v_and_b32_e32 v251, 0xffff0000, v236
	v_lshlrev_b32_e32 v248, 16, v226
	v_and_b32_e32 v249, 0xffff0000, v226
	v_lshlrev_b32_e32 v246, 16, v234
	v_and_b32_e32 v247, 0xffff0000, v234
	v_lshlrev_b32_e32 v234, 16, v235
	v_and_b32_e32 v235, 0xffff0000, v235
	v_pk_add_f32 v[210:211], v[202:203], 1.0 op_sel_hi:[1,0]
	v_pk_add_f32 v[206:207], v[204:205], 1.0 op_sel_hi:[1,0]
	v_pk_add_f32 v[208:209], v[200:201], 1.0 op_sel_hi:[1,0]
	v_pk_fma_f32 v[144:145], v[144:145], v[112:113], v[224:225]
	v_pk_fma_f32 v[142:143], v[142:143], v[110:111], v[228:229]
	v_pk_fma_f32 v[134:135], v[134:135], v[106:107], v[246:247]
	v_pk_fma_f32 v[136:137], v[136:137], v[108:109], v[234:235]
	v_pk_fma_f32 v[138:139], v[138:139], v[102:103], v[248:249]
	v_pk_mul_f32 v[234:235], v[210:211], v[134:135]
	v_pk_fma_f32 v[224:225], v[130:131], v[98:99], v[250:251]
	v_lshlrev_b32_e32 v130, 16, v227
	v_and_b32_e32 v131, 0xffff0000, v227
	v_pk_fma_f32 v[140:141], v[140:141], v[104:105], v[130:131]
	v_lshlrev_b32_e32 v130, 16, v237
	v_and_b32_e32 v131, 0xffff0000, v237
	v_pk_fma_f32 v[236:237], v[132:133], v[100:101], v[130:131]
	v_lshlrev_b64 v[130:131], 10, v[220:221]
	v_lshl_add_u64 v[130:131], v[130:131], 0, v[196:197]
	v_lshlrev_b64 v[248:249], 1, v[130:131]
	v_lshl_add_u64 v[250:251], s[28:29], 0, v[248:249]
	v_cvt_pk_bf16_f32 v130, v142, v143
	v_cvt_pk_bf16_f32 v131, v144, v145
	v_cvt_pk_bf16_f32 v132, v138, v139
	v_cvt_pk_bf16_f32 v133, v140, v141
	global_store_dwordx4 v[250:251], v[130:133], off nt
	v_pk_add_f32 v[200:201], v[240:241], 1.0 op_sel_hi:[1,0]
	v_pk_mul_f32 v[240:241], v[206:207], v[136:137]
	v_cvt_pk_bf16_f32 v130, v134, v135
	v_cvt_pk_bf16_f32 v131, v136, v137
	v_cvt_pk_bf16_f32 v132, v224, v225
	v_cvt_pk_bf16_f32 v133, v236, v237
	global_store_dwordx4 v[250:251], v[130:133], off offset:256 nt
	v_pk_add_f32 v[204:205], v[238:239], 1.0 op_sel_hi:[1,0]
	v_pk_add_f32 v[202:203], v[242:243], 1.0 op_sel_hi:[1,0]
	v_pk_mul_f32 v[132:133], v[134:135], v[134:135]
	v_pk_mul_f32 v[134:135], v[136:137], v[136:137]
	v_pk_fma_f32 v[132:133], v[142:143], v[142:143], v[132:133]
	v_pk_fma_f32 v[134:135], v[144:145], v[144:145], v[134:135]
	v_add_f32_e32 v132, v132, v133
	v_pk_mul_f32 v[136:137], v[224:225], v[224:225]
	v_add_f32_e32 v132, v134, v132
	v_pk_fma_f32 v[136:137], v[138:139], v[138:139], v[136:137]
	v_add_f32_e32 v132, v135, v132
	v_pk_mul_f32 v[242:243], v[204:205], v[138:139]
	v_pk_mul_f32 v[138:139], v[236:237], v[236:237]
	v_add_f32_e32 v132, v136, v132
	v_pk_fma_f32 v[138:139], v[140:141], v[140:141], v[138:139]
	v_add_f32_e32 v132, v137, v132
	v_add_f32_e32 v132, v138, v132
	v_and_b32_e32 v133, 64, v223
	v_add_f32_e32 v134, v139, v132
	v_xor_b32_e32 v132, 16, v223
	v_add_u32_e32 v135, 64, v133
	v_cmp_lt_i32_e32 vcc, v132, v135
	v_pk_add_f32 v[212:213], v[198:199], 1.0 op_sel_hi:[1,0]
	v_pk_mul_f32 v[238:239], v[208:209], v[144:145]
	v_cndmask_b32_e32 v132, v223, v132, vcc
	v_pk_mul_f32 v[228:229], v[212:213], v[142:143]
	v_lshlrev_b32_e32 v142, 2, v132
	v_pk_mul_f32 v[226:227], v[200:201], v[140:141]
	ds_bpermute_b32 v136, v142, v134
	v_lshl_add_u64 v[248:249], s[6:7], 0, v[248:249]
	v_cvt_pk_bf16_f32 v130, v228, v229
	v_cvt_pk_bf16_f32 v131, v238, v239
	v_cvt_pk_bf16_f32 v132, v242, v243
	v_cvt_pk_bf16_f32 v133, v226, v227
	global_store_dwordx4 v[248:249], v[130:133], off nt
	v_pk_add_f32 v[198:199], v[244:245], 1.0 op_sel_hi:[1,0]
	v_pk_mul_f32 v[244:245], v[202:203], v[224:225]
	v_xor_b32_e32 v131, 32, v223
	v_cmp_lt_i32_e32 vcc, v131, v135
	s_waitcnt lgkmcnt(0)
	v_add_f32_e32 v130, v134, v136
	v_pk_mul_f32 v[246:247], v[198:199], v[236:237]
	v_cndmask_b32_e32 v131, v223, v131, vcc
	v_lshlrev_b32_e32 v143, 2, v131
	ds_bpermute_b32 v131, v143, v130
	v_cvt_pk_bf16_f32 v132, v234, v235
	v_cvt_pk_bf16_f32 v133, v240, v241
	v_cvt_pk_bf16_f32 v134, v244, v245
	v_cvt_pk_bf16_f32 v135, v246, v247
	global_store_dwordx4 v[248:249], v[132:135], off offset:256 nt
	s_and_saveexec_b64 s[18:19], s[2:3]
	s_cbranch_execz .LBB0_2848
	s_waitcnt lgkmcnt(0)
	v_add_f32_e32 v132, v130, v131
	v_lshlrev_b64 v[130:131], 6, v[220:221]
	v_lshl_add_u64 v[130:131], s[8:9], 0, v[130:131]
	v_lshl_add_u64 v[130:131], s[42:43], 2, v[130:131]
	s_lshl_b32 s0, s61, 2
	v_lshl_add_u64 v[130:131], v[130:131], 0, s[0:1]
	global_store_dword v[130:131], v132, off

.LBB0_3264:
	s_ashr_i32 s11, s10, 31
	v_cmp_lt_i64_e32 vcc, s[12:13], v[162:163]
	s_lshl_b64 s[12:13], s[10:11], 19
	s_add_u32 s12, s36, s12
	s_addc_u32 s13, s37, s13
	s_and_b64 s[14:15], vcc, exec
	s_cselect_b32 s11, s13, s25
	s_cselect_b32 s57, s12, s24
	s_ashr_i32 s9, s8, 31
	s_lshl_b64 s[14:15], s[8:9], 19
	s_add_u32 s14, s38, s14
	s_addc_u32 s15, s39, s15
	s_and_b64 s[18:19], vcc, exec
	s_cselect_b32 s9, s15, s35
	s_cselect_b32 s60, s14, s34
	s_add_u32 s24, s24, 0x40080
	s_addc_u32 s25, s25, 0
	s_add_u32 s61, s34, 0x100
	s_addc_u32 s62, s35, 0
	s_mov_b32 s63, -2
	ds_read_b128 v[130:133], v171
	ds_read_b128 v[134:137], v171 offset:1024
	ds_read_b128 v[138:141], v171 offset:2048
	ds_read_b128 v[142:145], v171 offset:3072
	s_add_u32 s18, s24, 0xfffc0080
	s_addc_u32 s19, s25, -1
	s_cmp_eq_u32 s63, 12
	s_cselect_b32 s19, s11, s19
	s_cselect_b32 s18, s57, s18
	s_cselect_b32 s35, s9, s62
	s_cselect_b32 s34, s60, s61
	v_lshl_add_u64 v[174:175], s[24:25], 0, v[158:159]
	s_add_i32 m0, s43, 0xc000
	ds_read_b128 v[166:169], v173
	ds_read_b128 v[178:181], v173 offset:1024
	ds_read_b128 v[182:185], v173 offset:2048
	ds_read_b128 v[186:189], v173 offset:3072
	ds_read_b128 v[190:193], v173 offset:4096
	ds_read_b128 v[194:197], v173 offset:5120
	ds_read_b128 v[198:201], v173 offset:6144
	ds_read_b128 v[202:205], v173 offset:7168
	global_load_lds_dwordx4 v[174:175], off
	v_lshl_add_u64 v[174:175], s[24:25], 0, v[160:161]
	s_add_i32 m0, s43, 0xe000
	s_nop 0
	global_load_lds_dwordx4 v[174:175], off
	ds_read_b128 v[206:209], v177
	ds_read_b128 v[210:213], v177 offset:1024
	ds_read_b128 v[214:217], v177 offset:2048
	ds_read_b128 v[218:221], v177 offset:3072
	s_waitcnt vmcnt(8)
	s_waitcnt lgkmcnt(0)
	s_setprio 1
	s_barrier
	v_mfma_f32_16x16x32_bf16 v[126:129], v[130:133], v[166:169], 0
	v_mfma_f32_16x16x32_bf16 v[122:125], v[138:141], v[166:169], 0
	v_mfma_f32_16x16x32_bf16 v[110:113], v[130:133], v[182:185], 0
	v_mfma_f32_16x16x32_bf16 v[106:109], v[138:141], v[182:185], 0
	v_mfma_f32_16x16x32_bf16 v[94:97], v[130:133], v[190:193], 0
	v_mfma_f32_16x16x32_bf16 v[90:93], v[138:141], v[190:193], 0
	v_mfma_f32_16x16x32_bf16 v[78:81], v[130:133], v[198:201], 0
	v_mfma_f32_16x16x32_bf16 v[74:77], v[138:141], v[198:201], 0
	v_mfma_f32_16x16x32_bf16 v[126:129], v[134:137], v[178:181], v[126:129]
	v_mfma_f32_16x16x32_bf16 v[122:125], v[142:145], v[178:181], v[122:125]
	v_mfma_f32_16x16x32_bf16 v[110:113], v[134:137], v[186:189], v[110:113]
	v_mfma_f32_16x16x32_bf16 v[106:109], v[142:145], v[186:189], v[106:109]
	v_mfma_f32_16x16x32_bf16 v[94:97], v[134:137], v[194:197], v[94:97]
	v_mfma_f32_16x16x32_bf16 v[90:93], v[142:145], v[194:197], v[90:93]
	v_mfma_f32_16x16x32_bf16 v[78:81], v[134:137], v[202:205], v[78:81]
	v_mfma_f32_16x16x32_bf16 v[74:77], v[142:145], v[202:205], v[74:77]
	v_mfma_f32_16x16x32_bf16 v[118:121], v[206:209], v[166:169], 0
	v_mfma_f32_16x16x32_bf16 v[114:117], v[214:217], v[166:169], 0
	v_mfma_f32_16x16x32_bf16 v[102:105], v[206:209], v[182:185], 0
	v_mfma_f32_16x16x32_bf16 v[98:101], v[214:217], v[182:185], 0
	v_mfma_f32_16x16x32_bf16 v[86:89], v[206:209], v[190:193], 0
	v_mfma_f32_16x16x32_bf16 v[82:85], v[214:217], v[190:193], 0
	v_mfma_f32_16x16x32_bf16 v[70:73], v[206:209], v[198:201], 0
	v_mfma_f32_16x16x32_bf16 v[66:69], v[214:217], v[198:201], 0
	v_mfma_f32_16x16x32_bf16 v[118:121], v[210:213], v[178:181], v[118:121]
	v_mfma_f32_16x16x32_bf16 v[114:117], v[218:221], v[178:181], v[114:117]
	v_mfma_f32_16x16x32_bf16 v[102:105], v[210:213], v[186:189], v[102:105]
	v_mfma_f32_16x16x32_bf16 v[98:101], v[218:221], v[186:189], v[98:101]
	v_mfma_f32_16x16x32_bf16 v[86:89], v[210:213], v[194:197], v[86:89]
	v_mfma_f32_16x16x32_bf16 v[82:85], v[218:221], v[194:197], v[82:85]
	v_mfma_f32_16x16x32_bf16 v[70:73], v[210:213], v[202:205], v[70:73]
	v_mfma_f32_16x16x32_bf16 v[66:69], v[218:221], v[202:205], v[66:69]
	s_barrier
	s_setprio 0
	s_add_i32 s20, s54, s42
	v_lshl_add_u64 v[174:175], s[34:35], 0, v[150:151]
	s_mov_b32 m0, s20
	s_nop 0
	global_load_lds_dwordx4 v[174:175], off
	v_lshl_add_u64 v[222:223], s[34:35], 0, v[146:147]
	s_add_i32 m0, s20, 0x2000
	s_nop 0
	global_load_lds_dwordx4 v[222:223], off
	s_mov_b32 m0, s43
	v_lshl_add_u64 v[224:225], s[18:19], 0, v[152:153]
	ds_read_b128 v[166:169], v173 offset:16384
	ds_read_b128 v[178:181], v173 offset:17408
	ds_read_b128 v[182:185], v173 offset:18432
	ds_read_b128 v[186:189], v173 offset:19456
	ds_read_b128 v[190:193], v173 offset:20480
	ds_read_b128 v[194:197], v173 offset:21504
	ds_read_b128 v[198:201], v173 offset:22528
	ds_read_b128 v[202:205], v173 offset:23552
	global_load_lds_dwordx4 v[224:225], off
	v_lshl_add_u64 v[226:227], s[18:19], 0, v[148:149]
	s_mov_b32 m0, s44
	s_nop 0
	global_load_lds_dwordx4 v[226:227], off
	s_add_u32 s20, s34, 0x40000
	s_addc_u32 s21, s35, 0
	s_add_i32 s64, s55, s42
	v_lshl_add_u64 v[246:247], s[20:21], 0, v[150:151]
	s_mov_b32 m0, s64
	s_nop 0
	global_load_lds_dwordx4 v[246:247], off
	v_lshl_add_u64 v[246:247], s[20:21], 0, v[146:147]
	s_add_i32 m0, s64, 0x2000
	s_nop 0
	global_load_lds_dwordx4 v[246:247], off
	s_waitcnt vmcnt(8)
	s_waitcnt lgkmcnt(0)
	s_setprio 1
	s_barrier
	v_mfma_f32_16x16x32_bf16 v[62:65], v[130:133], v[166:169], 0
	v_mfma_f32_16x16x32_bf16 v[58:61], v[138:141], v[166:169], 0
	v_mfma_f32_16x16x32_bf16 v[46:49], v[130:133], v[182:185], 0
	v_mfma_f32_16x16x32_bf16 v[42:45], v[138:141], v[182:185], 0
	v_mfma_f32_16x16x32_bf16 v[30:33], v[130:133], v[190:193], 0
	v_mfma_f32_16x16x32_bf16 v[26:29], v[138:141], v[190:193], 0
	v_mfma_f32_16x16x32_bf16 v[14:17], v[130:133], v[198:201], 0
	v_mfma_f32_16x16x32_bf16 v[10:13], v[138:141], v[198:201], 0
	v_mfma_f32_16x16x32_bf16 v[62:65], v[134:137], v[178:181], v[62:65]
	v_mfma_f32_16x16x32_bf16 v[58:61], v[142:145], v[178:181], v[58:61]
	v_mfma_f32_16x16x32_bf16 v[46:49], v[134:137], v[186:189], v[46:49]
	v_mfma_f32_16x16x32_bf16 v[42:45], v[142:145], v[186:189], v[42:45]
	v_mfma_f32_16x16x32_bf16 v[30:33], v[134:137], v[194:197], v[30:33]
	v_mfma_f32_16x16x32_bf16 v[26:29], v[142:145], v[194:197], v[26:29]
	v_mfma_f32_16x16x32_bf16 v[14:17], v[134:137], v[202:205], v[14:17]
	v_mfma_f32_16x16x32_bf16 v[10:13], v[142:145], v[202:205], v[10:13]
	v_mfma_f32_16x16x32_bf16 v[54:57], v[206:209], v[166:169], 0
	v_mfma_f32_16x16x32_bf16 v[50:53], v[214:217], v[166:169], 0
	v_mfma_f32_16x16x32_bf16 v[38:41], v[206:209], v[182:185], 0
	v_mfma_f32_16x16x32_bf16 v[34:37], v[214:217], v[182:185], 0
	v_mfma_f32_16x16x32_bf16 v[22:25], v[206:209], v[190:193], 0
	v_mfma_f32_16x16x32_bf16 v[18:21], v[214:217], v[190:193], 0
	v_mfma_f32_16x16x32_bf16 v[6:9], v[206:209], v[198:201], 0
	v_mfma_f32_16x16x32_bf16 v[2:5], v[214:217], v[198:201], 0
	v_mfma_f32_16x16x32_bf16 v[54:57], v[210:213], v[178:181], v[54:57]
	v_mfma_f32_16x16x32_bf16 v[50:53], v[218:221], v[178:181], v[50:53]
	v_mfma_f32_16x16x32_bf16 v[38:41], v[210:213], v[186:189], v[38:41]
	v_mfma_f32_16x16x32_bf16 v[34:37], v[218:221], v[186:189], v[34:37]
	v_mfma_f32_16x16x32_bf16 v[22:25], v[210:213], v[194:197], v[22:25]
	v_mfma_f32_16x16x32_bf16 v[18:21], v[218:221], v[194:197], v[18:21]
	v_mfma_f32_16x16x32_bf16 v[6:9], v[210:213], v[202:205], v[6:9]
	v_mfma_f32_16x16x32_bf16 v[2:5], v[218:221], v[202:205], v[2:5]
	s_barrier
	s_setprio 0
	s_add_i32 s20, 0, 0x18000
	v_add_u32_e32 v142, s20, v157
	ds_read_b128 v[130:133], v142
	ds_read_b128 v[134:137], v142 offset:1024
	ds_read_b128 v[138:141], v142 offset:2048
	ds_read_b128 v[142:145], v142 offset:3072
	s_add_u32 s18, s18, 0x40000
	s_addc_u32 s19, s19, 0
	s_mov_b32 m0, s45
	v_lshl_add_u64 v[206:207], s[18:19], 0, v[152:153]
	ds_read_b128 v[166:169], v173 offset:32768
	ds_read_b128 v[178:181], v173 offset:33792
	ds_read_b128 v[182:185], v173 offset:34816
	ds_read_b128 v[186:189], v173 offset:35840
	ds_read_b128 v[190:193], v173 offset:36864
	ds_read_b128 v[194:197], v173 offset:37888
	ds_read_b128 v[198:201], v173 offset:38912
	ds_read_b128 v[202:205], v173 offset:39936
	global_load_lds_dwordx4 v[206:207], off
	v_lshl_add_u64 v[206:207], s[18:19], 0, v[148:149]
	s_mov_b32 m0, s46
	s_nop 0
	global_load_lds_dwordx4 v[206:207], off
	s_add_i32 s21, 0, 0x1c000
	v_add_u32_e32 v154, s21, v157
	ds_read_b128 v[206:209], v154
	ds_read_b128 v[210:213], v154 offset:1024
	ds_read_b128 v[214:217], v154 offset:2048
	ds_read_b128 v[218:221], v154 offset:3072
	s_waitcnt vmcnt(8)
	s_waitcnt lgkmcnt(0)
	s_setprio 1
	s_barrier
	v_mfma_f32_16x16x32_bf16 v[126:129], v[130:133], v[166:169], v[126:129]
	v_mfma_f32_16x16x32_bf16 v[122:125], v[138:141], v[166:169], v[122:125]
	v_mfma_f32_16x16x32_bf16 v[110:113], v[130:133], v[182:185], v[110:113]
	v_mfma_f32_16x16x32_bf16 v[106:109], v[138:141], v[182:185], v[106:109]
	v_mfma_f32_16x16x32_bf16 v[94:97], v[130:133], v[190:193], v[94:97]
	v_mfma_f32_16x16x32_bf16 v[90:93], v[138:141], v[190:193], v[90:93]
	v_mfma_f32_16x16x32_bf16 v[78:81], v[130:133], v[198:201], v[78:81]
	v_mfma_f32_16x16x32_bf16 v[74:77], v[138:141], v[198:201], v[74:77]
	v_mfma_f32_16x16x32_bf16 v[126:129], v[134:137], v[178:181], v[126:129]
	v_mfma_f32_16x16x32_bf16 v[122:125], v[142:145], v[178:181], v[122:125]
	v_mfma_f32_16x16x32_bf16 v[110:113], v[134:137], v[186:189], v[110:113]
	v_mfma_f32_16x16x32_bf16 v[106:109], v[142:145], v[186:189], v[106:109]
	v_mfma_f32_16x16x32_bf16 v[94:97], v[134:137], v[194:197], v[94:97]
	v_mfma_f32_16x16x32_bf16 v[90:93], v[142:145], v[194:197], v[90:93]
	v_mfma_f32_16x16x32_bf16 v[78:81], v[134:137], v[202:205], v[78:81]
	v_mfma_f32_16x16x32_bf16 v[74:77], v[142:145], v[202:205], v[74:77]
	v_mfma_f32_16x16x32_bf16 v[118:121], v[206:209], v[166:169], v[118:121]
	v_mfma_f32_16x16x32_bf16 v[114:117], v[214:217], v[166:169], v[114:117]
	v_mfma_f32_16x16x32_bf16 v[102:105], v[206:209], v[182:185], v[102:105]
	v_mfma_f32_16x16x32_bf16 v[98:101], v[214:217], v[182:185], v[98:101]
	v_mfma_f32_16x16x32_bf16 v[86:89], v[206:209], v[190:193], v[86:89]
	v_mfma_f32_16x16x32_bf16 v[82:85], v[214:217], v[190:193], v[82:85]
	v_mfma_f32_16x16x32_bf16 v[70:73], v[206:209], v[198:201], v[70:73]
	v_mfma_f32_16x16x32_bf16 v[66:69], v[214:217], v[198:201], v[66:69]
	v_mfma_f32_16x16x32_bf16 v[118:121], v[210:213], v[178:181], v[118:121]
	v_mfma_f32_16x16x32_bf16 v[114:117], v[218:221], v[178:181], v[114:117]
	v_mfma_f32_16x16x32_bf16 v[102:105], v[210:213], v[186:189], v[102:105]
	v_mfma_f32_16x16x32_bf16 v[98:101], v[218:221], v[186:189], v[98:101]
	v_mfma_f32_16x16x32_bf16 v[86:89], v[210:213], v[194:197], v[86:89]
	v_mfma_f32_16x16x32_bf16 v[82:85], v[218:221], v[194:197], v[82:85]
	v_mfma_f32_16x16x32_bf16 v[70:73], v[210:213], v[202:205], v[70:73]
	v_mfma_f32_16x16x32_bf16 v[66:69], v[218:221], v[202:205], v[66:69]
	s_barrier
	s_setprio 0
	s_add_i32 s18, s20, s42
	v_lshl_add_u64 v[174:175], v[174:175], 0, s[6:7]
	s_mov_b32 m0, s18
	s_nop 0
	global_load_lds_dwordx4 v[174:175], off
	v_lshl_add_u64 v[174:175], v[222:223], 0, s[6:7]
	s_add_i32 m0, s18, 0x2000
	s_nop 0
	global_load_lds_dwordx4 v[174:175], off
	s_mov_b32 m0, s50
	v_lshl_add_u64 v[174:175], v[224:225], 0, s[6:7]
	ds_read_b128 v[166:169], v173 offset:49152
	ds_read_b128 v[178:181], v173 offset:50176
	ds_read_b128 v[182:185], v173 offset:51200
	ds_read_b128 v[186:189], v173 offset:52224
	ds_read_b128 v[190:193], v173 offset:53248
	ds_read_b128 v[194:197], v173 offset:54272
	ds_read_b128 v[198:201], v173 offset:55296
	ds_read_b128 v[202:205], v173 offset:56320
	global_load_lds_dwordx4 v[174:175], off
	v_lshl_add_u64 v[174:175], v[226:227], 0, s[6:7]
	s_mov_b32 m0, s51
	s_nop 0
	global_load_lds_dwordx4 v[174:175], off
	s_add_u32 s18, s34, 0x40080
	s_addc_u32 s19, s35, 0
	s_add_i32 s20, s21, s42
	v_lshl_add_u64 v[248:249], s[18:19], 0, v[150:151]
	s_mov_b32 m0, s20
	s_nop 0
	global_load_lds_dwordx4 v[248:249], off
	v_lshl_add_u64 v[248:249], s[18:19], 0, v[146:147]
	s_add_i32 m0, s20, 0x2000
	s_nop 0
	global_load_lds_dwordx4 v[248:249], off
	s_waitcnt vmcnt(8)
	s_waitcnt lgkmcnt(0)
	s_setprio 1
	s_barrier
	v_mfma_f32_16x16x32_bf16 v[62:65], v[130:133], v[166:169], v[62:65]
	v_mfma_f32_16x16x32_bf16 v[58:61], v[138:141], v[166:169], v[58:61]
	v_mfma_f32_16x16x32_bf16 v[46:49], v[130:133], v[182:185], v[46:49]
	v_mfma_f32_16x16x32_bf16 v[42:45], v[138:141], v[182:185], v[42:45]
	v_mfma_f32_16x16x32_bf16 v[30:33], v[130:133], v[190:193], v[30:33]
	v_mfma_f32_16x16x32_bf16 v[26:29], v[138:141], v[190:193], v[26:29]
	v_mfma_f32_16x16x32_bf16 v[14:17], v[130:133], v[198:201], v[14:17]
	v_mfma_f32_16x16x32_bf16 v[10:13], v[138:141], v[198:201], v[10:13]
	v_mfma_f32_16x16x32_bf16 v[62:65], v[134:137], v[178:181], v[62:65]
	v_mfma_f32_16x16x32_bf16 v[58:61], v[142:145], v[178:181], v[58:61]
	v_mfma_f32_16x16x32_bf16 v[46:49], v[134:137], v[186:189], v[46:49]
	v_mfma_f32_16x16x32_bf16 v[42:45], v[142:145], v[186:189], v[42:45]
	v_mfma_f32_16x16x32_bf16 v[30:33], v[134:137], v[194:197], v[30:33]
	v_mfma_f32_16x16x32_bf16 v[26:29], v[142:145], v[194:197], v[26:29]
	v_mfma_f32_16x16x32_bf16 v[14:17], v[134:137], v[202:205], v[14:17]
	v_mfma_f32_16x16x32_bf16 v[10:13], v[142:145], v[202:205], v[10:13]
	v_mfma_f32_16x16x32_bf16 v[54:57], v[206:209], v[166:169], v[54:57]
	v_mfma_f32_16x16x32_bf16 v[50:53], v[214:217], v[166:169], v[50:53]
	v_mfma_f32_16x16x32_bf16 v[38:41], v[206:209], v[182:185], v[38:41]
	v_mfma_f32_16x16x32_bf16 v[34:37], v[214:217], v[182:185], v[34:37]
	v_mfma_f32_16x16x32_bf16 v[22:25], v[206:209], v[190:193], v[22:25]
	v_mfma_f32_16x16x32_bf16 v[18:21], v[214:217], v[190:193], v[18:21]
	v_mfma_f32_16x16x32_bf16 v[6:9], v[206:209], v[198:201], v[6:9]
	v_mfma_f32_16x16x32_bf16 v[2:5], v[214:217], v[198:201], v[2:5]
	v_mfma_f32_16x16x32_bf16 v[54:57], v[210:213], v[178:181], v[54:57]
	v_mfma_f32_16x16x32_bf16 v[50:53], v[218:221], v[178:181], v[50:53]
	v_mfma_f32_16x16x32_bf16 v[38:41], v[210:213], v[186:189], v[38:41]
	v_mfma_f32_16x16x32_bf16 v[34:37], v[218:221], v[186:189], v[34:37]
	v_mfma_f32_16x16x32_bf16 v[22:25], v[210:213], v[194:197], v[22:25]
	v_mfma_f32_16x16x32_bf16 v[18:21], v[218:221], v[194:197], v[18:21]
	v_mfma_f32_16x16x32_bf16 v[6:9], v[210:213], v[202:205], v[6:9]
	v_mfma_f32_16x16x32_bf16 v[2:5], v[218:221], v[202:205], v[2:5]
	s_barrier
	s_setprio 0
	s_add_i32 s63, s63, 2
	s_add_u32 s24, s24, 0x100
	s_addc_u32 s25, s25, 0
	s_add_u32 s61, s61, 0x100
	s_addc_u32 s62, s62, 0
	s_cmp_gt_u32 s63, 13
.LBB0_3265:
	ds_read_b128 v[130:133], v171
	ds_read_b128 v[134:137], v171 offset:1024
	ds_read_b128 v[138:141], v171 offset:2048
	ds_read_b128 v[142:145], v171 offset:3072
	s_add_u32 s18, s24, 0xfffc0080
	s_addc_u32 s19, s25, -1
	s_cmp_eq_u32 s63, 12
	s_cselect_b32 s19, s11, s19
	s_cselect_b32 s18, s57, s18
	s_cselect_b32 s35, s9, s62
	s_cselect_b32 s34, s60, s61
	v_lshl_add_u64 v[174:175], s[24:25], 0, v[158:159]
	s_add_i32 m0, s43, 0xc000
	ds_read_b128 v[166:169], v173
	ds_read_b128 v[178:181], v173 offset:1024
	ds_read_b128 v[182:185], v173 offset:2048
	ds_read_b128 v[186:189], v173 offset:3072
	ds_read_b128 v[190:193], v173 offset:4096
	ds_read_b128 v[194:197], v173 offset:5120
	ds_read_b128 v[198:201], v173 offset:6144
	ds_read_b128 v[202:205], v173 offset:7168
	global_load_lds_dwordx4 v[174:175], off
	v_lshl_add_u64 v[174:175], s[24:25], 0, v[160:161]
	s_add_i32 m0, s43, 0xe000
	s_nop 0
	global_load_lds_dwordx4 v[174:175], off
	ds_read_b128 v[206:209], v177
	ds_read_b128 v[210:213], v177 offset:1024
	ds_read_b128 v[214:217], v177 offset:2048
	ds_read_b128 v[218:221], v177 offset:3072
	s_waitcnt vmcnt(8)
	s_waitcnt lgkmcnt(0)
	s_setprio 1
	s_barrier
	v_mfma_f32_16x16x32_bf16 v[126:129], v[130:133], v[166:169], v[126:129]
	v_mfma_f32_16x16x32_bf16 v[122:125], v[138:141], v[166:169], v[122:125]
	v_mfma_f32_16x16x32_bf16 v[110:113], v[130:133], v[182:185], v[110:113]
	v_mfma_f32_16x16x32_bf16 v[106:109], v[138:141], v[182:185], v[106:109]
	v_mfma_f32_16x16x32_bf16 v[94:97], v[130:133], v[190:193], v[94:97]
	v_mfma_f32_16x16x32_bf16 v[90:93], v[138:141], v[190:193], v[90:93]
	v_mfma_f32_16x16x32_bf16 v[78:81], v[130:133], v[198:201], v[78:81]
	v_mfma_f32_16x16x32_bf16 v[74:77], v[138:141], v[198:201], v[74:77]
	v_mfma_f32_16x16x32_bf16 v[126:129], v[134:137], v[178:181], v[126:129]
	v_mfma_f32_16x16x32_bf16 v[122:125], v[142:145], v[178:181], v[122:125]
	v_mfma_f32_16x16x32_bf16 v[110:113], v[134:137], v[186:189], v[110:113]
	v_mfma_f32_16x16x32_bf16 v[106:109], v[142:145], v[186:189], v[106:109]
	v_mfma_f32_16x16x32_bf16 v[94:97], v[134:137], v[194:197], v[94:97]
	v_mfma_f32_16x16x32_bf16 v[90:93], v[142:145], v[194:197], v[90:93]
	v_mfma_f32_16x16x32_bf16 v[78:81], v[134:137], v[202:205], v[78:81]
	v_mfma_f32_16x16x32_bf16 v[74:77], v[142:145], v[202:205], v[74:77]
	v_mfma_f32_16x16x32_bf16 v[118:121], v[206:209], v[166:169], v[118:121]
	v_mfma_f32_16x16x32_bf16 v[114:117], v[214:217], v[166:169], v[114:117]
	v_mfma_f32_16x16x32_bf16 v[102:105], v[206:209], v[182:185], v[102:105]
	v_mfma_f32_16x16x32_bf16 v[98:101], v[214:217], v[182:185], v[98:101]
	v_mfma_f32_16x16x32_bf16 v[86:89], v[206:209], v[190:193], v[86:89]
	v_mfma_f32_16x16x32_bf16 v[82:85], v[214:217], v[190:193], v[82:85]
	v_mfma_f32_16x16x32_bf16 v[70:73], v[206:209], v[198:201], v[70:73]
	v_mfma_f32_16x16x32_bf16 v[66:69], v[214:217], v[198:201], v[66:69]
	v_mfma_f32_16x16x32_bf16 v[118:121], v[210:213], v[178:181], v[118:121]
	v_mfma_f32_16x16x32_bf16 v[114:117], v[218:221], v[178:181], v[114:117]
	v_mfma_f32_16x16x32_bf16 v[102:105], v[210:213], v[186:189], v[102:105]
	v_mfma_f32_16x16x32_bf16 v[98:101], v[218:221], v[186:189], v[98:101]
	v_mfma_f32_16x16x32_bf16 v[86:89], v[210:213], v[194:197], v[86:89]
	v_mfma_f32_16x16x32_bf16 v[82:85], v[218:221], v[194:197], v[82:85]
	v_mfma_f32_16x16x32_bf16 v[70:73], v[210:213], v[202:205], v[70:73]
	v_mfma_f32_16x16x32_bf16 v[66:69], v[218:221], v[202:205], v[66:69]
	s_barrier
	s_setprio 0
	s_add_i32 s20, s54, s42
	v_lshl_add_u64 v[174:175], s[34:35], 0, v[150:151]
	s_mov_b32 m0, s20
	s_nop 0
	global_load_lds_dwordx4 v[174:175], off
	v_lshl_add_u64 v[222:223], s[34:35], 0, v[146:147]
	s_add_i32 m0, s20, 0x2000
	s_nop 0
	global_load_lds_dwordx4 v[222:223], off
	s_mov_b32 m0, s43
	v_lshl_add_u64 v[224:225], s[18:19], 0, v[152:153]
	ds_read_b128 v[166:169], v173 offset:16384
	ds_read_b128 v[178:181], v173 offset:17408
	ds_read_b128 v[182:185], v173 offset:18432
	ds_read_b128 v[186:189], v173 offset:19456
	ds_read_b128 v[190:193], v173 offset:20480
	ds_read_b128 v[194:197], v173 offset:21504
	ds_read_b128 v[198:201], v173 offset:22528
	ds_read_b128 v[202:205], v173 offset:23552
	global_load_lds_dwordx4 v[224:225], off
	v_lshl_add_u64 v[226:227], s[18:19], 0, v[148:149]
	s_mov_b32 m0, s44
	s_nop 0
	global_load_lds_dwordx4 v[226:227], off
	s_add_u32 s20, s34, 0x40000
	s_addc_u32 s21, s35, 0
	s_add_i32 s64, s55, s42
	v_lshl_add_u64 v[246:247], s[20:21], 0, v[150:151]
	s_mov_b32 m0, s64
	s_nop 0
	global_load_lds_dwordx4 v[246:247], off
	v_lshl_add_u64 v[246:247], s[20:21], 0, v[146:147]
	s_add_i32 m0, s64, 0x2000
	s_nop 0
	global_load_lds_dwordx4 v[246:247], off
	s_waitcnt vmcnt(8)
	s_waitcnt lgkmcnt(0)
	s_setprio 1
	s_barrier
	v_mfma_f32_16x16x32_bf16 v[62:65], v[130:133], v[166:169], v[62:65]
	v_mfma_f32_16x16x32_bf16 v[58:61], v[138:141], v[166:169], v[58:61]
	v_mfma_f32_16x16x32_bf16 v[46:49], v[130:133], v[182:185], v[46:49]
	v_mfma_f32_16x16x32_bf16 v[42:45], v[138:141], v[182:185], v[42:45]
	v_mfma_f32_16x16x32_bf16 v[30:33], v[130:133], v[190:193], v[30:33]
	v_mfma_f32_16x16x32_bf16 v[26:29], v[138:141], v[190:193], v[26:29]
	v_mfma_f32_16x16x32_bf16 v[14:17], v[130:133], v[198:201], v[14:17]
	v_mfma_f32_16x16x32_bf16 v[10:13], v[138:141], v[198:201], v[10:13]
	v_mfma_f32_16x16x32_bf16 v[62:65], v[134:137], v[178:181], v[62:65]
	v_mfma_f32_16x16x32_bf16 v[58:61], v[142:145], v[178:181], v[58:61]
	v_mfma_f32_16x16x32_bf16 v[46:49], v[134:137], v[186:189], v[46:49]
	v_mfma_f32_16x16x32_bf16 v[42:45], v[142:145], v[186:189], v[42:45]
	v_mfma_f32_16x16x32_bf16 v[30:33], v[134:137], v[194:197], v[30:33]
	v_mfma_f32_16x16x32_bf16 v[26:29], v[142:145], v[194:197], v[26:29]
	v_mfma_f32_16x16x32_bf16 v[14:17], v[134:137], v[202:205], v[14:17]
	v_mfma_f32_16x16x32_bf16 v[10:13], v[142:145], v[202:205], v[10:13]
	v_mfma_f32_16x16x32_bf16 v[54:57], v[206:209], v[166:169], v[54:57]
	v_mfma_f32_16x16x32_bf16 v[50:53], v[214:217], v[166:169], v[50:53]
	v_mfma_f32_16x16x32_bf16 v[38:41], v[206:209], v[182:185], v[38:41]
	v_mfma_f32_16x16x32_bf16 v[34:37], v[214:217], v[182:185], v[34:37]
	v_mfma_f32_16x16x32_bf16 v[22:25], v[206:209], v[190:193], v[22:25]
	v_mfma_f32_16x16x32_bf16 v[18:21], v[214:217], v[190:193], v[18:21]
	v_mfma_f32_16x16x32_bf16 v[6:9], v[206:209], v[198:201], v[6:9]
	v_mfma_f32_16x16x32_bf16 v[2:5], v[214:217], v[198:201], v[2:5]
	v_mfma_f32_16x16x32_bf16 v[54:57], v[210:213], v[178:181], v[54:57]
	v_mfma_f32_16x16x32_bf16 v[50:53], v[218:221], v[178:181], v[50:53]
	v_mfma_f32_16x16x32_bf16 v[38:41], v[210:213], v[186:189], v[38:41]
	v_mfma_f32_16x16x32_bf16 v[34:37], v[218:221], v[186:189], v[34:37]
	v_mfma_f32_16x16x32_bf16 v[22:25], v[210:213], v[194:197], v[22:25]
	v_mfma_f32_16x16x32_bf16 v[18:21], v[218:221], v[194:197], v[18:21]
	v_mfma_f32_16x16x32_bf16 v[6:9], v[210:213], v[202:205], v[6:9]
	v_mfma_f32_16x16x32_bf16 v[2:5], v[218:221], v[202:205], v[2:5]
	s_barrier
	s_setprio 0
	s_add_i32 s20, 0, 0x18000
	v_add_u32_e32 v142, s20, v157
	ds_read_b128 v[130:133], v142
	ds_read_b128 v[134:137], v142 offset:1024
	ds_read_b128 v[138:141], v142 offset:2048
	ds_read_b128 v[142:145], v142 offset:3072
	s_add_u32 s18, s18, 0x40000
	s_addc_u32 s19, s19, 0
	s_mov_b32 m0, s45
	v_lshl_add_u64 v[206:207], s[18:19], 0, v[152:153]
	ds_read_b128 v[166:169], v173 offset:32768
	ds_read_b128 v[178:181], v173 offset:33792
	ds_read_b128 v[182:185], v173 offset:34816
	ds_read_b128 v[186:189], v173 offset:35840
	ds_read_b128 v[190:193], v173 offset:36864
	ds_read_b128 v[194:197], v173 offset:37888
	ds_read_b128 v[198:201], v173 offset:38912
	ds_read_b128 v[202:205], v173 offset:39936
	global_load_lds_dwordx4 v[206:207], off
	v_lshl_add_u64 v[206:207], s[18:19], 0, v[148:149]
	s_mov_b32 m0, s46
	s_nop 0
	global_load_lds_dwordx4 v[206:207], off
	s_add_i32 s21, 0, 0x1c000
	v_add_u32_e32 v154, s21, v157
	ds_read_b128 v[206:209], v154
	ds_read_b128 v[210:213], v154 offset:1024
	ds_read_b128 v[214:217], v154 offset:2048
	ds_read_b128 v[218:221], v154 offset:3072
	s_waitcnt vmcnt(8)
	s_waitcnt lgkmcnt(0)
	s_setprio 1
	s_barrier
	v_mfma_f32_16x16x32_bf16 v[126:129], v[130:133], v[166:169], v[126:129]
	v_mfma_f32_16x16x32_bf16 v[122:125], v[138:141], v[166:169], v[122:125]
	v_mfma_f32_16x16x32_bf16 v[110:113], v[130:133], v[182:185], v[110:113]
	v_mfma_f32_16x16x32_bf16 v[106:109], v[138:141], v[182:185], v[106:109]
	v_mfma_f32_16x16x32_bf16 v[94:97], v[130:133], v[190:193], v[94:97]
	v_mfma_f32_16x16x32_bf16 v[90:93], v[138:141], v[190:193], v[90:93]
	v_mfma_f32_16x16x32_bf16 v[78:81], v[130:133], v[198:201], v[78:81]
	v_mfma_f32_16x16x32_bf16 v[74:77], v[138:141], v[198:201], v[74:77]
	v_mfma_f32_16x16x32_bf16 v[126:129], v[134:137], v[178:181], v[126:129]
	v_mfma_f32_16x16x32_bf16 v[122:125], v[142:145], v[178:181], v[122:125]
	v_mfma_f32_16x16x32_bf16 v[110:113], v[134:137], v[186:189], v[110:113]
	v_mfma_f32_16x16x32_bf16 v[106:109], v[142:145], v[186:189], v[106:109]
	v_mfma_f32_16x16x32_bf16 v[94:97], v[134:137], v[194:197], v[94:97]
	v_mfma_f32_16x16x32_bf16 v[90:93], v[142:145], v[194:197], v[90:93]
	v_mfma_f32_16x16x32_bf16 v[78:81], v[134:137], v[202:205], v[78:81]
	v_mfma_f32_16x16x32_bf16 v[74:77], v[142:145], v[202:205], v[74:77]
	v_mfma_f32_16x16x32_bf16 v[118:121], v[206:209], v[166:169], v[118:121]
	v_mfma_f32_16x16x32_bf16 v[114:117], v[214:217], v[166:169], v[114:117]
	v_mfma_f32_16x16x32_bf16 v[102:105], v[206:209], v[182:185], v[102:105]
	v_mfma_f32_16x16x32_bf16 v[98:101], v[214:217], v[182:185], v[98:101]
	v_mfma_f32_16x16x32_bf16 v[86:89], v[206:209], v[190:193], v[86:89]
	v_mfma_f32_16x16x32_bf16 v[82:85], v[214:217], v[190:193], v[82:85]
	v_mfma_f32_16x16x32_bf16 v[70:73], v[206:209], v[198:201], v[70:73]
	v_mfma_f32_16x16x32_bf16 v[66:69], v[214:217], v[198:201], v[66:69]
	v_mfma_f32_16x16x32_bf16 v[118:121], v[210:213], v[178:181], v[118:121]
	v_mfma_f32_16x16x32_bf16 v[114:117], v[218:221], v[178:181], v[114:117]
	v_mfma_f32_16x16x32_bf16 v[102:105], v[210:213], v[186:189], v[102:105]
	v_mfma_f32_16x16x32_bf16 v[98:101], v[218:221], v[186:189], v[98:101]
	v_mfma_f32_16x16x32_bf16 v[86:89], v[210:213], v[194:197], v[86:89]
	v_mfma_f32_16x16x32_bf16 v[82:85], v[218:221], v[194:197], v[82:85]
	v_mfma_f32_16x16x32_bf16 v[70:73], v[210:213], v[202:205], v[70:73]
	v_mfma_f32_16x16x32_bf16 v[66:69], v[218:221], v[202:205], v[66:69]
	s_barrier
	s_setprio 0
	s_add_i32 s18, s20, s42
	v_lshl_add_u64 v[174:175], v[174:175], 0, s[6:7]
	s_mov_b32 m0, s18
	s_nop 0
	global_load_lds_dwordx4 v[174:175], off
	v_lshl_add_u64 v[174:175], v[222:223], 0, s[6:7]
	s_add_i32 m0, s18, 0x2000
	s_nop 0
	global_load_lds_dwordx4 v[174:175], off
	s_mov_b32 m0, s50
	v_lshl_add_u64 v[174:175], v[224:225], 0, s[6:7]
	ds_read_b128 v[166:169], v173 offset:49152
	ds_read_b128 v[178:181], v173 offset:50176
	ds_read_b128 v[182:185], v173 offset:51200
	ds_read_b128 v[186:189], v173 offset:52224
	ds_read_b128 v[190:193], v173 offset:53248
	ds_read_b128 v[194:197], v173 offset:54272
	ds_read_b128 v[198:201], v173 offset:55296
	ds_read_b128 v[202:205], v173 offset:56320
	global_load_lds_dwordx4 v[174:175], off
	v_lshl_add_u64 v[174:175], v[226:227], 0, s[6:7]
	s_mov_b32 m0, s51
	s_nop 0
	global_load_lds_dwordx4 v[174:175], off
	s_add_u32 s18, s34, 0x40080
	s_addc_u32 s19, s35, 0
	s_add_i32 s20, s21, s42
	v_lshl_add_u64 v[248:249], s[18:19], 0, v[150:151]
	s_mov_b32 m0, s20
	s_nop 0
	global_load_lds_dwordx4 v[248:249], off
	v_lshl_add_u64 v[248:249], s[18:19], 0, v[146:147]
	s_add_i32 m0, s20, 0x2000
	s_nop 0
	global_load_lds_dwordx4 v[248:249], off
	s_waitcnt vmcnt(8)
	s_waitcnt lgkmcnt(0)
	s_setprio 1
	s_barrier
	v_mfma_f32_16x16x32_bf16 v[62:65], v[130:133], v[166:169], v[62:65]
	v_mfma_f32_16x16x32_bf16 v[58:61], v[138:141], v[166:169], v[58:61]
	v_mfma_f32_16x16x32_bf16 v[46:49], v[130:133], v[182:185], v[46:49]
	v_mfma_f32_16x16x32_bf16 v[42:45], v[138:141], v[182:185], v[42:45]
	v_mfma_f32_16x16x32_bf16 v[30:33], v[130:133], v[190:193], v[30:33]
	v_mfma_f32_16x16x32_bf16 v[26:29], v[138:141], v[190:193], v[26:29]
	v_mfma_f32_16x16x32_bf16 v[14:17], v[130:133], v[198:201], v[14:17]
	v_mfma_f32_16x16x32_bf16 v[10:13], v[138:141], v[198:201], v[10:13]
	v_mfma_f32_16x16x32_bf16 v[62:65], v[134:137], v[178:181], v[62:65]
	v_mfma_f32_16x16x32_bf16 v[58:61], v[142:145], v[178:181], v[58:61]
	v_mfma_f32_16x16x32_bf16 v[46:49], v[134:137], v[186:189], v[46:49]
	v_mfma_f32_16x16x32_bf16 v[42:45], v[142:145], v[186:189], v[42:45]
	v_mfma_f32_16x16x32_bf16 v[30:33], v[134:137], v[194:197], v[30:33]
	v_mfma_f32_16x16x32_bf16 v[26:29], v[142:145], v[194:197], v[26:29]
	v_mfma_f32_16x16x32_bf16 v[14:17], v[134:137], v[202:205], v[14:17]
	v_mfma_f32_16x16x32_bf16 v[10:13], v[142:145], v[202:205], v[10:13]
	v_mfma_f32_16x16x32_bf16 v[54:57], v[206:209], v[166:169], v[54:57]
	v_mfma_f32_16x16x32_bf16 v[50:53], v[214:217], v[166:169], v[50:53]
	v_mfma_f32_16x16x32_bf16 v[38:41], v[206:209], v[182:185], v[38:41]
	v_mfma_f32_16x16x32_bf16 v[34:37], v[214:217], v[182:185], v[34:37]
	v_mfma_f32_16x16x32_bf16 v[22:25], v[206:209], v[190:193], v[22:25]
	v_mfma_f32_16x16x32_bf16 v[18:21], v[214:217], v[190:193], v[18:21]
	v_mfma_f32_16x16x32_bf16 v[6:9], v[206:209], v[198:201], v[6:9]
	v_mfma_f32_16x16x32_bf16 v[2:5], v[214:217], v[198:201], v[2:5]
	v_mfma_f32_16x16x32_bf16 v[54:57], v[210:213], v[178:181], v[54:57]
	v_mfma_f32_16x16x32_bf16 v[50:53], v[218:221], v[178:181], v[50:53]
	v_mfma_f32_16x16x32_bf16 v[38:41], v[210:213], v[186:189], v[38:41]
	v_mfma_f32_16x16x32_bf16 v[34:37], v[218:221], v[186:189], v[34:37]
	v_mfma_f32_16x16x32_bf16 v[22:25], v[210:213], v[194:197], v[22:25]
	v_mfma_f32_16x16x32_bf16 v[18:21], v[218:221], v[194:197], v[18:21]
	v_mfma_f32_16x16x32_bf16 v[6:9], v[210:213], v[202:205], v[6:9]
	v_mfma_f32_16x16x32_bf16 v[2:5], v[218:221], v[202:205], v[2:5]
	s_barrier
	s_setprio 0
	s_add_i32 s63, s63, 2
	s_add_u32 s24, s24, 0x100
	s_addc_u32 s25, s25, 0
	s_add_u32 s61, s61, 0x100
	s_addc_u32 s62, s62, 0
	s_cmp_gt_u32 s63, 13
	s_cbranch_scc0 .LBB0_3265
	s_ashr_i32 s9, s16, 3
	s_mul_hi_i32 s11, s9, 0x5800
	s_mulk_i32 s9, 0x5800
	s_add_u32 s9, s48, s9
	s_addc_u32 s11, s49, s11
	s_lshl_b32 s18, s17, 8
	s_ashr_i32 s19, s18, 31
	s_lshl_b64 s[18:19], s[18:19], 2
	v_lshl_add_u32 v180, s16, 8, v1
	s_add_u32 s18, s9, s18
	s_addc_u32 s19, s11, s19
	v_lshlrev_b32_e32 v130, 2, v156
	v_ashrrev_i32_e32 v181, 31, v180
	global_load_dwordx4 v[142:145], v130, s[18:19]
	v_lshl_add_u64 v[182:183], v[180:181], 2, s[4:5]
	global_load_dword v190, v[182:183], off
	global_load_dwordx4 v[138:141], v130, s[18:19] offset:512
	global_load_dwordx4 v[134:137], v130, s[18:19] offset:16
	s_nop 0
	global_load_dwordx4 v[130:133], v130, s[18:19] offset:528
	v_or_b32_e32 v192, 16, v180
	v_ashrrev_i32_e32 v193, 31, v192
	v_lshl_add_u64 v[168:169], v[192:193], 2, s[4:5]
	global_load_dword v194, v[168:169], off
	v_or_b32_e32 v188, 32, v180
	v_or_b32_e32 v184, 48, v180
	v_mov_b64_e32 v[166:167], s[0:1]
	v_add_u32_e32 v178, 0x90, v180
	v_add_u32_e32 v174, 0xa0, v180
	v_add_u32_e32 v168, 0xb0, v180
	v_ashrrev_i32_e32 v189, 31, v188
	v_ashrrev_i32_e32 v185, 31, v184
	v_add_u32_e32 v193, 0x80, v180
	v_mad_i64_i32 v[196:197], s[18:19], v180, s56, v[166:167]
	v_ashrrev_i32_e32 v179, 31, v178
	v_ashrrev_i32_e32 v175, 31, v174
	v_ashrrev_i32_e32 v169, 31, v168
	v_lshl_add_u64 v[180:181], v[188:189], 2, s[4:5]
	v_lshl_add_u64 v[186:187], v[184:185], 2, s[4:5]
	v_lshl_add_u64 v[198:199], v[178:179], 2, s[4:5]
	v_lshl_add_u64 v[200:201], v[174:175], 2, s[4:5]
	v_lshl_add_u64 v[202:203], v[168:169], 2, s[4:5]
	global_load_dword v204, v[180:181], off
	s_nop 0
	global_load_dword v186, v[186:187], off
	s_nop 0
	global_load_dword v180, v[198:199], off
	global_load_dword v176, v[200:201], off
	global_load_dword v172, v[202:203], off
	s_nop 0
	global_load_dword v182, v[182:183], off offset:512
	s_lshl_b32 s16, s17, 7
	s_ashr_i32 s17, s16, 31
	s_lshl_b64 s[16:17], s[16:17], 1
	v_lshlrev_b32_e32 v154, 1, v156
	v_lshl_add_u64 v[196:197], v[196:197], 0, s[16:17]
	s_and_b64 vcc, exec, s[2:3]
	s_mov_b64 s[34:35], s[14:15]
	s_mov_b64 s[24:25], s[12:13]
	s_waitcnt vmcnt(0)
	v_pk_fma_f32 v[118:119], v[118:119], v[190:191], v[138:139] op_sel_hi:[1,0,1]
	v_pk_fma_f32 v[126:127], v[126:127], v[190:191], v[142:143] op_sel_hi:[1,0,1]
	v_pk_fma_f32 v[128:129], v[128:129], v[190:191], v[144:145] op_sel_hi:[1,0,1]
	v_pk_fma_f32 v[122:123], v[122:123], v[190:191], v[134:135] op_sel_hi:[1,0,1]
	v_pk_fma_f32 v[124:125], v[124:125], v[190:191], v[136:137] op_sel_hi:[1,0,1]
	v_mul_f32_e32 v169, 0xbfb8aa3b, v126
	v_mul_f32_e32 v175, 0xbfb8aa3b, v127
	v_mul_f32_e32 v179, 0xbfb8aa3b, v128
	v_mul_f32_e32 v181, 0xbfb8aa3b, v129
	v_mul_f32_e32 v183, 0xbfb8aa3b, v122
	v_mul_f32_e32 v185, 0xbfb8aa3b, v123
	v_mul_f32_e32 v187, 0xbfb8aa3b, v124
	v_mul_f32_e32 v189, 0xbfb8aa3b, v125
	v_exp_f32_e32 v169, v169
	v_exp_f32_e32 v175, v175
	v_exp_f32_e32 v179, v179
	v_exp_f32_e32 v181, v181
	v_exp_f32_e32 v183, v183
	v_exp_f32_e32 v185, v185
	v_exp_f32_e32 v187, v187
	v_exp_f32_e32 v189, v189
	v_add_f32_e32 v169, 1.0, v169
	v_add_f32_e32 v175, 1.0, v175
	v_add_f32_e32 v179, 1.0, v179
	v_add_f32_e32 v181, 1.0, v181
	v_add_f32_e32 v183, 1.0, v183
	v_add_f32_e32 v185, 1.0, v185
	v_add_f32_e32 v187, 1.0, v187
	v_add_f32_e32 v189, 1.0, v189
	v_pk_fma_f32 v[120:121], v[120:121], v[190:191], v[140:141] op_sel_hi:[1,0,1]
	v_pk_fma_f32 v[114:115], v[114:115], v[190:191], v[130:131] op_sel_hi:[1,0,1]
	v_pk_fma_f32 v[116:117], v[116:117], v[190:191], v[132:133] op_sel_hi:[1,0,1]
	v_rcp_f32_e32 v190, v169
	v_rcp_f32_e32 v191, v175
	v_rcp_f32_e32 v198, v179
	v_rcp_f32_e32 v199, v181
	v_rcp_f32_e32 v200, v183
	v_rcp_f32_e32 v201, v185
	v_rcp_f32_e32 v202, v187
	v_rcp_f32_e32 v203, v189
	v_pk_mul_f32 v[126:127], v[126:127], v[190:191]
	v_pk_mul_f32 v[128:129], v[128:129], v[198:199]
	v_pk_mul_f32 v[122:123], v[122:123], v[200:201]
	v_pk_mul_f32 v[124:125], v[124:125], v[202:203]
	v_pk_mul_f32 v[118:119], v[118:119], v[126:127]
	v_pk_mul_f32 v[120:121], v[120:121], v[128:129]
	v_pk_mul_f32 v[122:123], v[114:115], v[122:123]
	v_pk_mul_f32 v[124:125], v[116:117], v[124:125]
	v_pk_fma_f32 v[110:111], v[110:111], v[194:195], v[142:143] op_sel_hi:[1,0,1]
	v_lshl_add_u64 v[126:127], v[196:197], 0, v[154:155]
	v_cvt_pk_bf16_f32 v114, v118, v119
	v_cvt_pk_bf16_f32 v115, v120, v121
	v_cvt_pk_bf16_f32 v116, v122, v123
	v_cvt_pk_bf16_f32 v117, v124, v125
	v_mul_f32_e32 v118, 0xbfb8aa3b, v110
	v_mul_f32_e32 v119, 0xbfb8aa3b, v111
	v_pk_fma_f32 v[112:113], v[112:113], v[194:195], v[144:145] op_sel_hi:[1,0,1]
	v_exp_f32_e32 v118, v118
	v_exp_f32_e32 v119, v119
	global_store_dwordx4 v[126:127], v[114:117], off nt
	v_pk_fma_f32 v[102:103], v[102:103], v[194:195], v[138:139] op_sel_hi:[1,0,1]
	v_pk_fma_f32 v[106:107], v[106:107], v[194:195], v[134:135] op_sel_hi:[1,0,1]
	v_mul_f32_e32 v116, 0xbfb8aa3b, v112
	v_mul_f32_e32 v117, 0xbfb8aa3b, v113
	v_exp_f32_e32 v116, v116
	v_exp_f32_e32 v117, v117
	v_add_f32_e32 v114, 1.0, v118
	v_add_f32_e32 v115, 1.0, v119
	v_rcp_f32_e32 v114, v114
	v_rcp_f32_e32 v115, v115
	v_add_f32_e32 v116, 1.0, v116
	v_add_f32_e32 v117, 1.0, v117
	v_rcp_f32_e32 v116, v116
	v_rcp_f32_e32 v117, v117
	v_pk_mul_f32 v[110:111], v[110:111], v[114:115]
	v_pk_fma_f32 v[104:105], v[104:105], v[194:195], v[140:141] op_sel_hi:[1,0,1]
	v_pk_mul_f32 v[102:103], v[102:103], v[110:111]
	v_pk_mul_f32 v[110:111], v[112:113], v[116:117]
	v_mul_f32_e32 v112, 0xbfb8aa3b, v106
	v_mul_f32_e32 v113, 0xbfb8aa3b, v107
	v_exp_f32_e32 v112, v112
	v_exp_f32_e32 v113, v113
	v_pk_fma_f32 v[108:109], v[108:109], v[194:195], v[136:137] op_sel_hi:[1,0,1]
	v_pk_mul_f32 v[104:105], v[104:105], v[110:111]
	v_add_f32_e32 v110, 1.0, v112
	v_add_f32_e32 v111, 1.0, v113
	v_mul_f32_e32 v112, 0xbfb8aa3b, v108
	v_mul_f32_e32 v113, 0xbfb8aa3b, v109
	v_exp_f32_e32 v112, v112
	v_exp_f32_e32 v113, v113
	v_rcp_f32_e32 v110, v110
	v_rcp_f32_e32 v111, v111
	v_add_f32_e32 v112, 1.0, v112
	v_add_f32_e32 v113, 1.0, v113
	v_rcp_f32_e32 v112, v112
	v_rcp_f32_e32 v113, v113
	v_pk_mul_f32 v[106:107], v[106:107], v[110:111]
	v_pk_fma_f32 v[98:99], v[98:99], v[194:195], v[130:131] op_sel_hi:[1,0,1]
	v_pk_fma_f32 v[100:101], v[100:101], v[194:195], v[132:133] op_sel_hi:[1,0,1]
	v_pk_mul_f32 v[106:107], v[98:99], v[106:107]
	v_pk_mul_f32 v[98:99], v[108:109], v[112:113]
	v_pk_fma_f32 v[94:95], v[94:95], v[204:205], v[142:143] op_sel_hi:[1,0,1]
	v_pk_mul_f32 v[108:109], v[100:101], v[98:99]
	v_mad_i64_i32 v[98:99], s[18:19], v192, s56, v[166:167]
	v_lshl_add_u64 v[98:99], v[98:99], 0, s[16:17]
	v_lshl_add_u64 v[110:111], v[98:99], 0, v[154:155]
	v_cvt_pk_bf16_f32 v98, v102, v103
	v_cvt_pk_bf16_f32 v99, v104, v105
	v_cvt_pk_bf16_f32 v100, v106, v107
	v_cvt_pk_bf16_f32 v101, v108, v109
	v_mul_f32_e32 v102, 0xbfb8aa3b, v94
	v_mul_f32_e32 v103, 0xbfb8aa3b, v95
	v_pk_fma_f32 v[96:97], v[96:97], v[204:205], v[144:145] op_sel_hi:[1,0,1]
	v_exp_f32_e32 v102, v102
	v_exp_f32_e32 v103, v103
	global_store_dwordx4 v[110:111], v[98:101], off nt
	v_pk_fma_f32 v[86:87], v[86:87], v[204:205], v[138:139] op_sel_hi:[1,0,1]
	v_pk_fma_f32 v[90:91], v[90:91], v[204:205], v[134:135] op_sel_hi:[1,0,1]
	v_mul_f32_e32 v100, 0xbfb8aa3b, v96
	v_mul_f32_e32 v101, 0xbfb8aa3b, v97
	v_exp_f32_e32 v100, v100
	v_exp_f32_e32 v101, v101
	v_add_f32_e32 v98, 1.0, v102
	v_add_f32_e32 v99, 1.0, v103
	v_rcp_f32_e32 v98, v98
	v_rcp_f32_e32 v99, v99
	v_add_f32_e32 v100, 1.0, v100
	v_add_f32_e32 v101, 1.0, v101
	v_rcp_f32_e32 v100, v100
	v_rcp_f32_e32 v101, v101
	v_pk_mul_f32 v[94:95], v[94:95], v[98:99]
	v_pk_fma_f32 v[88:89], v[88:89], v[204:205], v[140:141] op_sel_hi:[1,0,1]
	v_pk_mul_f32 v[86:87], v[86:87], v[94:95]
	v_pk_mul_f32 v[94:95], v[96:97], v[100:101]
	v_mul_f32_e32 v96, 0xbfb8aa3b, v90
	v_mul_f32_e32 v97, 0xbfb8aa3b, v91
	v_exp_f32_e32 v96, v96
	v_exp_f32_e32 v97, v97
	v_pk_fma_f32 v[92:93], v[92:93], v[204:205], v[136:137] op_sel_hi:[1,0,1]
	v_pk_mul_f32 v[88:89], v[88:89], v[94:95]
	v_add_f32_e32 v94, 1.0, v96
	v_add_f32_e32 v95, 1.0, v97
	v_mul_f32_e32 v96, 0xbfb8aa3b, v92
	v_mul_f32_e32 v97, 0xbfb8aa3b, v93
	v_exp_f32_e32 v96, v96
	v_exp_f32_e32 v97, v97
	v_rcp_f32_e32 v94, v94
	v_rcp_f32_e32 v95, v95
	v_add_f32_e32 v96, 1.0, v96
	v_add_f32_e32 v97, 1.0, v97
	v_rcp_f32_e32 v96, v96
	v_rcp_f32_e32 v97, v97
	v_pk_mul_f32 v[90:91], v[90:91], v[94:95]
	v_pk_fma_f32 v[82:83], v[82:83], v[204:205], v[130:131] op_sel_hi:[1,0,1]
	v_pk_fma_f32 v[84:85], v[84:85], v[204:205], v[132:133] op_sel_hi:[1,0,1]
	v_pk_mul_f32 v[90:91], v[82:83], v[90:91]
	v_pk_mul_f32 v[82:83], v[92:93], v[96:97]
	v_pk_fma_f32 v[78:79], v[78:79], v[186:187], v[142:143] op_sel_hi:[1,0,1]
	v_pk_mul_f32 v[92:93], v[84:85], v[82:83]
	v_mad_i64_i32 v[82:83], s[18:19], v188, s56, v[166:167]
	v_lshl_add_u64 v[82:83], v[82:83], 0, s[16:17]
	v_lshl_add_u64 v[94:95], v[82:83], 0, v[154:155]
	v_cvt_pk_bf16_f32 v82, v86, v87
	v_cvt_pk_bf16_f32 v83, v88, v89
	v_cvt_pk_bf16_f32 v84, v90, v91
	v_cvt_pk_bf16_f32 v85, v92, v93
	v_mul_f32_e32 v86, 0xbfb8aa3b, v78
	v_mul_f32_e32 v87, 0xbfb8aa3b, v79
	v_pk_fma_f32 v[80:81], v[80:81], v[186:187], v[144:145] op_sel_hi:[1,0,1]
	v_exp_f32_e32 v86, v86
	v_exp_f32_e32 v87, v87
	global_store_dwordx4 v[94:95], v[82:85], off nt
	v_pk_fma_f32 v[70:71], v[70:71], v[186:187], v[138:139] op_sel_hi:[1,0,1]
	v_pk_fma_f32 v[74:75], v[74:75], v[186:187], v[134:135] op_sel_hi:[1,0,1]
	v_mul_f32_e32 v84, 0xbfb8aa3b, v80
	v_mul_f32_e32 v85, 0xbfb8aa3b, v81
	v_exp_f32_e32 v84, v84
	v_exp_f32_e32 v85, v85
	v_add_f32_e32 v82, 1.0, v86
	v_add_f32_e32 v83, 1.0, v87
	v_rcp_f32_e32 v82, v82
	v_rcp_f32_e32 v83, v83
	v_add_f32_e32 v84, 1.0, v84
	v_add_f32_e32 v85, 1.0, v85
	v_rcp_f32_e32 v84, v84
	v_rcp_f32_e32 v85, v85
	v_pk_mul_f32 v[78:79], v[78:79], v[82:83]
	v_pk_fma_f32 v[72:73], v[72:73], v[186:187], v[140:141] op_sel_hi:[1,0,1]
	v_pk_mul_f32 v[70:71], v[70:71], v[78:79]
	v_pk_mul_f32 v[78:79], v[80:81], v[84:85]
	v_mul_f32_e32 v80, 0xbfb8aa3b, v74
	v_mul_f32_e32 v81, 0xbfb8aa3b, v75
	v_exp_f32_e32 v80, v80
	v_exp_f32_e32 v81, v81
	v_pk_fma_f32 v[76:77], v[76:77], v[186:187], v[136:137] op_sel_hi:[1,0,1]
	v_pk_mul_f32 v[72:73], v[72:73], v[78:79]
	v_add_f32_e32 v78, 1.0, v80
	v_add_f32_e32 v79, 1.0, v81
	v_mul_f32_e32 v80, 0xbfb8aa3b, v76
	v_mul_f32_e32 v81, 0xbfb8aa3b, v77
	v_exp_f32_e32 v80, v80
	v_exp_f32_e32 v81, v81
	v_rcp_f32_e32 v78, v78
	v_rcp_f32_e32 v79, v79
	v_add_f32_e32 v80, 1.0, v80
	v_add_f32_e32 v81, 1.0, v81
	v_rcp_f32_e32 v80, v80
	v_rcp_f32_e32 v81, v81
	v_pk_mul_f32 v[74:75], v[74:75], v[78:79]
	v_pk_fma_f32 v[66:67], v[66:67], v[186:187], v[130:131] op_sel_hi:[1,0,1]
	v_pk_fma_f32 v[68:69], v[68:69], v[186:187], v[132:133] op_sel_hi:[1,0,1]
	v_pk_mul_f32 v[74:75], v[66:67], v[74:75]
	v_pk_mul_f32 v[66:67], v[76:77], v[80:81]
	v_pk_fma_f32 v[62:63], v[62:63], v[182:183], v[142:143] op_sel_hi:[1,0,1]
	v_pk_mul_f32 v[76:77], v[68:69], v[66:67]
	v_mad_i64_i32 v[66:67], s[18:19], v184, s56, v[166:167]
	v_lshl_add_u64 v[66:67], v[66:67], 0, s[16:17]
	v_lshl_add_u64 v[78:79], v[66:67], 0, v[154:155]
	v_cvt_pk_bf16_f32 v66, v70, v71
	v_cvt_pk_bf16_f32 v67, v72, v73
	v_cvt_pk_bf16_f32 v68, v74, v75
	v_cvt_pk_bf16_f32 v69, v76, v77
	v_mul_f32_e32 v70, 0xbfb8aa3b, v62
	v_mul_f32_e32 v71, 0xbfb8aa3b, v63
	v_pk_fma_f32 v[64:65], v[64:65], v[182:183], v[144:145] op_sel_hi:[1,0,1]
	v_exp_f32_e32 v70, v70
	v_exp_f32_e32 v71, v71
	global_store_dwordx4 v[78:79], v[66:69], off nt
	v_pk_fma_f32 v[54:55], v[54:55], v[182:183], v[138:139] op_sel_hi:[1,0,1]
	v_pk_fma_f32 v[58:59], v[58:59], v[182:183], v[134:135] op_sel_hi:[1,0,1]
	v_mul_f32_e32 v68, 0xbfb8aa3b, v64
	v_mul_f32_e32 v69, 0xbfb8aa3b, v65
	v_exp_f32_e32 v68, v68
	v_exp_f32_e32 v69, v69
	v_add_f32_e32 v66, 1.0, v70
	v_add_f32_e32 v67, 1.0, v71
	v_rcp_f32_e32 v66, v66
	v_rcp_f32_e32 v67, v67
	v_add_f32_e32 v68, 1.0, v68
	v_add_f32_e32 v69, 1.0, v69
	v_rcp_f32_e32 v68, v68
	v_rcp_f32_e32 v69, v69
	v_pk_mul_f32 v[62:63], v[62:63], v[66:67]
	v_pk_fma_f32 v[56:57], v[56:57], v[182:183], v[140:141] op_sel_hi:[1,0,1]
	v_pk_mul_f32 v[54:55], v[54:55], v[62:63]
	v_pk_mul_f32 v[62:63], v[64:65], v[68:69]
	v_mul_f32_e32 v64, 0xbfb8aa3b, v58
	v_mul_f32_e32 v65, 0xbfb8aa3b, v59
	v_exp_f32_e32 v64, v64
	v_exp_f32_e32 v65, v65
	v_pk_fma_f32 v[60:61], v[60:61], v[182:183], v[136:137] op_sel_hi:[1,0,1]
	v_pk_mul_f32 v[56:57], v[56:57], v[62:63]
	v_add_f32_e32 v62, 1.0, v64
	v_add_f32_e32 v63, 1.0, v65
	v_mul_f32_e32 v64, 0xbfb8aa3b, v60
	v_mul_f32_e32 v65, 0xbfb8aa3b, v61
	v_exp_f32_e32 v64, v64
	v_exp_f32_e32 v65, v65
	v_rcp_f32_e32 v62, v62
	v_rcp_f32_e32 v63, v63
	v_add_f32_e32 v64, 1.0, v64
	v_add_f32_e32 v65, 1.0, v65
	v_rcp_f32_e32 v64, v64
	v_rcp_f32_e32 v65, v65
	v_pk_mul_f32 v[58:59], v[58:59], v[62:63]
	v_pk_fma_f32 v[50:51], v[50:51], v[182:183], v[130:131] op_sel_hi:[1,0,1]
	v_pk_fma_f32 v[52:53], v[52:53], v[182:183], v[132:133] op_sel_hi:[1,0,1]
	v_pk_mul_f32 v[58:59], v[50:51], v[58:59]
	v_pk_mul_f32 v[50:51], v[60:61], v[64:65]
	v_pk_fma_f32 v[46:47], v[46:47], v[180:181], v[142:143] op_sel_hi:[1,0,1]
	v_pk_mul_f32 v[60:61], v[52:53], v[50:51]
	v_mad_i64_i32 v[50:51], s[18:19], v193, s56, v[166:167]
	v_lshl_add_u64 v[50:51], v[50:51], 0, s[16:17]
	v_lshl_add_u64 v[62:63], v[50:51], 0, v[154:155]
	v_cvt_pk_bf16_f32 v50, v54, v55
	v_cvt_pk_bf16_f32 v51, v56, v57
	v_cvt_pk_bf16_f32 v52, v58, v59
	v_cvt_pk_bf16_f32 v53, v60, v61
	v_mul_f32_e32 v54, 0xbfb8aa3b, v46
	v_mul_f32_e32 v55, 0xbfb8aa3b, v47
	v_pk_fma_f32 v[48:49], v[48:49], v[180:181], v[144:145] op_sel_hi:[1,0,1]
	v_exp_f32_e32 v54, v54
	v_exp_f32_e32 v55, v55
	global_store_dwordx4 v[62:63], v[50:53], off nt
	v_pk_fma_f32 v[38:39], v[38:39], v[180:181], v[138:139] op_sel_hi:[1,0,1]
	v_pk_fma_f32 v[42:43], v[42:43], v[180:181], v[134:135] op_sel_hi:[1,0,1]
	v_mul_f32_e32 v52, 0xbfb8aa3b, v48
	v_mul_f32_e32 v53, 0xbfb8aa3b, v49
	v_exp_f32_e32 v52, v52
	v_exp_f32_e32 v53, v53
	v_add_f32_e32 v50, 1.0, v54
	v_add_f32_e32 v51, 1.0, v55
	v_rcp_f32_e32 v50, v50
	v_rcp_f32_e32 v51, v51
	v_add_f32_e32 v52, 1.0, v52
	v_add_f32_e32 v53, 1.0, v53
	v_rcp_f32_e32 v52, v52
	v_rcp_f32_e32 v53, v53
	v_pk_mul_f32 v[46:47], v[46:47], v[50:51]
	v_pk_fma_f32 v[40:41], v[40:41], v[180:181], v[140:141] op_sel_hi:[1,0,1]
	v_pk_mul_f32 v[38:39], v[38:39], v[46:47]
	v_pk_mul_f32 v[46:47], v[48:49], v[52:53]
	v_mul_f32_e32 v48, 0xbfb8aa3b, v42
	v_mul_f32_e32 v49, 0xbfb8aa3b, v43
	v_exp_f32_e32 v48, v48
	v_exp_f32_e32 v49, v49
	v_pk_fma_f32 v[44:45], v[44:45], v[180:181], v[136:137] op_sel_hi:[1,0,1]
	v_pk_mul_f32 v[40:41], v[40:41], v[46:47]
	v_add_f32_e32 v46, 1.0, v48
	v_add_f32_e32 v47, 1.0, v49
	v_mul_f32_e32 v48, 0xbfb8aa3b, v44
	v_mul_f32_e32 v49, 0xbfb8aa3b, v45
	v_exp_f32_e32 v48, v48
	v_exp_f32_e32 v49, v49
	v_rcp_f32_e32 v46, v46
	v_rcp_f32_e32 v47, v47
	v_add_f32_e32 v48, 1.0, v48
	v_add_f32_e32 v49, 1.0, v49
	v_rcp_f32_e32 v48, v48
	v_rcp_f32_e32 v49, v49
	v_pk_mul_f32 v[42:43], v[42:43], v[46:47]
	v_pk_fma_f32 v[34:35], v[34:35], v[180:181], v[130:131] op_sel_hi:[1,0,1]
	v_pk_fma_f32 v[36:37], v[36:37], v[180:181], v[132:133] op_sel_hi:[1,0,1]
	v_pk_mul_f32 v[42:43], v[34:35], v[42:43]
	v_pk_mul_f32 v[34:35], v[44:45], v[48:49]
	v_pk_fma_f32 v[30:31], v[30:31], v[176:177], v[142:143] op_sel_hi:[1,0,1]
	v_pk_mul_f32 v[44:45], v[36:37], v[34:35]
	v_mad_i64_i32 v[34:35], s[18:19], v178, s56, v[166:167]
	v_lshl_add_u64 v[34:35], v[34:35], 0, s[16:17]
	v_lshl_add_u64 v[46:47], v[34:35], 0, v[154:155]
	v_cvt_pk_bf16_f32 v34, v38, v39
	v_cvt_pk_bf16_f32 v35, v40, v41
	v_cvt_pk_bf16_f32 v36, v42, v43
	v_cvt_pk_bf16_f32 v37, v44, v45
	v_mul_f32_e32 v38, 0xbfb8aa3b, v30
	v_mul_f32_e32 v39, 0xbfb8aa3b, v31
	v_pk_fma_f32 v[32:33], v[32:33], v[176:177], v[144:145] op_sel_hi:[1,0,1]
	v_exp_f32_e32 v38, v38
	v_exp_f32_e32 v39, v39
	global_store_dwordx4 v[46:47], v[34:37], off nt
	v_pk_fma_f32 v[22:23], v[22:23], v[176:177], v[138:139] op_sel_hi:[1,0,1]
	v_pk_fma_f32 v[26:27], v[26:27], v[176:177], v[134:135] op_sel_hi:[1,0,1]
	v_mul_f32_e32 v36, 0xbfb8aa3b, v32
	v_mul_f32_e32 v37, 0xbfb8aa3b, v33
	v_exp_f32_e32 v36, v36
	v_exp_f32_e32 v37, v37
	v_add_f32_e32 v34, 1.0, v38
	v_add_f32_e32 v35, 1.0, v39
	v_rcp_f32_e32 v34, v34
	v_rcp_f32_e32 v35, v35
	v_add_f32_e32 v36, 1.0, v36
	v_add_f32_e32 v37, 1.0, v37
	v_rcp_f32_e32 v36, v36
	v_rcp_f32_e32 v37, v37
	v_pk_mul_f32 v[30:31], v[30:31], v[34:35]
	v_pk_fma_f32 v[24:25], v[24:25], v[176:177], v[140:141] op_sel_hi:[1,0,1]
	v_pk_mul_f32 v[22:23], v[22:23], v[30:31]
	v_pk_mul_f32 v[30:31], v[32:33], v[36:37]
	v_mul_f32_e32 v32, 0xbfb8aa3b, v26
	v_mul_f32_e32 v33, 0xbfb8aa3b, v27
	v_exp_f32_e32 v32, v32
	v_exp_f32_e32 v33, v33
	v_pk_fma_f32 v[28:29], v[28:29], v[176:177], v[136:137] op_sel_hi:[1,0,1]
	v_pk_mul_f32 v[24:25], v[24:25], v[30:31]
	v_add_f32_e32 v30, 1.0, v32
	v_add_f32_e32 v31, 1.0, v33
	v_mul_f32_e32 v32, 0xbfb8aa3b, v28
	v_mul_f32_e32 v33, 0xbfb8aa3b, v29
	v_exp_f32_e32 v32, v32
	v_exp_f32_e32 v33, v33
	v_rcp_f32_e32 v30, v30
	v_rcp_f32_e32 v31, v31
	v_add_f32_e32 v32, 1.0, v32
	v_add_f32_e32 v33, 1.0, v33
	v_rcp_f32_e32 v32, v32
	v_rcp_f32_e32 v33, v33
	v_pk_mul_f32 v[26:27], v[26:27], v[30:31]
	v_pk_fma_f32 v[18:19], v[18:19], v[176:177], v[130:131] op_sel_hi:[1,0,1]
	v_pk_fma_f32 v[20:21], v[20:21], v[176:177], v[132:133] op_sel_hi:[1,0,1]
	v_pk_mul_f32 v[26:27], v[18:19], v[26:27]
	v_pk_mul_f32 v[18:19], v[28:29], v[32:33]
	v_pk_fma_f32 v[14:15], v[14:15], v[172:173], v[142:143] op_sel_hi:[1,0,1]
	v_pk_mul_f32 v[28:29], v[20:21], v[18:19]
	v_mad_i64_i32 v[18:19], s[18:19], v174, s56, v[166:167]
	v_lshl_add_u64 v[18:19], v[18:19], 0, s[16:17]
	v_lshl_add_u64 v[30:31], v[18:19], 0, v[154:155]
	v_cvt_pk_bf16_f32 v18, v22, v23
	v_cvt_pk_bf16_f32 v19, v24, v25
	v_cvt_pk_bf16_f32 v20, v26, v27
	v_cvt_pk_bf16_f32 v21, v28, v29
	v_mul_f32_e32 v22, 0xbfb8aa3b, v14
	v_mul_f32_e32 v23, 0xbfb8aa3b, v15
	v_pk_fma_f32 v[16:17], v[16:17], v[172:173], v[144:145] op_sel_hi:[1,0,1]
	v_exp_f32_e32 v22, v22
	v_exp_f32_e32 v23, v23
	global_store_dwordx4 v[30:31], v[18:21], off nt
	v_pk_fma_f32 v[6:7], v[6:7], v[172:173], v[138:139] op_sel_hi:[1,0,1]
	v_pk_fma_f32 v[10:11], v[10:11], v[172:173], v[134:135] op_sel_hi:[1,0,1]
	v_mul_f32_e32 v20, 0xbfb8aa3b, v16
	v_mul_f32_e32 v21, 0xbfb8aa3b, v17
	v_exp_f32_e32 v20, v20
	v_exp_f32_e32 v21, v21
	v_add_f32_e32 v18, 1.0, v22
	v_add_f32_e32 v19, 1.0, v23
	v_rcp_f32_e32 v18, v18
	v_rcp_f32_e32 v19, v19
	v_add_f32_e32 v20, 1.0, v20
	v_add_f32_e32 v21, 1.0, v21
	v_rcp_f32_e32 v20, v20
	v_rcp_f32_e32 v21, v21
	v_pk_mul_f32 v[14:15], v[14:15], v[18:19]
	v_pk_fma_f32 v[8:9], v[8:9], v[172:173], v[140:141] op_sel_hi:[1,0,1]
	v_pk_mul_f32 v[6:7], v[6:7], v[14:15]
	v_pk_mul_f32 v[14:15], v[16:17], v[20:21]
	v_mul_f32_e32 v16, 0xbfb8aa3b, v10
	v_mul_f32_e32 v17, 0xbfb8aa3b, v11
	v_exp_f32_e32 v16, v16
	v_exp_f32_e32 v17, v17
	v_pk_fma_f32 v[12:13], v[12:13], v[172:173], v[136:137] op_sel_hi:[1,0,1]
	v_pk_mul_f32 v[8:9], v[8:9], v[14:15]
	v_add_f32_e32 v14, 1.0, v16
	v_add_f32_e32 v15, 1.0, v17
	v_mul_f32_e32 v16, 0xbfb8aa3b, v12
	v_mul_f32_e32 v17, 0xbfb8aa3b, v13
	v_exp_f32_e32 v16, v16
	v_exp_f32_e32 v17, v17
	v_rcp_f32_e32 v14, v14
	v_rcp_f32_e32 v15, v15
	v_add_f32_e32 v16, 1.0, v16
	v_add_f32_e32 v17, 1.0, v17
	v_rcp_f32_e32 v16, v16
	v_rcp_f32_e32 v17, v17
	v_pk_mul_f32 v[10:11], v[10:11], v[14:15]
	v_pk_fma_f32 v[2:3], v[2:3], v[172:173], v[130:131] op_sel_hi:[1,0,1]
	v_pk_fma_f32 v[4:5], v[4:5], v[172:173], v[132:133] op_sel_hi:[1,0,1]
	v_pk_mul_f32 v[10:11], v[2:3], v[10:11]
	v_pk_mul_f32 v[2:3], v[12:13], v[16:17]
	s_nop 0
	v_pk_mul_f32 v[12:13], v[4:5], v[2:3]
	v_mad_i64_i32 v[2:3], s[18:19], v168, s56, v[166:167]
	v_lshl_add_u64 v[2:3], v[2:3], 0, s[16:17]
	v_lshl_add_u64 v[14:15], v[2:3], 0, v[154:155]
	v_cvt_pk_bf16_f32 v2, v6, v7
	v_cvt_pk_bf16_f32 v3, v8, v9
	v_cvt_pk_bf16_f32 v4, v10, v11
	v_cvt_pk_bf16_f32 v5, v12, v13
	s_mov_b32 s17, s8
	s_mov_b32 s16, s10
	global_store_dwordx4 v[14:15], v[2:5], off nt
	s_cbranch_vccz .LBB0_3262
	s_waitcnt vmcnt(0)
	s_cmpk_gt_u32 s33, 0xff
	s_cbranch_scc1 .LBB0_3269
	s_barrier

.LBB0_3482:
	s_add_u32 s24, s24, 0xb0080
	s_addc_u32 s25, s25, 0
	s_add_u32 s60, s34, 0x100
	s_addc_u32 s61, s35, 0
	s_mov_b32 s62, -2
	s_waitcnt lgkmcnt(0)
	s_waitcnt vmcnt(0)
	ds_read_b128 v[130:133], v171
	ds_read_b128 v[134:137], v171 offset:1024
	ds_read_b128 v[138:141], v171 offset:2048
	ds_read_b128 v[142:145], v171 offset:3072
	s_add_u32 s18, s24, 0xfff50080
	s_addc_u32 s19, s25, -1
	s_cmp_eq_u32 s62, 40
	s_cselect_b32 s19, s7, s19
	s_cselect_b32 s18, s6, s18
	s_cselect_b32 s35, s1, s61
	s_cselect_b32 s34, s0, s60
	v_lshl_add_u64 v[202:203], s[24:25], 0, v[168:169]
	s_add_i32 m0, s41, 0xc000
	ds_read_b128 v[146:149], v210
	ds_read_b128 v[150:153], v210 offset:1024
	ds_read_b128 v[178:181], v210 offset:2048
	ds_read_b128 v[182:185], v210 offset:3072
	ds_read_b128 v[186:189], v210 offset:4096
	ds_read_b128 v[190:193], v210 offset:5120
	ds_read_b128 v[194:197], v210 offset:6144
	ds_read_b128 v[198:201], v210 offset:7168
	global_load_lds_dwordx4 v[202:203], off
	v_lshl_add_u64 v[202:203], s[24:25], 0, v[172:173]
	s_add_i32 m0, s41, 0xe000
	s_nop 0
	global_load_lds_dwordx4 v[202:203], off
	ds_read_b128 v[202:205], v211
	ds_read_b128 v[206:209], v211 offset:1024
	ds_read_b128 v[214:217], v211 offset:2048
	ds_read_b128 v[218:221], v211 offset:3072
	s_waitcnt vmcnt(8)
	s_waitcnt lgkmcnt(0)
	s_setprio 1
	s_barrier
	v_mfma_f32_16x16x32_bf16 v[126:129], v[130:133], v[146:149], 0
	v_mfma_f32_16x16x32_bf16 v[122:125], v[138:141], v[146:149], 0
	v_mfma_f32_16x16x32_bf16 v[110:113], v[130:133], v[178:181], 0
	v_mfma_f32_16x16x32_bf16 v[106:109], v[138:141], v[178:181], 0
	v_mfma_f32_16x16x32_bf16 v[94:97], v[130:133], v[186:189], 0
	v_mfma_f32_16x16x32_bf16 v[90:93], v[138:141], v[186:189], 0
	v_mfma_f32_16x16x32_bf16 v[78:81], v[130:133], v[194:197], 0
	v_mfma_f32_16x16x32_bf16 v[74:77], v[138:141], v[194:197], 0
	v_mfma_f32_16x16x32_bf16 v[126:129], v[134:137], v[150:153], v[126:129]
	v_mfma_f32_16x16x32_bf16 v[122:125], v[142:145], v[150:153], v[122:125]
	v_mfma_f32_16x16x32_bf16 v[110:113], v[134:137], v[182:185], v[110:113]
	v_mfma_f32_16x16x32_bf16 v[106:109], v[142:145], v[182:185], v[106:109]
	v_mfma_f32_16x16x32_bf16 v[94:97], v[134:137], v[190:193], v[94:97]
	v_mfma_f32_16x16x32_bf16 v[90:93], v[142:145], v[190:193], v[90:93]
	v_mfma_f32_16x16x32_bf16 v[78:81], v[134:137], v[198:201], v[78:81]
	v_mfma_f32_16x16x32_bf16 v[74:77], v[142:145], v[198:201], v[74:77]
	v_mfma_f32_16x16x32_bf16 v[118:121], v[202:205], v[146:149], 0
	v_mfma_f32_16x16x32_bf16 v[114:117], v[214:217], v[146:149], 0
	v_mfma_f32_16x16x32_bf16 v[102:105], v[202:205], v[178:181], 0
	v_mfma_f32_16x16x32_bf16 v[98:101], v[214:217], v[178:181], 0
	v_mfma_f32_16x16x32_bf16 v[86:89], v[202:205], v[186:189], 0
	v_mfma_f32_16x16x32_bf16 v[82:85], v[214:217], v[186:189], 0
	v_mfma_f32_16x16x32_bf16 v[70:73], v[202:205], v[194:197], 0
	v_mfma_f32_16x16x32_bf16 v[66:69], v[214:217], v[194:197], 0
	v_mfma_f32_16x16x32_bf16 v[118:121], v[206:209], v[150:153], v[118:121]
	v_mfma_f32_16x16x32_bf16 v[114:117], v[218:221], v[150:153], v[114:117]
	v_mfma_f32_16x16x32_bf16 v[102:105], v[206:209], v[182:185], v[102:105]
	v_mfma_f32_16x16x32_bf16 v[98:101], v[218:221], v[182:185], v[98:101]
	v_mfma_f32_16x16x32_bf16 v[86:89], v[206:209], v[190:193], v[86:89]
	v_mfma_f32_16x16x32_bf16 v[82:85], v[218:221], v[190:193], v[82:85]
	v_mfma_f32_16x16x32_bf16 v[70:73], v[206:209], v[198:201], v[70:73]
	v_mfma_f32_16x16x32_bf16 v[66:69], v[218:221], v[198:201], v[66:69]
	s_barrier
	s_setprio 0
	s_add_i32 s20, s52, s40
	v_lshl_add_u64 v[222:223], s[34:35], 0, v[156:157]
	s_mov_b32 m0, s20
	s_nop 0
	global_load_lds_dwordx4 v[222:223], off
	v_lshl_add_u64 v[224:225], s[34:35], 0, v[160:161]
	s_add_i32 m0, s20, 0x2000
	s_nop 0
	global_load_lds_dwordx4 v[224:225], off
	s_mov_b32 m0, s41
	v_lshl_add_u64 v[226:227], s[18:19], 0, v[154:155]
	ds_read_b128 v[146:149], v210 offset:16384
	ds_read_b128 v[150:153], v210 offset:17408
	ds_read_b128 v[178:181], v210 offset:18432
	ds_read_b128 v[182:185], v210 offset:19456
	ds_read_b128 v[186:189], v210 offset:20480
	ds_read_b128 v[190:193], v210 offset:21504
	ds_read_b128 v[194:197], v210 offset:22528
	ds_read_b128 v[198:201], v210 offset:23552
	global_load_lds_dwordx4 v[226:227], off
	v_lshl_add_u64 v[228:229], s[18:19], 0, v[158:159]
	s_mov_b32 m0, s42
	s_nop 0
	global_load_lds_dwordx4 v[228:229], off
	s_add_u32 s20, s34, 0xb0000
	s_addc_u32 s21, s35, 0
	s_add_i32 s63, s53, s40
	v_lshl_add_u64 v[246:247], s[20:21], 0, v[156:157]
	s_mov_b32 m0, s63
	s_nop 0
	global_load_lds_dwordx4 v[246:247], off
	v_lshl_add_u64 v[246:247], s[20:21], 0, v[160:161]
	s_add_i32 m0, s63, 0x2000
	s_nop 0
	global_load_lds_dwordx4 v[246:247], off
	s_waitcnt vmcnt(8)
	s_waitcnt lgkmcnt(0)
	s_setprio 1
	s_barrier
	v_mfma_f32_16x16x32_bf16 v[62:65], v[130:133], v[146:149], 0
	v_mfma_f32_16x16x32_bf16 v[58:61], v[138:141], v[146:149], 0
	v_mfma_f32_16x16x32_bf16 v[46:49], v[130:133], v[178:181], 0
	v_mfma_f32_16x16x32_bf16 v[42:45], v[138:141], v[178:181], 0
	v_mfma_f32_16x16x32_bf16 v[30:33], v[130:133], v[186:189], 0
	v_mfma_f32_16x16x32_bf16 v[26:29], v[138:141], v[186:189], 0
	v_mfma_f32_16x16x32_bf16 v[14:17], v[130:133], v[194:197], 0
	v_mfma_f32_16x16x32_bf16 v[10:13], v[138:141], v[194:197], 0
	v_mfma_f32_16x16x32_bf16 v[62:65], v[134:137], v[150:153], v[62:65]
	v_mfma_f32_16x16x32_bf16 v[58:61], v[142:145], v[150:153], v[58:61]
	v_mfma_f32_16x16x32_bf16 v[46:49], v[134:137], v[182:185], v[46:49]
	v_mfma_f32_16x16x32_bf16 v[42:45], v[142:145], v[182:185], v[42:45]
	v_mfma_f32_16x16x32_bf16 v[30:33], v[134:137], v[190:193], v[30:33]
	v_mfma_f32_16x16x32_bf16 v[26:29], v[142:145], v[190:193], v[26:29]
	v_mfma_f32_16x16x32_bf16 v[14:17], v[134:137], v[198:201], v[14:17]
	v_mfma_f32_16x16x32_bf16 v[10:13], v[142:145], v[198:201], v[10:13]
	v_mfma_f32_16x16x32_bf16 v[54:57], v[202:205], v[146:149], 0
	v_mfma_f32_16x16x32_bf16 v[50:53], v[214:217], v[146:149], 0
	v_mfma_f32_16x16x32_bf16 v[38:41], v[202:205], v[178:181], 0
	v_mfma_f32_16x16x32_bf16 v[34:37], v[214:217], v[178:181], 0
	v_mfma_f32_16x16x32_bf16 v[22:25], v[202:205], v[186:189], 0
	v_mfma_f32_16x16x32_bf16 v[18:21], v[214:217], v[186:189], 0
	v_mfma_f32_16x16x32_bf16 v[6:9], v[202:205], v[194:197], 0
	v_mfma_f32_16x16x32_bf16 v[2:5], v[214:217], v[194:197], 0
	v_mfma_f32_16x16x32_bf16 v[54:57], v[206:209], v[150:153], v[54:57]
	v_mfma_f32_16x16x32_bf16 v[50:53], v[218:221], v[150:153], v[50:53]
	v_mfma_f32_16x16x32_bf16 v[38:41], v[206:209], v[182:185], v[38:41]
	v_mfma_f32_16x16x32_bf16 v[34:37], v[218:221], v[182:185], v[34:37]
	v_mfma_f32_16x16x32_bf16 v[22:25], v[206:209], v[190:193], v[22:25]
	v_mfma_f32_16x16x32_bf16 v[18:21], v[218:221], v[190:193], v[18:21]
	v_mfma_f32_16x16x32_bf16 v[6:9], v[206:209], v[198:201], v[6:9]
	v_mfma_f32_16x16x32_bf16 v[2:5], v[218:221], v[198:201], v[2:5]
	s_barrier
	s_setprio 0
	s_add_i32 s20, 0, 0x18000
	v_add_u32_e32 v142, s20, v165
	ds_read_b128 v[130:133], v142
	ds_read_b128 v[134:137], v142 offset:1024
	ds_read_b128 v[138:141], v142 offset:2048
	ds_read_b128 v[142:145], v142 offset:3072
	s_add_u32 s18, s18, 0xb0000
	s_addc_u32 s19, s19, 0
	s_mov_b32 m0, s43
	v_lshl_add_u64 v[202:203], s[18:19], 0, v[154:155]
	ds_read_b128 v[146:149], v210 offset:32768
	ds_read_b128 v[150:153], v210 offset:33792
	ds_read_b128 v[178:181], v210 offset:34816
	ds_read_b128 v[182:185], v210 offset:35840
	ds_read_b128 v[186:189], v210 offset:36864
	ds_read_b128 v[190:193], v210 offset:37888
	ds_read_b128 v[194:197], v210 offset:38912
	ds_read_b128 v[198:201], v210 offset:39936
	global_load_lds_dwordx4 v[202:203], off
	v_lshl_add_u64 v[202:203], s[18:19], 0, v[158:159]
	s_mov_b32 m0, s44
	s_nop 0
	global_load_lds_dwordx4 v[202:203], off
	s_add_i32 s21, 0, 0x1c000
	v_add_u32_e32 v162, s21, v165
	ds_read_b128 v[202:205], v162
	ds_read_b128 v[206:209], v162 offset:1024
	ds_read_b128 v[214:217], v162 offset:2048
	ds_read_b128 v[218:221], v162 offset:3072
	s_waitcnt vmcnt(8)
	s_waitcnt lgkmcnt(0)
	s_setprio 1
	s_barrier
	v_mfma_f32_16x16x32_bf16 v[126:129], v[130:133], v[146:149], v[126:129]
	v_mfma_f32_16x16x32_bf16 v[122:125], v[138:141], v[146:149], v[122:125]
	v_mfma_f32_16x16x32_bf16 v[110:113], v[130:133], v[178:181], v[110:113]
	v_mfma_f32_16x16x32_bf16 v[106:109], v[138:141], v[178:181], v[106:109]
	v_mfma_f32_16x16x32_bf16 v[94:97], v[130:133], v[186:189], v[94:97]
	v_mfma_f32_16x16x32_bf16 v[90:93], v[138:141], v[186:189], v[90:93]
	v_mfma_f32_16x16x32_bf16 v[78:81], v[130:133], v[194:197], v[78:81]
	v_mfma_f32_16x16x32_bf16 v[74:77], v[138:141], v[194:197], v[74:77]
	v_mfma_f32_16x16x32_bf16 v[126:129], v[134:137], v[150:153], v[126:129]
	v_mfma_f32_16x16x32_bf16 v[122:125], v[142:145], v[150:153], v[122:125]
	v_mfma_f32_16x16x32_bf16 v[110:113], v[134:137], v[182:185], v[110:113]
	v_mfma_f32_16x16x32_bf16 v[106:109], v[142:145], v[182:185], v[106:109]
	v_mfma_f32_16x16x32_bf16 v[94:97], v[134:137], v[190:193], v[94:97]
	v_mfma_f32_16x16x32_bf16 v[90:93], v[142:145], v[190:193], v[90:93]
	v_mfma_f32_16x16x32_bf16 v[78:81], v[134:137], v[198:201], v[78:81]
	v_mfma_f32_16x16x32_bf16 v[74:77], v[142:145], v[198:201], v[74:77]
	v_mfma_f32_16x16x32_bf16 v[118:121], v[202:205], v[146:149], v[118:121]
	v_mfma_f32_16x16x32_bf16 v[114:117], v[214:217], v[146:149], v[114:117]
	v_mfma_f32_16x16x32_bf16 v[102:105], v[202:205], v[178:181], v[102:105]
	v_mfma_f32_16x16x32_bf16 v[98:101], v[214:217], v[178:181], v[98:101]
	v_mfma_f32_16x16x32_bf16 v[86:89], v[202:205], v[186:189], v[86:89]
	v_mfma_f32_16x16x32_bf16 v[82:85], v[214:217], v[186:189], v[82:85]
	v_mfma_f32_16x16x32_bf16 v[70:73], v[202:205], v[194:197], v[70:73]
	v_mfma_f32_16x16x32_bf16 v[66:69], v[214:217], v[194:197], v[66:69]
	v_mfma_f32_16x16x32_bf16 v[118:121], v[206:209], v[150:153], v[118:121]
	v_mfma_f32_16x16x32_bf16 v[114:117], v[218:221], v[150:153], v[114:117]
	v_mfma_f32_16x16x32_bf16 v[102:105], v[206:209], v[182:185], v[102:105]
	v_mfma_f32_16x16x32_bf16 v[98:101], v[218:221], v[182:185], v[98:101]
	v_mfma_f32_16x16x32_bf16 v[86:89], v[206:209], v[190:193], v[86:89]
	v_mfma_f32_16x16x32_bf16 v[82:85], v[218:221], v[190:193], v[82:85]
	v_mfma_f32_16x16x32_bf16 v[70:73], v[206:209], v[198:201], v[70:73]
	v_mfma_f32_16x16x32_bf16 v[66:69], v[218:221], v[198:201], v[66:69]
	s_barrier
	s_setprio 0
	s_add_i32 s18, s20, s40
	v_lshl_add_u64 v[222:223], v[222:223], 0, s[14:15]
	s_mov_b32 m0, s18
	s_nop 0
	global_load_lds_dwordx4 v[222:223], off
	v_lshl_add_u64 v[222:223], v[224:225], 0, s[14:15]
	s_add_i32 m0, s18, 0x2000
	s_nop 0
	global_load_lds_dwordx4 v[222:223], off
	s_mov_b32 m0, s48
	v_lshl_add_u64 v[222:223], v[226:227], 0, s[14:15]
	ds_read_b128 v[146:149], v210 offset:49152
	ds_read_b128 v[150:153], v210 offset:50176
	ds_read_b128 v[178:181], v210 offset:51200
	ds_read_b128 v[182:185], v210 offset:52224
	ds_read_b128 v[186:189], v210 offset:53248
	ds_read_b128 v[190:193], v210 offset:54272
	ds_read_b128 v[194:197], v210 offset:55296
	ds_read_b128 v[198:201], v210 offset:56320
	global_load_lds_dwordx4 v[222:223], off
	v_lshl_add_u64 v[222:223], v[228:229], 0, s[14:15]
	s_mov_b32 m0, s49
	s_nop 0
	global_load_lds_dwordx4 v[222:223], off
	s_add_u32 s18, s34, 0xb0080
	s_addc_u32 s19, s35, 0
	s_add_i32 s20, s21, s40
	v_lshl_add_u64 v[248:249], s[18:19], 0, v[156:157]
	s_mov_b32 m0, s20
	s_nop 0
	global_load_lds_dwordx4 v[248:249], off
	v_lshl_add_u64 v[248:249], s[18:19], 0, v[160:161]
	s_add_i32 m0, s20, 0x2000
	s_nop 0
	global_load_lds_dwordx4 v[248:249], off
	s_waitcnt vmcnt(8)
	s_waitcnt lgkmcnt(0)
	s_setprio 1
	s_barrier
	v_mfma_f32_16x16x32_bf16 v[62:65], v[130:133], v[146:149], v[62:65]
	v_mfma_f32_16x16x32_bf16 v[58:61], v[138:141], v[146:149], v[58:61]
	v_mfma_f32_16x16x32_bf16 v[46:49], v[130:133], v[178:181], v[46:49]
	v_mfma_f32_16x16x32_bf16 v[42:45], v[138:141], v[178:181], v[42:45]
	v_mfma_f32_16x16x32_bf16 v[30:33], v[130:133], v[186:189], v[30:33]
	v_mfma_f32_16x16x32_bf16 v[26:29], v[138:141], v[186:189], v[26:29]
	v_mfma_f32_16x16x32_bf16 v[14:17], v[130:133], v[194:197], v[14:17]
	v_mfma_f32_16x16x32_bf16 v[10:13], v[138:141], v[194:197], v[10:13]
	v_mfma_f32_16x16x32_bf16 v[62:65], v[134:137], v[150:153], v[62:65]
	v_mfma_f32_16x16x32_bf16 v[58:61], v[142:145], v[150:153], v[58:61]
	v_mfma_f32_16x16x32_bf16 v[46:49], v[134:137], v[182:185], v[46:49]
	v_mfma_f32_16x16x32_bf16 v[42:45], v[142:145], v[182:185], v[42:45]
	v_mfma_f32_16x16x32_bf16 v[30:33], v[134:137], v[190:193], v[30:33]
	v_mfma_f32_16x16x32_bf16 v[26:29], v[142:145], v[190:193], v[26:29]
	v_mfma_f32_16x16x32_bf16 v[14:17], v[134:137], v[198:201], v[14:17]
	v_mfma_f32_16x16x32_bf16 v[10:13], v[142:145], v[198:201], v[10:13]
	v_mfma_f32_16x16x32_bf16 v[54:57], v[202:205], v[146:149], v[54:57]
	v_mfma_f32_16x16x32_bf16 v[50:53], v[214:217], v[146:149], v[50:53]
	v_mfma_f32_16x16x32_bf16 v[38:41], v[202:205], v[178:181], v[38:41]
	v_mfma_f32_16x16x32_bf16 v[34:37], v[214:217], v[178:181], v[34:37]
	v_mfma_f32_16x16x32_bf16 v[22:25], v[202:205], v[186:189], v[22:25]
	v_mfma_f32_16x16x32_bf16 v[18:21], v[214:217], v[186:189], v[18:21]
	v_mfma_f32_16x16x32_bf16 v[6:9], v[202:205], v[194:197], v[6:9]
	v_mfma_f32_16x16x32_bf16 v[2:5], v[214:217], v[194:197], v[2:5]
	v_mfma_f32_16x16x32_bf16 v[54:57], v[206:209], v[150:153], v[54:57]
	v_mfma_f32_16x16x32_bf16 v[50:53], v[218:221], v[150:153], v[50:53]
	v_mfma_f32_16x16x32_bf16 v[38:41], v[206:209], v[182:185], v[38:41]
	v_mfma_f32_16x16x32_bf16 v[34:37], v[218:221], v[182:185], v[34:37]
	v_mfma_f32_16x16x32_bf16 v[22:25], v[206:209], v[190:193], v[22:25]
	v_mfma_f32_16x16x32_bf16 v[18:21], v[218:221], v[190:193], v[18:21]
	v_mfma_f32_16x16x32_bf16 v[6:9], v[206:209], v[198:201], v[6:9]
	v_mfma_f32_16x16x32_bf16 v[2:5], v[218:221], v[198:201], v[2:5]
	s_barrier
	s_setprio 0
	s_add_i32 s62, s62, 2
	s_add_u32 s24, s24, 0x100
	s_addc_u32 s25, s25, 0
	s_add_u32 s60, s60, 0x100
	s_addc_u32 s61, s61, 0
	s_cmp_gt_u32 s62, 41
.LBB0_3483:
	ds_read_b128 v[130:133], v171
	ds_read_b128 v[134:137], v171 offset:1024
	ds_read_b128 v[138:141], v171 offset:2048
	ds_read_b128 v[142:145], v171 offset:3072
	s_add_u32 s18, s24, 0xfff50080
	s_addc_u32 s19, s25, -1
	s_cmp_eq_u32 s62, 40
	s_cselect_b32 s19, s7, s19
	s_cselect_b32 s18, s6, s18
	s_cselect_b32 s35, s1, s61
	s_cselect_b32 s34, s0, s60
	v_lshl_add_u64 v[202:203], s[24:25], 0, v[168:169]
	s_add_i32 m0, s41, 0xc000
	ds_read_b128 v[146:149], v210
	ds_read_b128 v[150:153], v210 offset:1024
	ds_read_b128 v[178:181], v210 offset:2048
	ds_read_b128 v[182:185], v210 offset:3072
	ds_read_b128 v[186:189], v210 offset:4096
	ds_read_b128 v[190:193], v210 offset:5120
	ds_read_b128 v[194:197], v210 offset:6144
	ds_read_b128 v[198:201], v210 offset:7168
	global_load_lds_dwordx4 v[202:203], off
	v_lshl_add_u64 v[202:203], s[24:25], 0, v[172:173]
	s_add_i32 m0, s41, 0xe000
	s_nop 0
	global_load_lds_dwordx4 v[202:203], off
	ds_read_b128 v[202:205], v211
	ds_read_b128 v[206:209], v211 offset:1024
	ds_read_b128 v[214:217], v211 offset:2048
	ds_read_b128 v[218:221], v211 offset:3072
	s_waitcnt vmcnt(8)
	s_waitcnt lgkmcnt(0)
	s_setprio 1
	s_barrier
	v_mfma_f32_16x16x32_bf16 v[126:129], v[130:133], v[146:149], v[126:129]
	v_mfma_f32_16x16x32_bf16 v[122:125], v[138:141], v[146:149], v[122:125]
	v_mfma_f32_16x16x32_bf16 v[110:113], v[130:133], v[178:181], v[110:113]
	v_mfma_f32_16x16x32_bf16 v[106:109], v[138:141], v[178:181], v[106:109]
	v_mfma_f32_16x16x32_bf16 v[94:97], v[130:133], v[186:189], v[94:97]
	v_mfma_f32_16x16x32_bf16 v[90:93], v[138:141], v[186:189], v[90:93]
	v_mfma_f32_16x16x32_bf16 v[78:81], v[130:133], v[194:197], v[78:81]
	v_mfma_f32_16x16x32_bf16 v[74:77], v[138:141], v[194:197], v[74:77]
	v_mfma_f32_16x16x32_bf16 v[126:129], v[134:137], v[150:153], v[126:129]
	v_mfma_f32_16x16x32_bf16 v[122:125], v[142:145], v[150:153], v[122:125]
	v_mfma_f32_16x16x32_bf16 v[110:113], v[134:137], v[182:185], v[110:113]
	v_mfma_f32_16x16x32_bf16 v[106:109], v[142:145], v[182:185], v[106:109]
	v_mfma_f32_16x16x32_bf16 v[94:97], v[134:137], v[190:193], v[94:97]
	v_mfma_f32_16x16x32_bf16 v[90:93], v[142:145], v[190:193], v[90:93]
	v_mfma_f32_16x16x32_bf16 v[78:81], v[134:137], v[198:201], v[78:81]
	v_mfma_f32_16x16x32_bf16 v[74:77], v[142:145], v[198:201], v[74:77]
	v_mfma_f32_16x16x32_bf16 v[118:121], v[202:205], v[146:149], v[118:121]
	v_mfma_f32_16x16x32_bf16 v[114:117], v[214:217], v[146:149], v[114:117]
	v_mfma_f32_16x16x32_bf16 v[102:105], v[202:205], v[178:181], v[102:105]
	v_mfma_f32_16x16x32_bf16 v[98:101], v[214:217], v[178:181], v[98:101]
	v_mfma_f32_16x16x32_bf16 v[86:89], v[202:205], v[186:189], v[86:89]
	v_mfma_f32_16x16x32_bf16 v[82:85], v[214:217], v[186:189], v[82:85]
	v_mfma_f32_16x16x32_bf16 v[70:73], v[202:205], v[194:197], v[70:73]
	v_mfma_f32_16x16x32_bf16 v[66:69], v[214:217], v[194:197], v[66:69]
	v_mfma_f32_16x16x32_bf16 v[118:121], v[206:209], v[150:153], v[118:121]
	v_mfma_f32_16x16x32_bf16 v[114:117], v[218:221], v[150:153], v[114:117]
	v_mfma_f32_16x16x32_bf16 v[102:105], v[206:209], v[182:185], v[102:105]
	v_mfma_f32_16x16x32_bf16 v[98:101], v[218:221], v[182:185], v[98:101]
	v_mfma_f32_16x16x32_bf16 v[86:89], v[206:209], v[190:193], v[86:89]
	v_mfma_f32_16x16x32_bf16 v[82:85], v[218:221], v[190:193], v[82:85]
	v_mfma_f32_16x16x32_bf16 v[70:73], v[206:209], v[198:201], v[70:73]
	v_mfma_f32_16x16x32_bf16 v[66:69], v[218:221], v[198:201], v[66:69]
	s_barrier
	s_setprio 0
	s_add_i32 s20, s52, s40
	v_lshl_add_u64 v[222:223], s[34:35], 0, v[156:157]
	s_mov_b32 m0, s20
	s_nop 0
	global_load_lds_dwordx4 v[222:223], off
	v_lshl_add_u64 v[224:225], s[34:35], 0, v[160:161]
	s_add_i32 m0, s20, 0x2000
	s_nop 0
	global_load_lds_dwordx4 v[224:225], off
	s_mov_b32 m0, s41
	v_lshl_add_u64 v[226:227], s[18:19], 0, v[154:155]
	ds_read_b128 v[146:149], v210 offset:16384
	ds_read_b128 v[150:153], v210 offset:17408
	ds_read_b128 v[178:181], v210 offset:18432
	ds_read_b128 v[182:185], v210 offset:19456
	ds_read_b128 v[186:189], v210 offset:20480
	ds_read_b128 v[190:193], v210 offset:21504
	ds_read_b128 v[194:197], v210 offset:22528
	ds_read_b128 v[198:201], v210 offset:23552
	global_load_lds_dwordx4 v[226:227], off
	v_lshl_add_u64 v[228:229], s[18:19], 0, v[158:159]
	s_mov_b32 m0, s42
	s_nop 0
	global_load_lds_dwordx4 v[228:229], off
	s_add_u32 s20, s34, 0xb0000
	s_addc_u32 s21, s35, 0
	s_add_i32 s63, s53, s40
	v_lshl_add_u64 v[246:247], s[20:21], 0, v[156:157]
	s_mov_b32 m0, s63
	s_nop 0
	global_load_lds_dwordx4 v[246:247], off
	v_lshl_add_u64 v[246:247], s[20:21], 0, v[160:161]
	s_add_i32 m0, s63, 0x2000
	s_nop 0
	global_load_lds_dwordx4 v[246:247], off
	s_waitcnt vmcnt(8)
	s_waitcnt lgkmcnt(0)
	s_setprio 1
	s_barrier
	v_mfma_f32_16x16x32_bf16 v[62:65], v[130:133], v[146:149], v[62:65]
	v_mfma_f32_16x16x32_bf16 v[58:61], v[138:141], v[146:149], v[58:61]
	v_mfma_f32_16x16x32_bf16 v[46:49], v[130:133], v[178:181], v[46:49]
	v_mfma_f32_16x16x32_bf16 v[42:45], v[138:141], v[178:181], v[42:45]
	v_mfma_f32_16x16x32_bf16 v[30:33], v[130:133], v[186:189], v[30:33]
	v_mfma_f32_16x16x32_bf16 v[26:29], v[138:141], v[186:189], v[26:29]
	v_mfma_f32_16x16x32_bf16 v[14:17], v[130:133], v[194:197], v[14:17]
	v_mfma_f32_16x16x32_bf16 v[10:13], v[138:141], v[194:197], v[10:13]
	v_mfma_f32_16x16x32_bf16 v[62:65], v[134:137], v[150:153], v[62:65]
	v_mfma_f32_16x16x32_bf16 v[58:61], v[142:145], v[150:153], v[58:61]
	v_mfma_f32_16x16x32_bf16 v[46:49], v[134:137], v[182:185], v[46:49]
	v_mfma_f32_16x16x32_bf16 v[42:45], v[142:145], v[182:185], v[42:45]
	v_mfma_f32_16x16x32_bf16 v[30:33], v[134:137], v[190:193], v[30:33]
	v_mfma_f32_16x16x32_bf16 v[26:29], v[142:145], v[190:193], v[26:29]
	v_mfma_f32_16x16x32_bf16 v[14:17], v[134:137], v[198:201], v[14:17]
	v_mfma_f32_16x16x32_bf16 v[10:13], v[142:145], v[198:201], v[10:13]
	v_mfma_f32_16x16x32_bf16 v[54:57], v[202:205], v[146:149], v[54:57]
	v_mfma_f32_16x16x32_bf16 v[50:53], v[214:217], v[146:149], v[50:53]
	v_mfma_f32_16x16x32_bf16 v[38:41], v[202:205], v[178:181], v[38:41]
	v_mfma_f32_16x16x32_bf16 v[34:37], v[214:217], v[178:181], v[34:37]
	v_mfma_f32_16x16x32_bf16 v[22:25], v[202:205], v[186:189], v[22:25]
	v_mfma_f32_16x16x32_bf16 v[18:21], v[214:217], v[186:189], v[18:21]
	v_mfma_f32_16x16x32_bf16 v[6:9], v[202:205], v[194:197], v[6:9]
	v_mfma_f32_16x16x32_bf16 v[2:5], v[214:217], v[194:197], v[2:5]
	v_mfma_f32_16x16x32_bf16 v[54:57], v[206:209], v[150:153], v[54:57]
	v_mfma_f32_16x16x32_bf16 v[50:53], v[218:221], v[150:153], v[50:53]
	v_mfma_f32_16x16x32_bf16 v[38:41], v[206:209], v[182:185], v[38:41]
	v_mfma_f32_16x16x32_bf16 v[34:37], v[218:221], v[182:185], v[34:37]
	v_mfma_f32_16x16x32_bf16 v[22:25], v[206:209], v[190:193], v[22:25]
	v_mfma_f32_16x16x32_bf16 v[18:21], v[218:221], v[190:193], v[18:21]
	v_mfma_f32_16x16x32_bf16 v[6:9], v[206:209], v[198:201], v[6:9]
	v_mfma_f32_16x16x32_bf16 v[2:5], v[218:221], v[198:201], v[2:5]
	s_barrier
	s_setprio 0
	s_add_i32 s20, 0, 0x18000
	v_add_u32_e32 v142, s20, v165
	ds_read_b128 v[130:133], v142
	ds_read_b128 v[134:137], v142 offset:1024
	ds_read_b128 v[138:141], v142 offset:2048
	ds_read_b128 v[142:145], v142 offset:3072
	s_add_u32 s18, s18, 0xb0000
	s_addc_u32 s19, s19, 0
	s_mov_b32 m0, s43
	v_lshl_add_u64 v[202:203], s[18:19], 0, v[154:155]
	ds_read_b128 v[146:149], v210 offset:32768
	ds_read_b128 v[150:153], v210 offset:33792
	ds_read_b128 v[178:181], v210 offset:34816
	ds_read_b128 v[182:185], v210 offset:35840
	ds_read_b128 v[186:189], v210 offset:36864
	ds_read_b128 v[190:193], v210 offset:37888
	ds_read_b128 v[194:197], v210 offset:38912
	ds_read_b128 v[198:201], v210 offset:39936
	global_load_lds_dwordx4 v[202:203], off
	v_lshl_add_u64 v[202:203], s[18:19], 0, v[158:159]
	s_mov_b32 m0, s44
	s_nop 0
	global_load_lds_dwordx4 v[202:203], off
	s_add_i32 s21, 0, 0x1c000
	v_add_u32_e32 v162, s21, v165
	ds_read_b128 v[202:205], v162
	ds_read_b128 v[206:209], v162 offset:1024
	ds_read_b128 v[214:217], v162 offset:2048
	ds_read_b128 v[218:221], v162 offset:3072
	s_waitcnt vmcnt(8)
	s_waitcnt lgkmcnt(0)
	s_setprio 1
	s_barrier
	v_mfma_f32_16x16x32_bf16 v[126:129], v[130:133], v[146:149], v[126:129]
	v_mfma_f32_16x16x32_bf16 v[122:125], v[138:141], v[146:149], v[122:125]
	v_mfma_f32_16x16x32_bf16 v[110:113], v[130:133], v[178:181], v[110:113]
	v_mfma_f32_16x16x32_bf16 v[106:109], v[138:141], v[178:181], v[106:109]
	v_mfma_f32_16x16x32_bf16 v[94:97], v[130:133], v[186:189], v[94:97]
	v_mfma_f32_16x16x32_bf16 v[90:93], v[138:141], v[186:189], v[90:93]
	v_mfma_f32_16x16x32_bf16 v[78:81], v[130:133], v[194:197], v[78:81]
	v_mfma_f32_16x16x32_bf16 v[74:77], v[138:141], v[194:197], v[74:77]
	v_mfma_f32_16x16x32_bf16 v[126:129], v[134:137], v[150:153], v[126:129]
	v_mfma_f32_16x16x32_bf16 v[122:125], v[142:145], v[150:153], v[122:125]
	v_mfma_f32_16x16x32_bf16 v[110:113], v[134:137], v[182:185], v[110:113]
	v_mfma_f32_16x16x32_bf16 v[106:109], v[142:145], v[182:185], v[106:109]
	v_mfma_f32_16x16x32_bf16 v[94:97], v[134:137], v[190:193], v[94:97]
	v_mfma_f32_16x16x32_bf16 v[90:93], v[142:145], v[190:193], v[90:93]
	v_mfma_f32_16x16x32_bf16 v[78:81], v[134:137], v[198:201], v[78:81]
	v_mfma_f32_16x16x32_bf16 v[74:77], v[142:145], v[198:201], v[74:77]
	v_mfma_f32_16x16x32_bf16 v[118:121], v[202:205], v[146:149], v[118:121]
	v_mfma_f32_16x16x32_bf16 v[114:117], v[214:217], v[146:149], v[114:117]
	v_mfma_f32_16x16x32_bf16 v[102:105], v[202:205], v[178:181], v[102:105]
	v_mfma_f32_16x16x32_bf16 v[98:101], v[214:217], v[178:181], v[98:101]
	v_mfma_f32_16x16x32_bf16 v[86:89], v[202:205], v[186:189], v[86:89]
	v_mfma_f32_16x16x32_bf16 v[82:85], v[214:217], v[186:189], v[82:85]
	v_mfma_f32_16x16x32_bf16 v[70:73], v[202:205], v[194:197], v[70:73]
	v_mfma_f32_16x16x32_bf16 v[66:69], v[214:217], v[194:197], v[66:69]
	v_mfma_f32_16x16x32_bf16 v[118:121], v[206:209], v[150:153], v[118:121]
	v_mfma_f32_16x16x32_bf16 v[114:117], v[218:221], v[150:153], v[114:117]
	v_mfma_f32_16x16x32_bf16 v[102:105], v[206:209], v[182:185], v[102:105]
	v_mfma_f32_16x16x32_bf16 v[98:101], v[218:221], v[182:185], v[98:101]
	v_mfma_f32_16x16x32_bf16 v[86:89], v[206:209], v[190:193], v[86:89]
	v_mfma_f32_16x16x32_bf16 v[82:85], v[218:221], v[190:193], v[82:85]
	v_mfma_f32_16x16x32_bf16 v[70:73], v[206:209], v[198:201], v[70:73]
	v_mfma_f32_16x16x32_bf16 v[66:69], v[218:221], v[198:201], v[66:69]
	s_barrier
	s_setprio 0
	s_add_i32 s18, s20, s40
	v_lshl_add_u64 v[222:223], v[222:223], 0, s[14:15]
	s_mov_b32 m0, s18
	s_nop 0
	global_load_lds_dwordx4 v[222:223], off
	v_lshl_add_u64 v[222:223], v[224:225], 0, s[14:15]
	s_add_i32 m0, s18, 0x2000
	s_nop 0
	global_load_lds_dwordx4 v[222:223], off
	s_mov_b32 m0, s48
	v_lshl_add_u64 v[222:223], v[226:227], 0, s[14:15]
	ds_read_b128 v[146:149], v210 offset:49152
	ds_read_b128 v[150:153], v210 offset:50176
	ds_read_b128 v[178:181], v210 offset:51200
	ds_read_b128 v[182:185], v210 offset:52224
	ds_read_b128 v[186:189], v210 offset:53248
	ds_read_b128 v[190:193], v210 offset:54272
	ds_read_b128 v[194:197], v210 offset:55296
	ds_read_b128 v[198:201], v210 offset:56320
	global_load_lds_dwordx4 v[222:223], off
	v_lshl_add_u64 v[222:223], v[228:229], 0, s[14:15]
	s_mov_b32 m0, s49
	s_nop 0
	global_load_lds_dwordx4 v[222:223], off
	s_add_u32 s18, s34, 0xb0080
	s_addc_u32 s19, s35, 0
	s_add_i32 s20, s21, s40
	v_lshl_add_u64 v[248:249], s[18:19], 0, v[156:157]
	s_mov_b32 m0, s20
	s_nop 0
	global_load_lds_dwordx4 v[248:249], off
	v_lshl_add_u64 v[248:249], s[18:19], 0, v[160:161]
	s_add_i32 m0, s20, 0x2000
	s_nop 0
	global_load_lds_dwordx4 v[248:249], off
	s_waitcnt vmcnt(8)
	s_waitcnt lgkmcnt(0)
	s_setprio 1
	s_barrier
	v_mfma_f32_16x16x32_bf16 v[62:65], v[130:133], v[146:149], v[62:65]
	v_mfma_f32_16x16x32_bf16 v[58:61], v[138:141], v[146:149], v[58:61]
	v_mfma_f32_16x16x32_bf16 v[46:49], v[130:133], v[178:181], v[46:49]
	v_mfma_f32_16x16x32_bf16 v[42:45], v[138:141], v[178:181], v[42:45]
	v_mfma_f32_16x16x32_bf16 v[30:33], v[130:133], v[186:189], v[30:33]
	v_mfma_f32_16x16x32_bf16 v[26:29], v[138:141], v[186:189], v[26:29]
	v_mfma_f32_16x16x32_bf16 v[14:17], v[130:133], v[194:197], v[14:17]
	v_mfma_f32_16x16x32_bf16 v[10:13], v[138:141], v[194:197], v[10:13]
	v_mfma_f32_16x16x32_bf16 v[62:65], v[134:137], v[150:153], v[62:65]
	v_mfma_f32_16x16x32_bf16 v[58:61], v[142:145], v[150:153], v[58:61]
	v_mfma_f32_16x16x32_bf16 v[46:49], v[134:137], v[182:185], v[46:49]
	v_mfma_f32_16x16x32_bf16 v[42:45], v[142:145], v[182:185], v[42:45]
	v_mfma_f32_16x16x32_bf16 v[30:33], v[134:137], v[190:193], v[30:33]
	v_mfma_f32_16x16x32_bf16 v[26:29], v[142:145], v[190:193], v[26:29]
	v_mfma_f32_16x16x32_bf16 v[14:17], v[134:137], v[198:201], v[14:17]
	v_mfma_f32_16x16x32_bf16 v[10:13], v[142:145], v[198:201], v[10:13]
	v_mfma_f32_16x16x32_bf16 v[54:57], v[202:205], v[146:149], v[54:57]
	v_mfma_f32_16x16x32_bf16 v[50:53], v[214:217], v[146:149], v[50:53]
	v_mfma_f32_16x16x32_bf16 v[38:41], v[202:205], v[178:181], v[38:41]
	v_mfma_f32_16x16x32_bf16 v[34:37], v[214:217], v[178:181], v[34:37]
	v_mfma_f32_16x16x32_bf16 v[22:25], v[202:205], v[186:189], v[22:25]
	v_mfma_f32_16x16x32_bf16 v[18:21], v[214:217], v[186:189], v[18:21]
	v_mfma_f32_16x16x32_bf16 v[6:9], v[202:205], v[194:197], v[6:9]
	v_mfma_f32_16x16x32_bf16 v[2:5], v[214:217], v[194:197], v[2:5]
	v_mfma_f32_16x16x32_bf16 v[54:57], v[206:209], v[150:153], v[54:57]
	v_mfma_f32_16x16x32_bf16 v[50:53], v[218:221], v[150:153], v[50:53]
	v_mfma_f32_16x16x32_bf16 v[38:41], v[206:209], v[182:185], v[38:41]
	v_mfma_f32_16x16x32_bf16 v[34:37], v[218:221], v[182:185], v[34:37]
	v_mfma_f32_16x16x32_bf16 v[22:25], v[206:209], v[190:193], v[22:25]
	v_mfma_f32_16x16x32_bf16 v[18:21], v[218:221], v[190:193], v[18:21]
	v_mfma_f32_16x16x32_bf16 v[6:9], v[206:209], v[198:201], v[6:9]
	v_mfma_f32_16x16x32_bf16 v[2:5], v[218:221], v[198:201], v[2:5]
	s_barrier
	s_setprio 0
	s_add_i32 s62, s62, 2
	s_add_u32 s24, s24, 0x100
	s_addc_u32 s25, s25, 0
	s_add_u32 s60, s60, 0x100
	s_addc_u32 s61, s61, 0
	s_cmp_gt_u32 s62, 41
	s_cbranch_scc0 .LBB0_3483
	s_ashr_i32 s18, s57, 3
	s_mul_hi_i32 s19, s18, 0x9000
	s_mul_i32 s18, s18, 0x9000
	s_add_u32 s20, s58, s18
	s_addc_u32 s21, s59, s19
	s_lshl_b32 s34, s8, 8
	v_lshl_add_u32 v206, s57, 8, v1
	s_ashr_i32 s35, s34, 31
	v_ashrrev_i32_e32 v207, 31, v206
	s_lshl_b64 s[18:19], s[34:35], 2
	v_lshl_add_u64 v[130:131], s[34:35], 1, v[166:167]
	v_lshlrev_b64 v[178:179], 11, v[206:207]
	s_add_u32 s18, s20, s18
	v_lshl_add_u64 v[132:133], v[130:131], 0, v[178:179]
	s_addc_u32 s19, s21, s19
	v_lshlrev_b32_e32 v162, 2, v164
	global_load_dwordx4 v[180:183], v[132:133], off
	global_load_dwordx4 v[184:187], v[132:133], off offset:256
	v_lshl_add_u64 v[132:133], s[18:19], 0, v[162:163]
	v_lshl_add_u64 v[134:135], v[132:133], 0, s[16:17]
	v_add_co_u32_e32 v132, vcc, s51, v132
	v_or_b32_e32 v204, 16, v206
	s_nop 0
	v_addc_co_u32_e32 v133, vcc, 0, v133, vcc
	global_load_dwordx4 v[188:191], v[132:133], off
	global_load_dwordx4 v[214:217], v[134:135], off offset:512
	global_load_dwordx4 v[218:221], v[134:135], off offset:16
	global_load_dwordx4 v[222:225], v[134:135], off offset:528
	v_or_b32_e32 v200, 32, v206
	v_or_b32_e32 v196, 48, v206
	v_ashrrev_i32_e32 v205, 31, v204
	v_ashrrev_i32_e32 v201, 31, v200
	v_ashrrev_i32_e32 v197, 31, v196
	v_lshlrev_b64 v[208:209], 11, v[204:205]
	v_lshlrev_b64 v[202:203], 11, v[200:201]
	v_lshlrev_b64 v[198:199], 11, v[196:197]
	v_lshl_add_u64 v[132:133], v[130:131], 0, v[208:209]
	v_lshl_add_u64 v[134:135], v[130:131], 0, v[202:203]
	v_lshl_add_u64 v[130:131], v[130:131], 0, v[198:199]
	global_load_dwordx4 v[150:153], v[132:133], off
	global_load_dwordx4 v[146:149], v[132:133], off offset:256
	global_load_dwordx4 v[142:145], v[134:135], off
	global_load_dwordx4 v[138:141], v[134:135], off offset:256
	s_nop 0
	global_load_dwordx4 v[134:137], v[130:131], off
	s_nop 0
	global_load_dwordx4 v[130:133], v[130:131], off offset:256
	v_lshl_add_u64 v[192:193], s[10:11], 0, v[178:179]
	v_or_b32_e32 v178, s34, v164
	v_mov_b32_e32 v179, s35
	v_lshl_add_u64 v[226:227], v[178:179], 1, v[192:193]
	s_lshl_b32 s24, s8, 2
	s_ashr_i32 s25, s24, 31
	s_waitcnt vmcnt(0)
	v_lshlrev_b32_e32 v228, 16, v180
	v_lshlrev_b32_e32 v232, 16, v184
	v_and_b32_e32 v233, 0xffff0000, v184
	v_and_b32_e32 v229, 0xffff0000, v180
	v_lshlrev_b32_e32 v234, 16, v181
	v_and_b32_e32 v235, 0xffff0000, v181
	v_lshlrev_b32_e32 v236, 16, v185
	v_pk_mul_f32 v[192:193], v[214:215], 0.5 op_sel_hi:[1,0]
	v_and_b32_e32 v237, 0xffff0000, v185
	v_lshlrev_b32_e32 v244, 16, v187
	v_and_b32_e32 v245, 0xffff0000, v187
	v_pk_mul_f32 v[194:195], v[188:189], 0.5 op_sel_hi:[1,0]
	v_pk_mul_f32 v[188:189], v[216:217], 0.5 op_sel_hi:[1,0]
	v_pk_mul_f32 v[180:181], v[224:225], 0.5 op_sel_hi:[1,0]
	v_pk_fma_f32 v[118:119], v[118:119], v[192:193], v[232:233]
	v_pk_mul_f32 v[190:191], v[190:191], 0.5 op_sel_hi:[1,0]
	v_pk_fma_f32 v[126:127], v[126:127], v[194:195], v[228:229]
	v_pk_fma_f32 v[120:121], v[120:121], v[188:189], v[236:237]
	v_pk_fma_f32 v[216:217], v[116:117], v[180:181], v[244:245]
	v_pk_mul_f32 v[116:117], v[118:119], v[118:119]
	v_lshlrev_b32_e32 v240, 16, v186
	v_and_b32_e32 v241, 0xffff0000, v186
	v_pk_mul_f32 v[186:187], v[218:219], 0.5 op_sel_hi:[1,0]
	v_pk_mul_f32 v[184:185], v[222:223], 0.5 op_sel_hi:[1,0]
	v_pk_fma_f32 v[128:129], v[128:129], v[190:191], v[234:235]
	v_pk_mul_f32 v[218:219], v[120:121], v[120:121]
	v_pk_fma_f32 v[116:117], v[126:127], v[126:127], v[116:117]
	v_lshlrev_b32_e32 v238, 16, v182
	v_and_b32_e32 v239, 0xffff0000, v182
	v_pk_fma_f32 v[214:215], v[114:115], v[184:185], v[240:241]
	v_cvt_pk_bf16_f32 v114, v126, v127
	v_pk_fma_f32 v[126:127], v[128:129], v[128:129], v[218:219]
	v_add_f32_e32 v116, v116, v117
	v_lshlrev_b32_e32 v242, 16, v183
	v_and_b32_e32 v243, 0xffff0000, v183
	v_pk_mul_f32 v[182:183], v[220:221], 0.5 op_sel_hi:[1,0]
	v_pk_fma_f32 v[122:123], v[122:123], v[186:187], v[238:239]
	v_pk_mul_f32 v[220:221], v[214:215], v[214:215]
	v_add_f32_e32 v116, v126, v116
	v_cvt_pk_bf16_f32 v115, v128, v129
	v_pk_fma_f32 v[128:129], v[122:123], v[122:123], v[220:221]
	v_add_f32_e32 v116, v127, v116
	v_pk_fma_f32 v[124:125], v[124:125], v[182:183], v[242:243]
	v_pk_mul_f32 v[222:223], v[216:217], v[216:217]
	v_add_f32_e32 v116, v128, v116
	v_pk_fma_f32 v[218:219], v[124:125], v[124:125], v[222:223]
	v_add_f32_e32 v116, v129, v116
	v_add_f32_e32 v116, v218, v116
	v_and_b32_e32 v117, 64, v212
	v_add_f32_e32 v127, v219, v116
	v_xor_b32_e32 v116, 16, v212
	v_add_u32_e32 v128, 64, v117
	v_cmp_lt_i32_e32 vcc, v116, v128
	v_cvt_pk_bf16_f32 v117, v124, v125
	s_nop 0
	v_cndmask_b32_e32 v116, v212, v116, vcc
	v_lshlrev_b32_e32 v126, 2, v116
	ds_bpermute_b32 v129, v126, v127
	v_cvt_pk_bf16_f32 v116, v122, v123
	global_store_dwordx4 v[226:227], v[114:117], off nt
	s_nop 1
	v_xor_b32_e32 v115, 32, v212
	v_cmp_lt_i32_e32 vcc, v115, v128
	s_waitcnt lgkmcnt(0)
	v_add_f32_e32 v114, v127, v129
	v_cvt_pk_bf16_f32 v116, v118, v119
	v_cndmask_b32_e32 v115, v212, v115, vcc
	v_lshlrev_b32_e32 v127, 2, v115
	ds_bpermute_b32 v115, v127, v114
	v_cvt_pk_bf16_f32 v117, v120, v121
	v_cvt_pk_bf16_f32 v118, v214, v215
	v_cvt_pk_bf16_f32 v119, v216, v217
	global_store_dwordx4 v[226:227], v[116:119], off offset:256 nt
	s_and_saveexec_b64 s[18:19], s[2:3]
	s_cbranch_execz .LBB0_3486
	s_waitcnt lgkmcnt(0)
	v_add_f32_e32 v116, v114, v115
	v_lshlrev_b64 v[114:115], 6, v[206:207]
	v_lshl_add_u64 v[114:115], s[12:13], 0, v[114:115]
	v_lshl_add_u64 v[114:115], s[24:25], 2, v[114:115]
	s_lshl_b32 s8, s47, 2
	v_lshl_add_u64 v[114:115], v[114:115], 0, s[8:9]
	global_store_dword v[114:115], v116, off
